# q/kv up-projection tiles paired by row block on a workgroup: second tile of a pair reuses the row-norm scales left in LDS (skips its pre-pass)
# speedup vs baseline: 1.0008x; 1.0008x over previous
.LBB0_804:
	s_mov_b32 s98, s20
	s_mov_b32 s99, 0
	s_cmpk_lt_u32 s20, 0x200
	s_cbranch_scc0 .Lrm_notkvpair
	s_lshr_b32 s99, s20, 8
	s_and_b32 s0, s20, 0xff
	s_lshl_b32 s0, s0, 1
	s_or_b32 s20, s0, s99
	s_branch .Lrm_done
.Lrm_notkvpair:
	s_cmpk_lt_u32 s20, 0x220
	s_cbranch_scc1 .Lrm_done
	s_sub_u32 s0, s20, 0x220
	v_readlane_b32 s1, v255, 14
	s_sub_u32 s1, s1, 0x320
	s_cmpk_lt_u32 s0, 0x100
	s_cbranch_scc0 .Lrm_qsecond
	s_cmp_lt_u32 s0, s1
	s_cbranch_scc0 .Lrm_qsingle
	s_lshl_b32 s0, s0, 1
	s_add_u32 s20, s0, 0x220
	s_branch .Lrm_done
.Lrm_qsingle:
	s_add_u32 s0, s0, s1
	s_add_u32 s20, s0, 0x220
	s_branch .Lrm_done
.Lrm_qsecond:
	s_sub_u32 s0, s0, 0x100
	s_lshl_b32 s0, s0, 1
	s_add_u32 s20, s0, 0x221
	s_mov_b32 s99, 1
.Lrm_done:
	v_readlane_b32 s0, v254, 1
	s_cmpk_eq_u32 s0, 0x100
	s_cselect_b32 s99, s99, 0
	s_cmpk_gt_i32 s20, 0x21f
	s_mov_b64 s[0:1], -1
	s_cbranch_scc0 .LBB0_906
	s_add_i32 s16, s20, 0xfde0
	s_and_b32 s8, s16, 0xffff
	s_mul_i32 s0, s8, 0xaaab
	v_mov_b32_e32 v128, v167
	s_lshr_b32 s9, s0, 18
	s_lshl_b32 s21, s9, 8
	v_ashrrev_i32_e32 v129, 1, v128
	v_and_b32_e32 v1, 0xffffffe0, v129
	v_add_u32_e32 v62, s21, v1
	v_and_b32_e32 v1, 64, v192
	v_add_u32_e32 v1, 64, v1
	v_xor_b32_e32 v2, 32, v192
	v_cmp_lt_i32_e32 vcc, v2, v1
	v_and_b32_e32 v0, 63, v128
	v_lshlrev_b32_e32 v164, 4, v0
	v_cndmask_b32_e32 v2, v192, v2, vcc
	v_lshlrev_b32_e32 v63, 2, v2
	v_xor_b32_e32 v2, 16, v192
	v_cmp_lt_i32_e32 vcc, v2, v1
	v_readlane_b32 s1, v254, 47
	v_lshl_add_u64 v[60:61], s[22:23], 0, v[164:165]
	v_cndmask_b32_e32 v2, v192, v2, vcc
	v_lshlrev_b32_e32 v64, 2, v2
	v_xor_b32_e32 v2, 8, v192
	v_cmp_lt_i32_e32 vcc, v2, v1
	s_mov_b32 s0, 0
	v_cmp_eq_u32_e64 s[10:11], 0, v0
	v_cndmask_b32_e32 v2, v192, v2, vcc
	v_lshlrev_b32_e32 v65, 2, v2
	v_xor_b32_e32 v2, 4, v192
	v_cmp_lt_i32_e32 vcc, v2, v1
	v_lshl_add_u32 v69, v129, 2, s1
	s_mov_b64 s[2:3], -1
	v_cndmask_b32_e32 v2, v192, v2, vcc
	v_lshlrev_b32_e32 v66, 2, v2
	v_xor_b32_e32 v2, 2, v192
	v_cmp_lt_i32_e32 vcc, v2, v1
	s_nop 1
	v_cndmask_b32_e32 v2, v192, v2, vcc
	v_lshlrev_b32_e32 v67, 2, v2
	v_xor_b32_e32 v2, 1, v192
	v_cmp_lt_i32_e32 vcc, v2, v1
	s_nop 1
	v_cndmask_b32_e32 v1, v192, v2, vcc
	v_lshlrev_b32_e32 v68, 2, v1
	s_cmp_eq_u32 s99, 1
	s_cbranch_scc1 .Lrsq_skip
	v_readfirstlane_b32 s0, v167
	v_and_b32_e32 v116, 63, v167
	v_and_b32_e32 v118, 15, v167
	s_lshr_b32 s0, s0, 6
	s_lshl_b32 s1, s0, 5
	s_add_u32 s2, s21, s1
	s_mul_i32 s2, s2, 0x1700
	s_add_u32 s24, s22, s2
	s_addc_u32 s25, s23, 0
	v_lshlrev_b32_e32 v116, 4, v116
	v_and_b32_e32 v117, 48, v167
	s_lshl_b32 s1, s0, 7
	v_add_u32_e32 v117, s1, v117
	v_add_u32_e32 v117, 0x20000, v117
	global_load_dwordx4 v[16:19], v116, s[24:25]
	s_add_u32 s24, s24, 0x1700
	s_addc_u32 s25, s25, 0
	global_load_dwordx4 v[20:23], v116, s[24:25]
	s_add_u32 s24, s24, 0x1700
	s_addc_u32 s25, s25, 0
	global_load_dwordx4 v[24:27], v116, s[24:25]
	s_add_u32 s24, s24, 0x1700
	s_addc_u32 s25, s25, 0
	global_load_dwordx4 v[28:31], v116, s[24:25]
	s_add_u32 s24, s24, 0x1700
	s_addc_u32 s25, s25, 0
	global_load_dwordx4 v[32:35], v116, s[24:25]
	s_add_u32 s24, s24, 0x1700
	s_addc_u32 s25, s25, 0
	global_load_dwordx4 v[36:39], v116, s[24:25]
	s_add_u32 s24, s24, 0x1700
	s_addc_u32 s25, s25, 0
	global_load_dwordx4 v[40:43], v116, s[24:25]
	s_add_u32 s24, s24, 0x1700
	s_addc_u32 s25, s25, 0
	global_load_dwordx4 v[44:47], v116, s[24:25]
	s_add_u32 s24, s24, 0x1700
	s_addc_u32 s25, s25, 0
	global_load_dwordx4 v[48:51], v116, s[24:25]
	s_add_u32 s24, s24, 0x1700
	s_addc_u32 s25, s25, 0
	global_load_dwordx4 v[52:55], v116, s[24:25]
	s_add_u32 s24, s24, 0x1700
	s_addc_u32 s25, s25, 0
	global_load_dwordx4 v[56:59], v116, s[24:25]
	s_add_u32 s24, s24, 0x1700
	s_addc_u32 s25, s25, 0
	global_load_dwordx4 v[60:63], v116, s[24:25]
	s_add_u32 s24, s24, 0x1700
	s_addc_u32 s25, s25, 0
	global_load_dwordx4 v[64:67], v116, s[24:25]
	s_add_u32 s24, s24, 0x1700
	s_addc_u32 s25, s25, 0
	global_load_dwordx4 v[68:71], v116, s[24:25]
	s_add_u32 s24, s24, 0x1700
	s_addc_u32 s25, s25, 0
	global_load_dwordx4 v[72:75], v116, s[24:25]
	s_add_u32 s24, s24, 0x1700
	s_addc_u32 s25, s25, 0
	global_load_dwordx4 v[76:79], v116, s[24:25]
	s_add_u32 s24, s24, 0x1700
	s_addc_u32 s25, s25, 0
	s_waitcnt vmcnt(15)
	v_lshlrev_b32_e32 v112, 16, v16
	v_and_b32_e32 v16, 0xffff0000, v16
	v_mul_f32_e32 v16, v16, v16
	v_fmac_f32_e32 v16, v112, v112
	v_lshlrev_b32_e32 v112, 16, v17
	v_and_b32_e32 v17, 0xffff0000, v17
	v_mul_f32_e32 v17, v17, v17
	v_fmac_f32_e32 v17, v112, v112
	v_add_f32_e32 v16, v16, v17
	v_lshlrev_b32_e32 v112, 16, v18
	v_and_b32_e32 v18, 0xffff0000, v18
	v_mul_f32_e32 v18, v18, v18
	v_fmac_f32_e32 v18, v112, v112
	v_add_f32_e32 v16, v16, v18
	v_lshlrev_b32_e32 v112, 16, v19
	v_and_b32_e32 v19, 0xffff0000, v19
	v_mul_f32_e32 v19, v19, v19
	v_fmac_f32_e32 v19, v112, v112
	v_add_f32_e32 v16, v16, v19
	s_waitcnt vmcnt(14)
	v_lshlrev_b32_e32 v112, 16, v20
	v_and_b32_e32 v20, 0xffff0000, v20
	v_mul_f32_e32 v20, v20, v20
	v_fmac_f32_e32 v20, v112, v112
	v_lshlrev_b32_e32 v112, 16, v21
	v_and_b32_e32 v21, 0xffff0000, v21
	v_mul_f32_e32 v21, v21, v21
	v_fmac_f32_e32 v21, v112, v112
	v_add_f32_e32 v20, v20, v21
	v_lshlrev_b32_e32 v112, 16, v22
	v_and_b32_e32 v22, 0xffff0000, v22
	v_mul_f32_e32 v22, v22, v22
	v_fmac_f32_e32 v22, v112, v112
	v_add_f32_e32 v20, v20, v22
	v_lshlrev_b32_e32 v112, 16, v23
	v_and_b32_e32 v23, 0xffff0000, v23
	v_mul_f32_e32 v23, v23, v23
	v_fmac_f32_e32 v23, v112, v112
	v_add_f32_e32 v20, v20, v23
	s_waitcnt vmcnt(13)
	v_lshlrev_b32_e32 v112, 16, v24
	v_and_b32_e32 v24, 0xffff0000, v24
	v_mul_f32_e32 v24, v24, v24
	v_fmac_f32_e32 v24, v112, v112
	v_lshlrev_b32_e32 v112, 16, v25
	v_and_b32_e32 v25, 0xffff0000, v25
	v_mul_f32_e32 v25, v25, v25
	v_fmac_f32_e32 v25, v112, v112
	v_add_f32_e32 v24, v24, v25
	v_lshlrev_b32_e32 v112, 16, v26
	v_and_b32_e32 v26, 0xffff0000, v26
	v_mul_f32_e32 v26, v26, v26
	v_fmac_f32_e32 v26, v112, v112
	v_add_f32_e32 v24, v24, v26
	v_lshlrev_b32_e32 v112, 16, v27
	v_and_b32_e32 v27, 0xffff0000, v27
	v_mul_f32_e32 v27, v27, v27
	v_fmac_f32_e32 v27, v112, v112
	v_add_f32_e32 v24, v24, v27
	s_waitcnt vmcnt(12)
	v_lshlrev_b32_e32 v112, 16, v28
	v_and_b32_e32 v28, 0xffff0000, v28
	v_mul_f32_e32 v28, v28, v28
	v_fmac_f32_e32 v28, v112, v112
	v_lshlrev_b32_e32 v112, 16, v29
	v_and_b32_e32 v29, 0xffff0000, v29
	v_mul_f32_e32 v29, v29, v29
	v_fmac_f32_e32 v29, v112, v112
	v_add_f32_e32 v28, v28, v29
	v_lshlrev_b32_e32 v112, 16, v30
	v_and_b32_e32 v30, 0xffff0000, v30
	v_mul_f32_e32 v30, v30, v30
	v_fmac_f32_e32 v30, v112, v112
	v_add_f32_e32 v28, v28, v30
	v_lshlrev_b32_e32 v112, 16, v31
	v_and_b32_e32 v31, 0xffff0000, v31
	v_mul_f32_e32 v31, v31, v31
	v_fmac_f32_e32 v31, v112, v112
	v_add_f32_e32 v28, v28, v31
	s_waitcnt vmcnt(11)
	v_lshlrev_b32_e32 v112, 16, v32
	v_and_b32_e32 v32, 0xffff0000, v32
	v_mul_f32_e32 v32, v32, v32
	v_fmac_f32_e32 v32, v112, v112
	v_lshlrev_b32_e32 v112, 16, v33
	v_and_b32_e32 v33, 0xffff0000, v33
	v_mul_f32_e32 v33, v33, v33
	v_fmac_f32_e32 v33, v112, v112
	v_add_f32_e32 v32, v32, v33
	v_lshlrev_b32_e32 v112, 16, v34
	v_and_b32_e32 v34, 0xffff0000, v34
	v_mul_f32_e32 v34, v34, v34
	v_fmac_f32_e32 v34, v112, v112
	v_add_f32_e32 v32, v32, v34
	v_lshlrev_b32_e32 v112, 16, v35
	v_and_b32_e32 v35, 0xffff0000, v35
	v_mul_f32_e32 v35, v35, v35
	v_fmac_f32_e32 v35, v112, v112
	v_add_f32_e32 v32, v32, v35
	s_waitcnt vmcnt(10)
	v_lshlrev_b32_e32 v112, 16, v36
	v_and_b32_e32 v36, 0xffff0000, v36
	v_mul_f32_e32 v36, v36, v36
	v_fmac_f32_e32 v36, v112, v112
	v_lshlrev_b32_e32 v112, 16, v37
	v_and_b32_e32 v37, 0xffff0000, v37
	v_mul_f32_e32 v37, v37, v37
	v_fmac_f32_e32 v37, v112, v112
	v_add_f32_e32 v36, v36, v37
	v_lshlrev_b32_e32 v112, 16, v38
	v_and_b32_e32 v38, 0xffff0000, v38
	v_mul_f32_e32 v38, v38, v38
	v_fmac_f32_e32 v38, v112, v112
	v_add_f32_e32 v36, v36, v38
	v_lshlrev_b32_e32 v112, 16, v39
	v_and_b32_e32 v39, 0xffff0000, v39
	v_mul_f32_e32 v39, v39, v39
	v_fmac_f32_e32 v39, v112, v112
	v_add_f32_e32 v36, v36, v39
	s_waitcnt vmcnt(9)
	v_lshlrev_b32_e32 v112, 16, v40
	v_and_b32_e32 v40, 0xffff0000, v40
	v_mul_f32_e32 v40, v40, v40
	v_fmac_f32_e32 v40, v112, v112
	v_lshlrev_b32_e32 v112, 16, v41
	v_and_b32_e32 v41, 0xffff0000, v41
	v_mul_f32_e32 v41, v41, v41
	v_fmac_f32_e32 v41, v112, v112
	v_add_f32_e32 v40, v40, v41
	v_lshlrev_b32_e32 v112, 16, v42
	v_and_b32_e32 v42, 0xffff0000, v42
	v_mul_f32_e32 v42, v42, v42
	v_fmac_f32_e32 v42, v112, v112
	v_add_f32_e32 v40, v40, v42
	v_lshlrev_b32_e32 v112, 16, v43
	v_and_b32_e32 v43, 0xffff0000, v43
	v_mul_f32_e32 v43, v43, v43
	v_fmac_f32_e32 v43, v112, v112
	v_add_f32_e32 v40, v40, v43
	s_waitcnt vmcnt(8)
	v_lshlrev_b32_e32 v112, 16, v44
	v_and_b32_e32 v44, 0xffff0000, v44
	v_mul_f32_e32 v44, v44, v44
	v_fmac_f32_e32 v44, v112, v112
	v_lshlrev_b32_e32 v112, 16, v45
	v_and_b32_e32 v45, 0xffff0000, v45
	v_mul_f32_e32 v45, v45, v45
	v_fmac_f32_e32 v45, v112, v112
	v_add_f32_e32 v44, v44, v45
	v_lshlrev_b32_e32 v112, 16, v46
	v_and_b32_e32 v46, 0xffff0000, v46
	v_mul_f32_e32 v46, v46, v46
	v_fmac_f32_e32 v46, v112, v112
	v_add_f32_e32 v44, v44, v46
	v_lshlrev_b32_e32 v112, 16, v47
	v_and_b32_e32 v47, 0xffff0000, v47
	v_mul_f32_e32 v47, v47, v47
	v_fmac_f32_e32 v47, v112, v112
	v_add_f32_e32 v44, v44, v47
	s_waitcnt vmcnt(7)
	v_lshlrev_b32_e32 v112, 16, v48
	v_and_b32_e32 v48, 0xffff0000, v48
	v_mul_f32_e32 v48, v48, v48
	v_fmac_f32_e32 v48, v112, v112
	v_lshlrev_b32_e32 v112, 16, v49
	v_and_b32_e32 v49, 0xffff0000, v49
	v_mul_f32_e32 v49, v49, v49
	v_fmac_f32_e32 v49, v112, v112
	v_add_f32_e32 v48, v48, v49
	v_lshlrev_b32_e32 v112, 16, v50
	v_and_b32_e32 v50, 0xffff0000, v50
	v_mul_f32_e32 v50, v50, v50
	v_fmac_f32_e32 v50, v112, v112
	v_add_f32_e32 v48, v48, v50
	v_lshlrev_b32_e32 v112, 16, v51
	v_and_b32_e32 v51, 0xffff0000, v51
	v_mul_f32_e32 v51, v51, v51
	v_fmac_f32_e32 v51, v112, v112
	v_add_f32_e32 v48, v48, v51
	s_waitcnt vmcnt(6)
	v_lshlrev_b32_e32 v112, 16, v52
	v_and_b32_e32 v52, 0xffff0000, v52
	v_mul_f32_e32 v52, v52, v52
	v_fmac_f32_e32 v52, v112, v112
	v_lshlrev_b32_e32 v112, 16, v53
	v_and_b32_e32 v53, 0xffff0000, v53
	v_mul_f32_e32 v53, v53, v53
	v_fmac_f32_e32 v53, v112, v112
	v_add_f32_e32 v52, v52, v53
	v_lshlrev_b32_e32 v112, 16, v54
	v_and_b32_e32 v54, 0xffff0000, v54
	v_mul_f32_e32 v54, v54, v54
	v_fmac_f32_e32 v54, v112, v112
	v_add_f32_e32 v52, v52, v54
	v_lshlrev_b32_e32 v112, 16, v55
	v_and_b32_e32 v55, 0xffff0000, v55
	v_mul_f32_e32 v55, v55, v55
	v_fmac_f32_e32 v55, v112, v112
	v_add_f32_e32 v52, v52, v55
	s_waitcnt vmcnt(5)
	v_lshlrev_b32_e32 v112, 16, v56
	v_and_b32_e32 v56, 0xffff0000, v56
	v_mul_f32_e32 v56, v56, v56
	v_fmac_f32_e32 v56, v112, v112
	v_lshlrev_b32_e32 v112, 16, v57
	v_and_b32_e32 v57, 0xffff0000, v57
	v_mul_f32_e32 v57, v57, v57
	v_fmac_f32_e32 v57, v112, v112
	v_add_f32_e32 v56, v56, v57
	v_lshlrev_b32_e32 v112, 16, v58
	v_and_b32_e32 v58, 0xffff0000, v58
	v_mul_f32_e32 v58, v58, v58
	v_fmac_f32_e32 v58, v112, v112
	v_add_f32_e32 v56, v56, v58
	v_lshlrev_b32_e32 v112, 16, v59
	v_and_b32_e32 v59, 0xffff0000, v59
	v_mul_f32_e32 v59, v59, v59
	v_fmac_f32_e32 v59, v112, v112
	v_add_f32_e32 v56, v56, v59
	s_waitcnt vmcnt(4)
	v_lshlrev_b32_e32 v112, 16, v60
	v_and_b32_e32 v60, 0xffff0000, v60
	v_mul_f32_e32 v60, v60, v60
	v_fmac_f32_e32 v60, v112, v112
	v_lshlrev_b32_e32 v112, 16, v61
	v_and_b32_e32 v61, 0xffff0000, v61
	v_mul_f32_e32 v61, v61, v61
	v_fmac_f32_e32 v61, v112, v112
	v_add_f32_e32 v60, v60, v61
	v_lshlrev_b32_e32 v112, 16, v62
	v_and_b32_e32 v62, 0xffff0000, v62
	v_mul_f32_e32 v62, v62, v62
	v_fmac_f32_e32 v62, v112, v112
	v_add_f32_e32 v60, v60, v62
	v_lshlrev_b32_e32 v112, 16, v63
	v_and_b32_e32 v63, 0xffff0000, v63
	v_mul_f32_e32 v63, v63, v63
	v_fmac_f32_e32 v63, v112, v112
	v_add_f32_e32 v60, v60, v63
	s_waitcnt vmcnt(3)
	v_lshlrev_b32_e32 v112, 16, v64
	v_and_b32_e32 v64, 0xffff0000, v64
	v_mul_f32_e32 v64, v64, v64
	v_fmac_f32_e32 v64, v112, v112
	v_lshlrev_b32_e32 v112, 16, v65
	v_and_b32_e32 v65, 0xffff0000, v65
	v_mul_f32_e32 v65, v65, v65
	v_fmac_f32_e32 v65, v112, v112
	v_add_f32_e32 v64, v64, v65
	v_lshlrev_b32_e32 v112, 16, v66
	v_and_b32_e32 v66, 0xffff0000, v66
	v_mul_f32_e32 v66, v66, v66
	v_fmac_f32_e32 v66, v112, v112
	v_add_f32_e32 v64, v64, v66
	v_lshlrev_b32_e32 v112, 16, v67
	v_and_b32_e32 v67, 0xffff0000, v67
	v_mul_f32_e32 v67, v67, v67
	v_fmac_f32_e32 v67, v112, v112
	v_add_f32_e32 v64, v64, v67
	s_waitcnt vmcnt(2)
	v_lshlrev_b32_e32 v112, 16, v68
	v_and_b32_e32 v68, 0xffff0000, v68
	v_mul_f32_e32 v68, v68, v68
	v_fmac_f32_e32 v68, v112, v112
	v_lshlrev_b32_e32 v112, 16, v69
	v_and_b32_e32 v69, 0xffff0000, v69
	v_mul_f32_e32 v69, v69, v69
	v_fmac_f32_e32 v69, v112, v112
	v_add_f32_e32 v68, v68, v69
	v_lshlrev_b32_e32 v112, 16, v70
	v_and_b32_e32 v70, 0xffff0000, v70
	v_mul_f32_e32 v70, v70, v70
	v_fmac_f32_e32 v70, v112, v112
	v_add_f32_e32 v68, v68, v70
	v_lshlrev_b32_e32 v112, 16, v71
	v_and_b32_e32 v71, 0xffff0000, v71
	v_mul_f32_e32 v71, v71, v71
	v_fmac_f32_e32 v71, v112, v112
	v_add_f32_e32 v68, v68, v71
	s_waitcnt vmcnt(1)
	v_lshlrev_b32_e32 v112, 16, v72
	v_and_b32_e32 v72, 0xffff0000, v72
	v_mul_f32_e32 v72, v72, v72
	v_fmac_f32_e32 v72, v112, v112
	v_lshlrev_b32_e32 v112, 16, v73
	v_and_b32_e32 v73, 0xffff0000, v73
	v_mul_f32_e32 v73, v73, v73
	v_fmac_f32_e32 v73, v112, v112
	v_add_f32_e32 v72, v72, v73
	v_lshlrev_b32_e32 v112, 16, v74
	v_and_b32_e32 v74, 0xffff0000, v74
	v_mul_f32_e32 v74, v74, v74
	v_fmac_f32_e32 v74, v112, v112
	v_add_f32_e32 v72, v72, v74
	v_lshlrev_b32_e32 v112, 16, v75
	v_and_b32_e32 v75, 0xffff0000, v75
	v_mul_f32_e32 v75, v75, v75
	v_fmac_f32_e32 v75, v112, v112
	v_add_f32_e32 v72, v72, v75
	s_waitcnt vmcnt(0)
	v_lshlrev_b32_e32 v112, 16, v76
	v_and_b32_e32 v76, 0xffff0000, v76
	v_mul_f32_e32 v76, v76, v76
	v_fmac_f32_e32 v76, v112, v112
	v_lshlrev_b32_e32 v112, 16, v77
	v_and_b32_e32 v77, 0xffff0000, v77
	v_mul_f32_e32 v77, v77, v77
	v_fmac_f32_e32 v77, v112, v112
	v_add_f32_e32 v76, v76, v77
	v_lshlrev_b32_e32 v112, 16, v78
	v_and_b32_e32 v78, 0xffff0000, v78
	v_mul_f32_e32 v78, v78, v78
	v_fmac_f32_e32 v78, v112, v112
	v_add_f32_e32 v76, v76, v78
	v_lshlrev_b32_e32 v112, 16, v79
	v_and_b32_e32 v79, 0xffff0000, v79
	v_mul_f32_e32 v79, v79, v79
	v_fmac_f32_e32 v79, v112, v112
	v_add_f32_e32 v76, v76, v79
	s_nop 1
	v_permlane32_swap_b32_e32 v16, v48
	v_permlane32_swap_b32_e32 v20, v52
	v_permlane32_swap_b32_e32 v24, v56
	v_permlane32_swap_b32_e32 v28, v60
	v_permlane32_swap_b32_e32 v32, v64
	v_permlane32_swap_b32_e32 v36, v68
	v_permlane32_swap_b32_e32 v40, v72
	v_permlane32_swap_b32_e32 v44, v76
	s_nop 0
	v_add_f32_e32 v16, v16, v48
	v_add_f32_e32 v20, v20, v52
	v_add_f32_e32 v24, v24, v56
	v_add_f32_e32 v28, v28, v60
	v_add_f32_e32 v32, v32, v64
	v_add_f32_e32 v36, v36, v68
	v_add_f32_e32 v40, v40, v72
	v_add_f32_e32 v44, v44, v76
	s_nop 1
	v_permlane16_swap_b32_e32 v16, v32
	v_permlane16_swap_b32_e32 v20, v36
	v_permlane16_swap_b32_e32 v24, v40
	v_permlane16_swap_b32_e32 v28, v44
	s_nop 0
	v_add_f32_e32 v16, v16, v32
	v_add_f32_e32 v20, v20, v36
	v_add_f32_e32 v24, v24, v40
	v_add_f32_e32 v28, v28, v44
	s_nop 1
	v_add_f32_dpp v16, v16, v16 row_ror:8 row_mask:0xf bank_mask:0xf
	v_add_f32_dpp v20, v20, v20 row_ror:8 row_mask:0xf bank_mask:0xf
	v_add_f32_dpp v24, v24, v24 row_ror:8 row_mask:0xf bank_mask:0xf
	v_add_f32_dpp v28, v28, v28 row_ror:8 row_mask:0xf bank_mask:0xf
	s_nop 1
	v_add_f32_dpp v16, v16, v16 row_ror:4 row_mask:0xf bank_mask:0xf
	v_add_f32_dpp v20, v20, v20 row_ror:4 row_mask:0xf bank_mask:0xf
	v_add_f32_dpp v24, v24, v24 row_ror:4 row_mask:0xf bank_mask:0xf
	v_add_f32_dpp v28, v28, v28 row_ror:4 row_mask:0xf bank_mask:0xf
	s_nop 1
	v_add_f32_dpp v16, v16, v16 row_ror:2 row_mask:0xf bank_mask:0xf
	v_add_f32_dpp v20, v20, v20 row_ror:2 row_mask:0xf bank_mask:0xf
	v_add_f32_dpp v24, v24, v24 row_ror:2 row_mask:0xf bank_mask:0xf
	v_add_f32_dpp v28, v28, v28 row_ror:2 row_mask:0xf bank_mask:0xf
	s_nop 1
	v_add_f32_dpp v16, v16, v16 row_ror:1 row_mask:0xf bank_mask:0xf
	v_add_f32_dpp v20, v20, v20 row_ror:1 row_mask:0xf bank_mask:0xf
	v_add_f32_dpp v24, v24, v24 row_ror:1 row_mask:0xf bank_mask:0xf
	v_add_f32_dpp v28, v28, v28 row_ror:1 row_mask:0xf bank_mask:0xf
	v_fmamk_f32 v16, v16, 0x3b000000, v166
	v_fmamk_f32 v20, v20, 0x3b000000, v166
	v_fmamk_f32 v24, v24, 0x3b000000, v166
	v_fmamk_f32 v28, v28, 0x3b000000, v166
	v_mul_f32_e32 v112, 0x4b800000, v16
	v_cmp_gt_f32_e32 vcc, s58, v16
	s_nop 1
	v_cndmask_b32_e32 v16, v16, v112, vcc
	v_rsq_f32_e32 v16, v16
	s_nop 0
	v_mul_f32_e32 v112, 0x45800000, v16
	v_cndmask_b32_e32 v16, v16, v112, vcc
	v_mul_f32_e32 v16, 0x3dd53b94, v16
	v_mul_f32_e32 v112, 0x4b800000, v20
	v_cmp_gt_f32_e32 vcc, s58, v20
	s_nop 1
	v_cndmask_b32_e32 v20, v20, v112, vcc
	v_rsq_f32_e32 v20, v20
	s_nop 0
	v_mul_f32_e32 v112, 0x45800000, v20
	v_cndmask_b32_e32 v20, v20, v112, vcc
	v_mul_f32_e32 v20, 0x3dd53b94, v20
	v_mul_f32_e32 v112, 0x4b800000, v24
	v_cmp_gt_f32_e32 vcc, s58, v24
	s_nop 1
	v_cndmask_b32_e32 v24, v24, v112, vcc
	v_rsq_f32_e32 v24, v24
	s_nop 0
	v_mul_f32_e32 v112, 0x45800000, v24
	v_cndmask_b32_e32 v24, v24, v112, vcc
	v_mul_f32_e32 v24, 0x3dd53b94, v24
	v_mul_f32_e32 v112, 0x4b800000, v28
	v_cmp_gt_f32_e32 vcc, s58, v28
	s_nop 1
	v_cndmask_b32_e32 v28, v28, v112, vcc
	v_rsq_f32_e32 v28, v28
	s_nop 0
	v_mul_f32_e32 v112, 0x45800000, v28
	v_cndmask_b32_e32 v28, v28, v112, vcc
	v_mul_f32_e32 v28, 0x3dd53b94, v28
	v_mov_b32_e32 v112, v16
	v_mov_b32_e32 v113, v20
	v_mov_b32_e32 v114, v24
	v_mov_b32_e32 v115, v28
	v_cmp_eq_u32_e32 vcc, 0, v118
	s_and_saveexec_b64 s[0:1], vcc
	ds_write_b128 v117, v[112:115]
	s_or_b64 exec, exec, s[0:1]
	global_load_dwordx4 v[16:19], v116, s[24:25]
	s_add_u32 s24, s24, 0x1700
	s_addc_u32 s25, s25, 0
	global_load_dwordx4 v[20:23], v116, s[24:25]
	s_add_u32 s24, s24, 0x1700
	s_addc_u32 s25, s25, 0
	global_load_dwordx4 v[24:27], v116, s[24:25]
	s_add_u32 s24, s24, 0x1700
	s_addc_u32 s25, s25, 0
	global_load_dwordx4 v[28:31], v116, s[24:25]
	s_add_u32 s24, s24, 0x1700
	s_addc_u32 s25, s25, 0
	global_load_dwordx4 v[32:35], v116, s[24:25]
	s_add_u32 s24, s24, 0x1700
	s_addc_u32 s25, s25, 0
	global_load_dwordx4 v[36:39], v116, s[24:25]
	s_add_u32 s24, s24, 0x1700
	s_addc_u32 s25, s25, 0
	global_load_dwordx4 v[40:43], v116, s[24:25]
	s_add_u32 s24, s24, 0x1700
	s_addc_u32 s25, s25, 0
	global_load_dwordx4 v[44:47], v116, s[24:25]
	s_add_u32 s24, s24, 0x1700
	s_addc_u32 s25, s25, 0
	global_load_dwordx4 v[48:51], v116, s[24:25]
	s_add_u32 s24, s24, 0x1700
	s_addc_u32 s25, s25, 0
	global_load_dwordx4 v[52:55], v116, s[24:25]
	s_add_u32 s24, s24, 0x1700
	s_addc_u32 s25, s25, 0
	global_load_dwordx4 v[56:59], v116, s[24:25]
	s_add_u32 s24, s24, 0x1700
	s_addc_u32 s25, s25, 0
	global_load_dwordx4 v[60:63], v116, s[24:25]
	s_add_u32 s24, s24, 0x1700
	s_addc_u32 s25, s25, 0
	global_load_dwordx4 v[64:67], v116, s[24:25]
	s_add_u32 s24, s24, 0x1700
	s_addc_u32 s25, s25, 0
	global_load_dwordx4 v[68:71], v116, s[24:25]
	s_add_u32 s24, s24, 0x1700
	s_addc_u32 s25, s25, 0
	global_load_dwordx4 v[72:75], v116, s[24:25]
	s_add_u32 s24, s24, 0x1700
	s_addc_u32 s25, s25, 0
	global_load_dwordx4 v[76:79], v116, s[24:25]
	s_add_u32 s24, s24, 0x1700
	s_addc_u32 s25, s25, 0
	s_waitcnt vmcnt(15)
	v_lshlrev_b32_e32 v112, 16, v16
	v_and_b32_e32 v16, 0xffff0000, v16
	v_mul_f32_e32 v16, v16, v16
	v_fmac_f32_e32 v16, v112, v112
	v_lshlrev_b32_e32 v112, 16, v17
	v_and_b32_e32 v17, 0xffff0000, v17
	v_mul_f32_e32 v17, v17, v17
	v_fmac_f32_e32 v17, v112, v112
	v_add_f32_e32 v16, v16, v17
	v_lshlrev_b32_e32 v112, 16, v18
	v_and_b32_e32 v18, 0xffff0000, v18
	v_mul_f32_e32 v18, v18, v18
	v_fmac_f32_e32 v18, v112, v112
	v_add_f32_e32 v16, v16, v18
	v_lshlrev_b32_e32 v112, 16, v19
	v_and_b32_e32 v19, 0xffff0000, v19
	v_mul_f32_e32 v19, v19, v19
	v_fmac_f32_e32 v19, v112, v112
	v_add_f32_e32 v16, v16, v19
	s_waitcnt vmcnt(14)
	v_lshlrev_b32_e32 v112, 16, v20
	v_and_b32_e32 v20, 0xffff0000, v20
	v_mul_f32_e32 v20, v20, v20
	v_fmac_f32_e32 v20, v112, v112
	v_lshlrev_b32_e32 v112, 16, v21
	v_and_b32_e32 v21, 0xffff0000, v21
	v_mul_f32_e32 v21, v21, v21
	v_fmac_f32_e32 v21, v112, v112
	v_add_f32_e32 v20, v20, v21
	v_lshlrev_b32_e32 v112, 16, v22
	v_and_b32_e32 v22, 0xffff0000, v22
	v_mul_f32_e32 v22, v22, v22
	v_fmac_f32_e32 v22, v112, v112
	v_add_f32_e32 v20, v20, v22
	v_lshlrev_b32_e32 v112, 16, v23
	v_and_b32_e32 v23, 0xffff0000, v23
	v_mul_f32_e32 v23, v23, v23
	v_fmac_f32_e32 v23, v112, v112
	v_add_f32_e32 v20, v20, v23
	s_waitcnt vmcnt(13)
	v_lshlrev_b32_e32 v112, 16, v24
	v_and_b32_e32 v24, 0xffff0000, v24
	v_mul_f32_e32 v24, v24, v24
	v_fmac_f32_e32 v24, v112, v112
	v_lshlrev_b32_e32 v112, 16, v25
	v_and_b32_e32 v25, 0xffff0000, v25
	v_mul_f32_e32 v25, v25, v25
	v_fmac_f32_e32 v25, v112, v112
	v_add_f32_e32 v24, v24, v25
	v_lshlrev_b32_e32 v112, 16, v26
	v_and_b32_e32 v26, 0xffff0000, v26
	v_mul_f32_e32 v26, v26, v26
	v_fmac_f32_e32 v26, v112, v112
	v_add_f32_e32 v24, v24, v26
	v_lshlrev_b32_e32 v112, 16, v27
	v_and_b32_e32 v27, 0xffff0000, v27
	v_mul_f32_e32 v27, v27, v27
	v_fmac_f32_e32 v27, v112, v112
	v_add_f32_e32 v24, v24, v27
	s_waitcnt vmcnt(12)
	v_lshlrev_b32_e32 v112, 16, v28
	v_and_b32_e32 v28, 0xffff0000, v28
	v_mul_f32_e32 v28, v28, v28
	v_fmac_f32_e32 v28, v112, v112
	v_lshlrev_b32_e32 v112, 16, v29
	v_and_b32_e32 v29, 0xffff0000, v29
	v_mul_f32_e32 v29, v29, v29
	v_fmac_f32_e32 v29, v112, v112
	v_add_f32_e32 v28, v28, v29
	v_lshlrev_b32_e32 v112, 16, v30
	v_and_b32_e32 v30, 0xffff0000, v30
	v_mul_f32_e32 v30, v30, v30
	v_fmac_f32_e32 v30, v112, v112
	v_add_f32_e32 v28, v28, v30
	v_lshlrev_b32_e32 v112, 16, v31
	v_and_b32_e32 v31, 0xffff0000, v31
	v_mul_f32_e32 v31, v31, v31
	v_fmac_f32_e32 v31, v112, v112
	v_add_f32_e32 v28, v28, v31
	s_waitcnt vmcnt(11)
	v_lshlrev_b32_e32 v112, 16, v32
	v_and_b32_e32 v32, 0xffff0000, v32
	v_mul_f32_e32 v32, v32, v32
	v_fmac_f32_e32 v32, v112, v112
	v_lshlrev_b32_e32 v112, 16, v33
	v_and_b32_e32 v33, 0xffff0000, v33
	v_mul_f32_e32 v33, v33, v33
	v_fmac_f32_e32 v33, v112, v112
	v_add_f32_e32 v32, v32, v33
	v_lshlrev_b32_e32 v112, 16, v34
	v_and_b32_e32 v34, 0xffff0000, v34
	v_mul_f32_e32 v34, v34, v34
	v_fmac_f32_e32 v34, v112, v112
	v_add_f32_e32 v32, v32, v34
	v_lshlrev_b32_e32 v112, 16, v35
	v_and_b32_e32 v35, 0xffff0000, v35
	v_mul_f32_e32 v35, v35, v35
	v_fmac_f32_e32 v35, v112, v112
	v_add_f32_e32 v32, v32, v35
	s_waitcnt vmcnt(10)
	v_lshlrev_b32_e32 v112, 16, v36
	v_and_b32_e32 v36, 0xffff0000, v36
	v_mul_f32_e32 v36, v36, v36
	v_fmac_f32_e32 v36, v112, v112
	v_lshlrev_b32_e32 v112, 16, v37
	v_and_b32_e32 v37, 0xffff0000, v37
	v_mul_f32_e32 v37, v37, v37
	v_fmac_f32_e32 v37, v112, v112
	v_add_f32_e32 v36, v36, v37
	v_lshlrev_b32_e32 v112, 16, v38
	v_and_b32_e32 v38, 0xffff0000, v38
	v_mul_f32_e32 v38, v38, v38
	v_fmac_f32_e32 v38, v112, v112
	v_add_f32_e32 v36, v36, v38
	v_lshlrev_b32_e32 v112, 16, v39
	v_and_b32_e32 v39, 0xffff0000, v39
	v_mul_f32_e32 v39, v39, v39
	v_fmac_f32_e32 v39, v112, v112
	v_add_f32_e32 v36, v36, v39
	s_waitcnt vmcnt(9)
	v_lshlrev_b32_e32 v112, 16, v40
	v_and_b32_e32 v40, 0xffff0000, v40
	v_mul_f32_e32 v40, v40, v40
	v_fmac_f32_e32 v40, v112, v112
	v_lshlrev_b32_e32 v112, 16, v41
	v_and_b32_e32 v41, 0xffff0000, v41
	v_mul_f32_e32 v41, v41, v41
	v_fmac_f32_e32 v41, v112, v112
	v_add_f32_e32 v40, v40, v41
	v_lshlrev_b32_e32 v112, 16, v42
	v_and_b32_e32 v42, 0xffff0000, v42
	v_mul_f32_e32 v42, v42, v42
	v_fmac_f32_e32 v42, v112, v112
	v_add_f32_e32 v40, v40, v42
	v_lshlrev_b32_e32 v112, 16, v43
	v_and_b32_e32 v43, 0xffff0000, v43
	v_mul_f32_e32 v43, v43, v43
	v_fmac_f32_e32 v43, v112, v112
	v_add_f32_e32 v40, v40, v43
	s_waitcnt vmcnt(8)
	v_lshlrev_b32_e32 v112, 16, v44
	v_and_b32_e32 v44, 0xffff0000, v44
	v_mul_f32_e32 v44, v44, v44
	v_fmac_f32_e32 v44, v112, v112
	v_lshlrev_b32_e32 v112, 16, v45
	v_and_b32_e32 v45, 0xffff0000, v45
	v_mul_f32_e32 v45, v45, v45
	v_fmac_f32_e32 v45, v112, v112
	v_add_f32_e32 v44, v44, v45
	v_lshlrev_b32_e32 v112, 16, v46
	v_and_b32_e32 v46, 0xffff0000, v46
	v_mul_f32_e32 v46, v46, v46
	v_fmac_f32_e32 v46, v112, v112
	v_add_f32_e32 v44, v44, v46
	v_lshlrev_b32_e32 v112, 16, v47
	v_and_b32_e32 v47, 0xffff0000, v47
	v_mul_f32_e32 v47, v47, v47
	v_fmac_f32_e32 v47, v112, v112
	v_add_f32_e32 v44, v44, v47
	s_waitcnt vmcnt(7)
	v_lshlrev_b32_e32 v112, 16, v48
	v_and_b32_e32 v48, 0xffff0000, v48
	v_mul_f32_e32 v48, v48, v48
	v_fmac_f32_e32 v48, v112, v112
	v_lshlrev_b32_e32 v112, 16, v49
	v_and_b32_e32 v49, 0xffff0000, v49
	v_mul_f32_e32 v49, v49, v49
	v_fmac_f32_e32 v49, v112, v112
	v_add_f32_e32 v48, v48, v49
	v_lshlrev_b32_e32 v112, 16, v50
	v_and_b32_e32 v50, 0xffff0000, v50
	v_mul_f32_e32 v50, v50, v50
	v_fmac_f32_e32 v50, v112, v112
	v_add_f32_e32 v48, v48, v50
	v_lshlrev_b32_e32 v112, 16, v51
	v_and_b32_e32 v51, 0xffff0000, v51
	v_mul_f32_e32 v51, v51, v51
	v_fmac_f32_e32 v51, v112, v112
	v_add_f32_e32 v48, v48, v51
	s_waitcnt vmcnt(6)
	v_lshlrev_b32_e32 v112, 16, v52
	v_and_b32_e32 v52, 0xffff0000, v52
	v_mul_f32_e32 v52, v52, v52
	v_fmac_f32_e32 v52, v112, v112
	v_lshlrev_b32_e32 v112, 16, v53
	v_and_b32_e32 v53, 0xffff0000, v53
	v_mul_f32_e32 v53, v53, v53
	v_fmac_f32_e32 v53, v112, v112
	v_add_f32_e32 v52, v52, v53
	v_lshlrev_b32_e32 v112, 16, v54
	v_and_b32_e32 v54, 0xffff0000, v54
	v_mul_f32_e32 v54, v54, v54
	v_fmac_f32_e32 v54, v112, v112
	v_add_f32_e32 v52, v52, v54
	v_lshlrev_b32_e32 v112, 16, v55
	v_and_b32_e32 v55, 0xffff0000, v55
	v_mul_f32_e32 v55, v55, v55
	v_fmac_f32_e32 v55, v112, v112
	v_add_f32_e32 v52, v52, v55
	s_waitcnt vmcnt(5)
	v_lshlrev_b32_e32 v112, 16, v56
	v_and_b32_e32 v56, 0xffff0000, v56
	v_mul_f32_e32 v56, v56, v56
	v_fmac_f32_e32 v56, v112, v112
	v_lshlrev_b32_e32 v112, 16, v57
	v_and_b32_e32 v57, 0xffff0000, v57
	v_mul_f32_e32 v57, v57, v57
	v_fmac_f32_e32 v57, v112, v112
	v_add_f32_e32 v56, v56, v57
	v_lshlrev_b32_e32 v112, 16, v58
	v_and_b32_e32 v58, 0xffff0000, v58
	v_mul_f32_e32 v58, v58, v58
	v_fmac_f32_e32 v58, v112, v112
	v_add_f32_e32 v56, v56, v58
	v_lshlrev_b32_e32 v112, 16, v59
	v_and_b32_e32 v59, 0xffff0000, v59
	v_mul_f32_e32 v59, v59, v59
	v_fmac_f32_e32 v59, v112, v112
	v_add_f32_e32 v56, v56, v59
	s_waitcnt vmcnt(4)
	v_lshlrev_b32_e32 v112, 16, v60
	v_and_b32_e32 v60, 0xffff0000, v60
	v_mul_f32_e32 v60, v60, v60
	v_fmac_f32_e32 v60, v112, v112
	v_lshlrev_b32_e32 v112, 16, v61
	v_and_b32_e32 v61, 0xffff0000, v61
	v_mul_f32_e32 v61, v61, v61
	v_fmac_f32_e32 v61, v112, v112
	v_add_f32_e32 v60, v60, v61
	v_lshlrev_b32_e32 v112, 16, v62
	v_and_b32_e32 v62, 0xffff0000, v62
	v_mul_f32_e32 v62, v62, v62
	v_fmac_f32_e32 v62, v112, v112
	v_add_f32_e32 v60, v60, v62
	v_lshlrev_b32_e32 v112, 16, v63
	v_and_b32_e32 v63, 0xffff0000, v63
	v_mul_f32_e32 v63, v63, v63
	v_fmac_f32_e32 v63, v112, v112
	v_add_f32_e32 v60, v60, v63
	s_waitcnt vmcnt(3)
	v_lshlrev_b32_e32 v112, 16, v64
	v_and_b32_e32 v64, 0xffff0000, v64
	v_mul_f32_e32 v64, v64, v64
	v_fmac_f32_e32 v64, v112, v112
	v_lshlrev_b32_e32 v112, 16, v65
	v_and_b32_e32 v65, 0xffff0000, v65
	v_mul_f32_e32 v65, v65, v65
	v_fmac_f32_e32 v65, v112, v112
	v_add_f32_e32 v64, v64, v65
	v_lshlrev_b32_e32 v112, 16, v66
	v_and_b32_e32 v66, 0xffff0000, v66
	v_mul_f32_e32 v66, v66, v66
	v_fmac_f32_e32 v66, v112, v112
	v_add_f32_e32 v64, v64, v66
	v_lshlrev_b32_e32 v112, 16, v67
	v_and_b32_e32 v67, 0xffff0000, v67
	v_mul_f32_e32 v67, v67, v67
	v_fmac_f32_e32 v67, v112, v112
	v_add_f32_e32 v64, v64, v67
	s_waitcnt vmcnt(2)
	v_lshlrev_b32_e32 v112, 16, v68
	v_and_b32_e32 v68, 0xffff0000, v68
	v_mul_f32_e32 v68, v68, v68
	v_fmac_f32_e32 v68, v112, v112
	v_lshlrev_b32_e32 v112, 16, v69
	v_and_b32_e32 v69, 0xffff0000, v69
	v_mul_f32_e32 v69, v69, v69
	v_fmac_f32_e32 v69, v112, v112
	v_add_f32_e32 v68, v68, v69
	v_lshlrev_b32_e32 v112, 16, v70
	v_and_b32_e32 v70, 0xffff0000, v70
	v_mul_f32_e32 v70, v70, v70
	v_fmac_f32_e32 v70, v112, v112
	v_add_f32_e32 v68, v68, v70
	v_lshlrev_b32_e32 v112, 16, v71
	v_and_b32_e32 v71, 0xffff0000, v71
	v_mul_f32_e32 v71, v71, v71
	v_fmac_f32_e32 v71, v112, v112
	v_add_f32_e32 v68, v68, v71
	s_waitcnt vmcnt(1)
	v_lshlrev_b32_e32 v112, 16, v72
	v_and_b32_e32 v72, 0xffff0000, v72
	v_mul_f32_e32 v72, v72, v72
	v_fmac_f32_e32 v72, v112, v112
	v_lshlrev_b32_e32 v112, 16, v73
	v_and_b32_e32 v73, 0xffff0000, v73
	v_mul_f32_e32 v73, v73, v73
	v_fmac_f32_e32 v73, v112, v112
	v_add_f32_e32 v72, v72, v73
	v_lshlrev_b32_e32 v112, 16, v74
	v_and_b32_e32 v74, 0xffff0000, v74
	v_mul_f32_e32 v74, v74, v74
	v_fmac_f32_e32 v74, v112, v112
	v_add_f32_e32 v72, v72, v74
	v_lshlrev_b32_e32 v112, 16, v75
	v_and_b32_e32 v75, 0xffff0000, v75
	v_mul_f32_e32 v75, v75, v75
	v_fmac_f32_e32 v75, v112, v112
	v_add_f32_e32 v72, v72, v75
	s_waitcnt vmcnt(0)
	v_lshlrev_b32_e32 v112, 16, v76
	v_and_b32_e32 v76, 0xffff0000, v76
	v_mul_f32_e32 v76, v76, v76
	v_fmac_f32_e32 v76, v112, v112
	v_lshlrev_b32_e32 v112, 16, v77
	v_and_b32_e32 v77, 0xffff0000, v77
	v_mul_f32_e32 v77, v77, v77
	v_fmac_f32_e32 v77, v112, v112
	v_add_f32_e32 v76, v76, v77
	v_lshlrev_b32_e32 v112, 16, v78
	v_and_b32_e32 v78, 0xffff0000, v78
	v_mul_f32_e32 v78, v78, v78
	v_fmac_f32_e32 v78, v112, v112
	v_add_f32_e32 v76, v76, v78
	v_lshlrev_b32_e32 v112, 16, v79
	v_and_b32_e32 v79, 0xffff0000, v79
	v_mul_f32_e32 v79, v79, v79
	v_fmac_f32_e32 v79, v112, v112
	v_add_f32_e32 v76, v76, v79
	s_nop 1
	v_permlane32_swap_b32_e32 v16, v48
	v_permlane32_swap_b32_e32 v20, v52
	v_permlane32_swap_b32_e32 v24, v56
	v_permlane32_swap_b32_e32 v28, v60
	v_permlane32_swap_b32_e32 v32, v64
	v_permlane32_swap_b32_e32 v36, v68
	v_permlane32_swap_b32_e32 v40, v72
	v_permlane32_swap_b32_e32 v44, v76
	s_nop 0
	v_add_f32_e32 v16, v16, v48
	v_add_f32_e32 v20, v20, v52
	v_add_f32_e32 v24, v24, v56
	v_add_f32_e32 v28, v28, v60
	v_add_f32_e32 v32, v32, v64
	v_add_f32_e32 v36, v36, v68
	v_add_f32_e32 v40, v40, v72
	v_add_f32_e32 v44, v44, v76
	s_nop 1
	v_permlane16_swap_b32_e32 v16, v32
	v_permlane16_swap_b32_e32 v20, v36
	v_permlane16_swap_b32_e32 v24, v40
	v_permlane16_swap_b32_e32 v28, v44
	s_nop 0
	v_add_f32_e32 v16, v16, v32
	v_add_f32_e32 v20, v20, v36
	v_add_f32_e32 v24, v24, v40
	v_add_f32_e32 v28, v28, v44
	s_nop 1
	v_add_f32_dpp v16, v16, v16 row_ror:8 row_mask:0xf bank_mask:0xf
	v_add_f32_dpp v20, v20, v20 row_ror:8 row_mask:0xf bank_mask:0xf
	v_add_f32_dpp v24, v24, v24 row_ror:8 row_mask:0xf bank_mask:0xf
	v_add_f32_dpp v28, v28, v28 row_ror:8 row_mask:0xf bank_mask:0xf
	s_nop 1
	v_add_f32_dpp v16, v16, v16 row_ror:4 row_mask:0xf bank_mask:0xf
	v_add_f32_dpp v20, v20, v20 row_ror:4 row_mask:0xf bank_mask:0xf
	v_add_f32_dpp v24, v24, v24 row_ror:4 row_mask:0xf bank_mask:0xf
	v_add_f32_dpp v28, v28, v28 row_ror:4 row_mask:0xf bank_mask:0xf
	s_nop 1
	v_add_f32_dpp v16, v16, v16 row_ror:2 row_mask:0xf bank_mask:0xf
	v_add_f32_dpp v20, v20, v20 row_ror:2 row_mask:0xf bank_mask:0xf
	v_add_f32_dpp v24, v24, v24 row_ror:2 row_mask:0xf bank_mask:0xf
	v_add_f32_dpp v28, v28, v28 row_ror:2 row_mask:0xf bank_mask:0xf
	s_nop 1
	v_add_f32_dpp v16, v16, v16 row_ror:1 row_mask:0xf bank_mask:0xf
	v_add_f32_dpp v20, v20, v20 row_ror:1 row_mask:0xf bank_mask:0xf
	v_add_f32_dpp v24, v24, v24 row_ror:1 row_mask:0xf bank_mask:0xf
	v_add_f32_dpp v28, v28, v28 row_ror:1 row_mask:0xf bank_mask:0xf
	v_fmamk_f32 v16, v16, 0x3b000000, v166
	v_fmamk_f32 v20, v20, 0x3b000000, v166
	v_fmamk_f32 v24, v24, 0x3b000000, v166
	v_fmamk_f32 v28, v28, 0x3b000000, v166
	v_mul_f32_e32 v112, 0x4b800000, v16
	v_cmp_gt_f32_e32 vcc, s58, v16
	s_nop 1
	v_cndmask_b32_e32 v16, v16, v112, vcc
	v_rsq_f32_e32 v16, v16
	s_nop 0
	v_mul_f32_e32 v112, 0x45800000, v16
	v_cndmask_b32_e32 v16, v16, v112, vcc
	v_mul_f32_e32 v16, 0x3dd53b94, v16
	v_mul_f32_e32 v112, 0x4b800000, v20
	v_cmp_gt_f32_e32 vcc, s58, v20
	s_nop 1
	v_cndmask_b32_e32 v20, v20, v112, vcc
	v_rsq_f32_e32 v20, v20
	s_nop 0
	v_mul_f32_e32 v112, 0x45800000, v20
	v_cndmask_b32_e32 v20, v20, v112, vcc
	v_mul_f32_e32 v20, 0x3dd53b94, v20
	v_mul_f32_e32 v112, 0x4b800000, v24
	v_cmp_gt_f32_e32 vcc, s58, v24
	s_nop 1
	v_cndmask_b32_e32 v24, v24, v112, vcc
	v_rsq_f32_e32 v24, v24
	s_nop 0
	v_mul_f32_e32 v112, 0x45800000, v24
	v_cndmask_b32_e32 v24, v24, v112, vcc
	v_mul_f32_e32 v24, 0x3dd53b94, v24
	v_mul_f32_e32 v112, 0x4b800000, v28
	v_cmp_gt_f32_e32 vcc, s58, v28
	s_nop 1
	v_cndmask_b32_e32 v28, v28, v112, vcc
	v_rsq_f32_e32 v28, v28
	s_nop 0
	v_mul_f32_e32 v112, 0x45800000, v28
	v_cndmask_b32_e32 v28, v28, v112, vcc
	v_mul_f32_e32 v28, 0x3dd53b94, v28
	v_mov_b32_e32 v112, v16
	v_mov_b32_e32 v113, v20
	v_mov_b32_e32 v114, v24
	v_mov_b32_e32 v115, v28
	v_cmp_eq_u32_e32 vcc, 0, v118
	s_and_saveexec_b64 s[0:1], vcc
	ds_write_b128 v117, v[112:115] offset:64
	s_or_b64 exec, exec, s[0:1]
.Lrsq_skip:
.LBB0_839:
	s_mul_i32 s0, s9, 6
	v_mov_b32_e32 v22, v167
	s_sub_i32 s1, s16, s0
	s_waitcnt lgkmcnt(0)
	s_barrier
	s_mul_i32 s16, s9, 0xb8000
	s_and_b32 s0, s1, 0xffff
	v_lshlrev_b32_e32 v1, 4, v22
	v_and_b32_e32 v0, 32, v22
	s_lshl_b64 s[2:3], s[16:17], 1
	v_bitop3_b32 v0, v1, v0, 48 bitop3:0x6c
	s_add_u32 s24, s22, s2
	v_lshrrev_b32_e32 v2, 1, v22
	v_lshrrev_b32_e32 v0, 1, v0
	s_addc_u32 s25, s23, s3
	s_lshl_b32 s1, s1, 18
	v_and_b32_e32 v16, 0xfffffc00, v1
	v_lshrrev_b32_e32 v3, 2, v22
	v_and_or_b32 v5, v2, 32, v0
	v_ashrrev_i32_e32 v0, 3, v22
	v_add_u32_e32 v4, 0x2000, v1
	v_add_u32_e32 v7, 0x4000, v1
	v_add_u32_e32 v1, 0x6000, v1
	s_add_u32 s26, s12, s1
	v_bfi_b32 v2, 15, v3, v0
	s_movk_i32 s1, 0xb80
	v_ashrrev_i32_e32 v4, 7, v4
	v_ashrrev_i32_e32 v7, 7, v7
	v_ashrrev_i32_e32 v1, 7, v1
	v_mul_lo_u32 v0, v2, s1
	v_bfi_b32 v6, -16, v4, v3
	v_bfi_b32 v7, -16, v7, v3
	v_bfi_b32 v1, -16, v1, v3
	v_or_b32_e32 v0, v0, v5
	v_mul_lo_u32 v4, v6, s1
	v_mul_lo_u32 v8, v7, s1
	v_mul_lo_u32 v3, v1, s1
	v_add_u32_e32 v17, 0, v16
	v_lshl_or_b32 v2, v2, 9, v5
	v_or_b32_e32 v4, v4, v5
	v_lshl_or_b32 v6, v6, 9, v5
	v_or_b32_e32 v8, v8, v5
	v_lshl_or_b32 v10, v7, 9, v5
	v_or_b32_e32 v12, v3, v5
	v_lshl_or_b32 v14, v1, 9, v5
	v_add_u32_e32 v5, 0x8000, v17
	v_ashrrev_i32_e32 v1, 31, v0
	v_readfirstlane_b32 s2, v17
	s_addc_u32 s27, s13, 0
	v_lshl_add_u64 v[0:1], v[0:1], 1, s[24:25]
	s_mov_b32 m0, s2
	v_ashrrev_i32_e32 v3, 31, v2
	v_readfirstlane_b32 s1, v5
	v_add_u32_e32 v32, 0x2000, v17
	global_load_lds_dwordx4 v[0:1], off
	v_lshl_add_u64 v[2:3], v[2:3], 1, s[26:27]
	s_mov_b32 m0, s1
	v_ashrrev_i32_e32 v5, 31, v4
	v_readfirstlane_b32 s3, v32
	v_add_u32_e32 v33, 0xa000, v17
	global_load_lds_dwordx4 v[2:3], off
	v_lshl_add_u64 v[4:5], v[4:5], 1, s[24:25]
	s_mov_b32 m0, s3
	v_ashrrev_i32_e32 v7, 31, v6
	v_readfirstlane_b32 s9, v33
	v_add_u32_e32 v34, 0x4000, v17
	global_load_lds_dwordx4 v[4:5], off
	v_lshl_add_u64 v[6:7], v[6:7], 1, s[26:27]
	s_mov_b32 m0, s9
	v_ashrrev_i32_e32 v9, 31, v8
	v_readfirstlane_b32 s10, v34
	v_add_u32_e32 v35, 0xc000, v17
	global_load_lds_dwordx4 v[6:7], off
	v_lshl_add_u64 v[8:9], v[8:9], 1, s[24:25]
	s_mov_b32 m0, s10
	v_ashrrev_i32_e32 v11, 31, v10
	v_readfirstlane_b32 s11, v35
	v_add_u32_e32 v36, 0x6000, v17
	v_add_u32_e32 v37, 0xe000, v17
	v_and_b32_e32 v17, 15, v22
	v_lshlrev_b32_e32 v19, 2, v22
	global_load_lds_dwordx4 v[8:9], off
	v_lshl_add_u64 v[10:11], v[10:11], 1, s[26:27]
	s_mov_b32 m0, s11
	v_ashrrev_i32_e32 v13, 31, v12
	v_readfirstlane_b32 s16, v36
	v_and_b32_e32 v18, 48, v22
	v_lshlrev_b32_e32 v17, 6, v17
	v_and_b32_e32 v19, 32, v19
	global_load_lds_dwordx4 v[10:11], off
	v_lshl_add_u64 v[12:13], v[12:13], 1, s[24:25]
	s_mov_b32 m0, s16
	v_ashrrev_i32_e32 v15, 31, v14
	v_readfirstlane_b32 s24, v37
	v_bitop3_b32 v25, v17, v19, v18 bitop3:0x36
	v_lshlrev_b32_e32 v17, 6, v22
	v_add_u32_e32 v39, s90, v16
	v_readlane_b32 s41, v254, 11
	global_load_lds_dwordx4 v[12:13], off
	v_lshl_add_u64 v[14:15], v[14:15], 1, s[26:27]
	s_mov_b32 m0, s24
	v_and_b32_e32 v30, 0xffffc000, v17
	v_and_b32_e32 v17, 0x3c0, v17
	v_add_u32_e32 v38, s41, v16
	v_readfirstlane_b32 s34, v39
	global_load_lds_dwordx4 v[14:15], off
	v_bitop3_b32 v127, v17, v19, v18 bitop3:0x36
	v_lshl_add_u64 v[16:17], v[0:1], 0, s[96:97]
	s_mov_b32 m0, s34
	v_readfirstlane_b32 s25, v38
	v_add_u32_e32 v40, 0x2000, v39
	s_waitcnt vmcnt(0)
	s_waitcnt vmcnt(0) lgkmcnt(0)
	s_barrier
	global_load_lds_dwordx4 v[16:17], off
	v_lshl_add_u64 v[16:17], v[2:3], 0, s[96:97]
	s_mov_b32 m0, s25
	v_readfirstlane_b32 s26, v40
	v_add_u32_e32 v41, 0x2000, v38
	global_load_lds_dwordx4 v[16:17], off
	v_lshl_add_u64 v[16:17], v[4:5], 0, s[96:97]
	s_mov_b32 m0, s26
	v_readfirstlane_b32 s27, v41
	v_add_u32_e32 v42, 0x4000, v39
	global_load_lds_dwordx4 v[16:17], off
	v_lshl_add_u64 v[16:17], v[6:7], 0, s[96:97]
	s_mov_b32 m0, s27
	v_readfirstlane_b32 s35, v42
	v_add_u32_e32 v43, 0x4000, v38
	global_load_lds_dwordx4 v[16:17], off
	v_lshl_add_u64 v[16:17], v[8:9], 0, s[96:97]
	s_mov_b32 m0, s35
	v_readfirstlane_b32 s36, v43
	v_add_u32_e32 v44, 0x6000, v39
	global_load_lds_dwordx4 v[16:17], off
	v_lshl_add_u64 v[16:17], v[10:11], 0, s[96:97]
	s_mov_b32 m0, s36
	v_readfirstlane_b32 s37, v44
	v_add_u32_e32 v45, 0x6000, v38
	global_load_lds_dwordx4 v[16:17], off
	v_lshl_add_u64 v[16:17], v[12:13], 0, s[96:97]
	s_mov_b32 m0, s37
	v_readfirstlane_b32 s40, v45
	global_load_lds_dwordx4 v[16:17], off
	v_lshl_add_u64 v[16:17], v[14:15], 0, s[96:97]
	s_mov_b32 m0, s40
	v_or_b32_e32 v126, 0x800, v30
	global_load_lds_dwordx4 v[16:17], off
	v_add_u32_e32 v16, 0, v25
	v_add_u32_e32 v24, v16, v30
	ds_read_b128 v[18:21], v24
	v_lshlrev_b32_e32 v17, 7, v22
	v_and_b32_e32 v162, 0x6000, v17
	v_add_u32_e32 v17, 0, v127
	v_add_u32_e32 v23, v16, v162
	v_add_u32_e32 v16, v17, v126
	ds_read_b128 v[26:29], v23 offset:32768
	ds_read_b128 v[46:49], v16
	ds_read_b128 v[50:53], v23 offset:34816
	ds_read_b128 v[62:65], v23 offset:36864
	ds_read_b128 v[66:69], v23 offset:38912
	v_or_b32_e32 v163, 0x1000, v30
	v_or_b32_e32 v164, 0x1800, v30
	v_or_b32_e32 v180, 0x2000, v30
	v_or_b32_e32 v182, 0x2800, v30
	v_or_b32_e32 v183, 0x3000, v30
	v_or_b32_e32 v193, 0x3800, v30
	s_waitcnt lgkmcnt(0)
	v_mfma_f32_16x16x32_bf16 v[54:57], v[26:29], v[18:21], 0
	v_add_u32_e32 v22, v17, v163
	ds_read_b128 v[90:93], v22
	v_mfma_f32_16x16x32_bf16 v[58:61], v[50:53], v[18:21], 0
	v_mfma_f32_16x16x32_bf16 v[70:73], v[62:65], v[18:21], 0
	v_mfma_f32_16x16x32_bf16 v[74:77], v[66:69], v[18:21], 0
	v_add_u32_e32 v19, v17, v164
	v_add_u32_e32 v21, v17, v180
	v_add_u32_e32 v18, v17, v182
	v_add_u32_e32 v20, v17, v183
	v_add_u32_e32 v17, v17, v193
	ds_read_b128 v[94:97], v19
	ds_read_b128 v[158:161], v20
	ds_read_b128 v[122:125], v21
	ds_read_b128 v[130:133], v18
	ds_read_b128 v[168:171], v17
	v_mfma_f32_16x16x32_bf16 v[78:81], v[26:29], v[46:49], 0
	v_mfma_f32_16x16x32_bf16 v[82:85], v[50:53], v[46:49], 0
	v_mfma_f32_16x16x32_bf16 v[86:89], v[62:65], v[46:49], 0
	v_mfma_f32_16x16x32_bf16 v[46:49], v[66:69], v[46:49], 0
	s_waitcnt lgkmcnt(0)
	v_mfma_f32_16x16x32_bf16 v[98:101], v[26:29], v[90:93], 0
	v_mfma_f32_16x16x32_bf16 v[102:105], v[50:53], v[90:93], 0
	v_mfma_f32_16x16x32_bf16 v[106:109], v[62:65], v[90:93], 0
	v_mfma_f32_16x16x32_bf16 v[90:93], v[66:69], v[90:93], 0
	v_mfma_f32_16x16x32_bf16 v[110:113], v[26:29], v[94:97], 0
	v_mfma_f32_16x16x32_bf16 v[114:117], v[50:53], v[94:97], 0
	v_mfma_f32_16x16x32_bf16 v[118:121], v[62:65], v[94:97], 0
	v_mfma_f32_16x16x32_bf16 v[94:97], v[66:69], v[94:97], 0
	v_mfma_f32_16x16x32_bf16 v[134:137], v[26:29], v[122:125], 0
	v_mfma_f32_16x16x32_bf16 v[138:141], v[50:53], v[122:125], 0
	v_mfma_f32_16x16x32_bf16 v[142:145], v[62:65], v[122:125], 0
	v_mfma_f32_16x16x32_bf16 v[122:125], v[66:69], v[122:125], 0
	v_mfma_f32_16x16x32_bf16 v[146:149], v[26:29], v[130:133], 0
	v_mfma_f32_16x16x32_bf16 v[150:153], v[50:53], v[130:133], 0
	v_mfma_f32_16x16x32_bf16 v[154:157], v[62:65], v[130:133], 0
	v_mfma_f32_16x16x32_bf16 v[130:133], v[66:69], v[130:133], 0
	v_mfma_f32_16x16x32_bf16 v[172:175], v[26:29], v[158:161], 0
	v_mfma_f32_16x16x32_bf16 v[176:179], v[50:53], v[158:161], 0
	v_mfma_f32_16x16x32_bf16 v[194:197], v[62:65], v[158:161], 0
	v_mfma_f32_16x16x32_bf16 v[158:161], v[66:69], v[158:161], 0
	v_mfma_f32_16x16x32_bf16 v[26:29], v[26:29], v[168:171], 0
	v_mfma_f32_16x16x32_bf16 v[50:53], v[50:53], v[168:171], 0
	v_mfma_f32_16x16x32_bf16 v[62:65], v[62:65], v[168:171], 0
	v_mfma_f32_16x16x32_bf16 v[66:69], v[66:69], v[168:171], 0
	ds_read_b128 v[168:171], v24 offset:1024
	ds_read_b128 v[198:201], v23 offset:33792
	ds_read_b128 v[202:205], v23 offset:35840
	ds_read_b128 v[206:209], v23 offset:37888
	ds_read_b128 v[210:213], v23 offset:39936
	s_waitcnt lgkmcnt(0)
	v_mfma_f32_16x16x32_bf16 v[54:57], v[198:201], v[168:171], v[54:57]
	v_mfma_f32_16x16x32_bf16 v[58:61], v[202:205], v[168:171], v[58:61]
	v_mfma_f32_16x16x32_bf16 v[70:73], v[206:209], v[168:171], v[70:73]
	v_mfma_f32_16x16x32_bf16 v[74:77], v[210:213], v[168:171], v[74:77]
	ds_read_b128 v[168:171], v16 offset:1024
	s_waitcnt lgkmcnt(0)
	v_mfma_f32_16x16x32_bf16 v[78:81], v[198:201], v[168:171], v[78:81]
	v_mfma_f32_16x16x32_bf16 v[82:85], v[202:205], v[168:171], v[82:85]
	v_mfma_f32_16x16x32_bf16 v[86:89], v[206:209], v[168:171], v[86:89]
	v_mfma_f32_16x16x32_bf16 v[46:49], v[210:213], v[168:171], v[46:49]
	ds_read_b128 v[168:171], v22 offset:1024
	s_waitcnt lgkmcnt(0)
	v_mfma_f32_16x16x32_bf16 v[98:101], v[198:201], v[168:171], v[98:101]
	v_mfma_f32_16x16x32_bf16 v[102:105], v[202:205], v[168:171], v[102:105]
	v_mfma_f32_16x16x32_bf16 v[106:109], v[206:209], v[168:171], v[106:109]
	v_mfma_f32_16x16x32_bf16 v[90:93], v[210:213], v[168:171], v[90:93]
	ds_read_b128 v[168:171], v19 offset:1024
	s_waitcnt lgkmcnt(0)
	v_mfma_f32_16x16x32_bf16 v[110:113], v[198:201], v[168:171], v[110:113]
	v_mfma_f32_16x16x32_bf16 v[114:117], v[202:205], v[168:171], v[114:117]
	v_mfma_f32_16x16x32_bf16 v[118:121], v[206:209], v[168:171], v[118:121]
	v_mfma_f32_16x16x32_bf16 v[94:97], v[210:213], v[168:171], v[94:97]
	ds_read_b128 v[168:171], v21 offset:1024
	s_waitcnt lgkmcnt(0)
	v_mfma_f32_16x16x32_bf16 v[134:137], v[198:201], v[168:171], v[134:137]
	v_mfma_f32_16x16x32_bf16 v[138:141], v[202:205], v[168:171], v[138:141]
	v_mfma_f32_16x16x32_bf16 v[142:145], v[206:209], v[168:171], v[142:145]
	v_mfma_f32_16x16x32_bf16 v[122:125], v[210:213], v[168:171], v[122:125]
	ds_read_b128 v[168:171], v18 offset:1024
	s_waitcnt lgkmcnt(0)
	v_mfma_f32_16x16x32_bf16 v[146:149], v[198:201], v[168:171], v[146:149]
	v_mfma_f32_16x16x32_bf16 v[150:153], v[202:205], v[168:171], v[150:153]
	v_mfma_f32_16x16x32_bf16 v[154:157], v[206:209], v[168:171], v[154:157]
	v_mfma_f32_16x16x32_bf16 v[168:171], v[210:213], v[168:171], v[130:133]
	s_nop 2
	ds_read_b128 v[130:133], v20 offset:1024
	s_waitcnt lgkmcnt(0)
	v_mfma_f32_16x16x32_bf16 v[172:175], v[198:201], v[130:133], v[172:175]
	v_mfma_f32_16x16x32_bf16 v[176:179], v[202:205], v[130:133], v[176:179]
	v_mfma_f32_16x16x32_bf16 v[194:197], v[206:209], v[130:133], v[194:197]
	v_mfma_f32_16x16x32_bf16 v[158:161], v[210:213], v[130:133], v[158:161]
	ds_read_b128 v[130:133], v17 offset:1024
	s_waitcnt lgkmcnt(0)
	v_mfma_f32_16x16x32_bf16 v[50:53], v[202:205], v[130:133], v[50:53]
	v_mfma_f32_16x16x32_bf16 v[62:65], v[206:209], v[130:133], v[62:65]
	v_mfma_f32_16x16x32_bf16 v[66:69], v[210:213], v[130:133], v[66:69]
	v_mfma_f32_16x16x32_bf16 v[198:201], v[198:201], v[130:133], v[26:29]
	s_mov_b32 m0, s2
	s_nop 1
	v_lshl_add_u64 v[26:27], v[0:1], 0, s[62:63]
	s_waitcnt vmcnt(0)
	s_waitcnt vmcnt(0)
	s_barrier
	global_load_lds_dwordx4 v[26:27], off
	v_lshl_add_u64 v[26:27], v[2:3], 0, s[62:63]
	s_mov_b32 m0, s1
	v_add_u32_e32 v127, s90, v127
	global_load_lds_dwordx4 v[26:27], off
	v_lshl_add_u64 v[26:27], v[4:5], 0, s[62:63]
	s_mov_b32 m0, s3
	s_nop 0
	global_load_lds_dwordx4 v[26:27], off
	v_lshl_add_u64 v[26:27], v[6:7], 0, s[62:63]
	s_mov_b32 m0, s9
	s_nop 0
	global_load_lds_dwordx4 v[26:27], off
	v_lshl_add_u64 v[26:27], v[8:9], 0, s[62:63]
	s_mov_b32 m0, s10
	s_nop 0
	global_load_lds_dwordx4 v[26:27], off
	v_lshl_add_u64 v[26:27], v[10:11], 0, s[62:63]
	s_mov_b32 m0, s11
	s_nop 0
	global_load_lds_dwordx4 v[26:27], off
	v_lshl_add_u64 v[26:27], v[12:13], 0, s[62:63]
	s_mov_b32 m0, s16
	s_nop 0
	global_load_lds_dwordx4 v[26:27], off
	v_lshl_add_u64 v[26:27], v[14:15], 0, s[62:63]
	s_mov_b32 m0, s24
	s_nop 0
	global_load_lds_dwordx4 v[26:27], off
	v_add3_u32 v26, s90, v25, v30
	ds_read_b128 v[28:31], v26
	v_add_u32_e32 v27, v127, v126
	ds_read_b128 v[130:133], v27
	v_add3_u32 v25, s41, v25, v162
	ds_read_b128 v[202:205], v25
	ds_read_b128 v[206:209], v25 offset:2048
	ds_read_b128 v[210:213], v25 offset:4096
	ds_read_b128 v[214:217], v25 offset:6144
	s_waitcnt lgkmcnt(0)
	v_mfma_f32_16x16x32_bf16 v[54:57], v[202:205], v[28:31], v[54:57]
	v_mfma_f32_16x16x32_bf16 v[58:61], v[206:209], v[28:31], v[58:61]
	v_mfma_f32_16x16x32_bf16 v[70:73], v[210:213], v[28:31], v[70:73]
	v_mfma_f32_16x16x32_bf16 v[74:77], v[214:217], v[28:31], v[74:77]
	v_add_u32_e32 v28, v127, v163
	v_add_u32_e32 v29, v127, v164
	v_add_u32_e32 v31, v127, v182
	v_mfma_f32_16x16x32_bf16 v[78:81], v[202:205], v[130:133], v[78:81]
	ds_read_b128 v[218:221], v31
	v_add_u32_e32 v30, v127, v180
	v_mfma_f32_16x16x32_bf16 v[82:85], v[206:209], v[130:133], v[82:85]
	v_mfma_f32_16x16x32_bf16 v[86:89], v[210:213], v[130:133], v[86:89]
	v_mfma_f32_16x16x32_bf16 v[46:49], v[214:217], v[130:133], v[46:49]
	ds_read_b128 v[130:133], v28
	s_waitcnt lgkmcnt(0)
	v_mfma_f32_16x16x32_bf16 v[98:101], v[202:205], v[130:133], v[98:101]
	v_mfma_f32_16x16x32_bf16 v[102:105], v[206:209], v[130:133], v[102:105]
	v_mfma_f32_16x16x32_bf16 v[106:109], v[210:213], v[130:133], v[106:109]
	v_mfma_f32_16x16x32_bf16 v[90:93], v[214:217], v[130:133], v[90:93]
	ds_read_b128 v[130:133], v29
	s_waitcnt lgkmcnt(0)
	v_mfma_f32_16x16x32_bf16 v[110:113], v[202:205], v[130:133], v[110:113]
	v_mfma_f32_16x16x32_bf16 v[114:117], v[206:209], v[130:133], v[114:117]
	v_mfma_f32_16x16x32_bf16 v[118:121], v[210:213], v[130:133], v[118:121]
	v_mfma_f32_16x16x32_bf16 v[94:97], v[214:217], v[130:133], v[94:97]
	ds_read_b128 v[130:133], v30
	s_waitcnt lgkmcnt(0)
	v_mfma_f32_16x16x32_bf16 v[134:137], v[202:205], v[130:133], v[134:137]
	v_mfma_f32_16x16x32_bf16 v[138:141], v[206:209], v[130:133], v[138:141]
	v_mfma_f32_16x16x32_bf16 v[142:145], v[210:213], v[130:133], v[142:145]
	v_mfma_f32_16x16x32_bf16 v[122:125], v[214:217], v[130:133], v[122:125]
	v_add_u32_e32 v130, v127, v183
	v_add_u32_e32 v131, v127, v193
	v_mfma_f32_16x16x32_bf16 v[146:149], v[202:205], v[218:221], v[146:149]
	v_mfma_f32_16x16x32_bf16 v[150:153], v[206:209], v[218:221], v[150:153]
	v_mfma_f32_16x16x32_bf16 v[154:157], v[210:213], v[218:221], v[154:157]
	v_mfma_f32_16x16x32_bf16 v[168:171], v[214:217], v[218:221], v[168:171]
	ds_read_b128 v[218:221], v130
	s_waitcnt lgkmcnt(0)
	v_mfma_f32_16x16x32_bf16 v[172:175], v[202:205], v[218:221], v[172:175]
	v_mfma_f32_16x16x32_bf16 v[176:179], v[206:209], v[218:221], v[176:179]
	v_mfma_f32_16x16x32_bf16 v[194:197], v[210:213], v[218:221], v[194:197]
	v_mfma_f32_16x16x32_bf16 v[158:161], v[214:217], v[218:221], v[158:161]
	ds_read_b128 v[218:221], v131
	s_waitcnt lgkmcnt(0)
	v_mfma_f32_16x16x32_bf16 v[50:53], v[206:209], v[218:221], v[50:53]
	v_mfma_f32_16x16x32_bf16 v[62:65], v[210:213], v[218:221], v[62:65]
	v_mfma_f32_16x16x32_bf16 v[66:69], v[214:217], v[218:221], v[66:69]
	v_mfma_f32_16x16x32_bf16 v[198:201], v[202:205], v[218:221], v[198:201]
	ds_read_b128 v[202:205], v26 offset:1024
	ds_read_b128 v[206:209], v25 offset:1024
	ds_read_b128 v[210:213], v25 offset:3072
	ds_read_b128 v[214:217], v25 offset:5120
	ds_read_b128 v[218:221], v25 offset:7168
	s_waitcnt lgkmcnt(0)
	v_mfma_f32_16x16x32_bf16 v[54:57], v[206:209], v[202:205], v[54:57]
	v_mfma_f32_16x16x32_bf16 v[58:61], v[210:213], v[202:205], v[58:61]
	v_mfma_f32_16x16x32_bf16 v[70:73], v[214:217], v[202:205], v[70:73]
	v_mfma_f32_16x16x32_bf16 v[74:77], v[218:221], v[202:205], v[74:77]
	ds_read_b128 v[202:205], v27 offset:1024
	s_waitcnt lgkmcnt(0)
	v_mfma_f32_16x16x32_bf16 v[78:81], v[206:209], v[202:205], v[78:81]
	v_mfma_f32_16x16x32_bf16 v[82:85], v[210:213], v[202:205], v[82:85]
	v_mfma_f32_16x16x32_bf16 v[86:89], v[214:217], v[202:205], v[86:89]
	v_mfma_f32_16x16x32_bf16 v[46:49], v[218:221], v[202:205], v[46:49]
	ds_read_b128 v[202:205], v28 offset:1024
	s_waitcnt lgkmcnt(0)
	v_mfma_f32_16x16x32_bf16 v[98:101], v[206:209], v[202:205], v[98:101]
	v_mfma_f32_16x16x32_bf16 v[102:105], v[210:213], v[202:205], v[102:105]
	v_mfma_f32_16x16x32_bf16 v[106:109], v[214:217], v[202:205], v[106:109]
	v_mfma_f32_16x16x32_bf16 v[90:93], v[218:221], v[202:205], v[90:93]
	ds_read_b128 v[202:205], v29 offset:1024
	s_waitcnt lgkmcnt(0)
	v_mfma_f32_16x16x32_bf16 v[110:113], v[206:209], v[202:205], v[110:113]
	v_mfma_f32_16x16x32_bf16 v[114:117], v[210:213], v[202:205], v[114:117]
	v_mfma_f32_16x16x32_bf16 v[118:121], v[214:217], v[202:205], v[118:121]
	v_mfma_f32_16x16x32_bf16 v[94:97], v[218:221], v[202:205], v[94:97]
	ds_read_b128 v[202:205], v30 offset:1024
	s_waitcnt lgkmcnt(0)
	v_mfma_f32_16x16x32_bf16 v[132:135], v[206:209], v[202:205], v[134:137]
	v_mfma_f32_16x16x32_bf16 v[136:139], v[210:213], v[202:205], v[138:141]
	v_mfma_f32_16x16x32_bf16 v[140:143], v[214:217], v[202:205], v[142:145]
	v_mfma_f32_16x16x32_bf16 v[122:125], v[218:221], v[202:205], v[122:125]
	ds_read_b128 v[202:205], v31 offset:1024
	s_waitcnt lgkmcnt(0)
	v_mfma_f32_16x16x32_bf16 v[144:147], v[206:209], v[202:205], v[146:149]
	v_mfma_f32_16x16x32_bf16 v[148:151], v[210:213], v[202:205], v[150:153]
	v_mfma_f32_16x16x32_bf16 v[152:155], v[214:217], v[202:205], v[154:157]
	v_mfma_f32_16x16x32_bf16 v[168:171], v[218:221], v[202:205], v[168:171]
	ds_read_b128 v[202:205], v130 offset:1024
	s_waitcnt lgkmcnt(0)
	v_mfma_f32_16x16x32_bf16 v[156:159], v[218:221], v[202:205], v[158:161]
	s_nop 2
	ds_read_b128 v[160:163], v131 offset:1024
	s_waitcnt lgkmcnt(0)
	v_mfma_f32_16x16x32_bf16 v[50:53], v[210:213], v[160:163], v[50:53]
	v_mfma_f32_16x16x32_bf16 v[62:65], v[214:217], v[160:163], v[62:65]
	v_mfma_f32_16x16x32_bf16 v[66:69], v[218:221], v[160:163], v[66:69]
	v_mfma_f32_16x16x32_bf16 v[172:175], v[206:209], v[202:205], v[172:175]
	v_mfma_f32_16x16x32_bf16 v[176:179], v[210:213], v[202:205], v[176:179]
	v_mfma_f32_16x16x32_bf16 v[194:197], v[214:217], v[202:205], v[194:197]
	v_mfma_f32_16x16x32_bf16 v[198:201], v[206:209], v[160:163], v[198:201]
	s_mov_b32 m0, s34
	v_lshl_add_u64 v[126:127], v[0:1], 0, s[6:7]
	s_waitcnt vmcnt(0)
	s_waitcnt vmcnt(0)
	s_barrier
	global_load_lds_dwordx4 v[126:127], off
	v_lshl_add_u64 v[126:127], v[2:3], 0, s[6:7]
	s_mov_b32 m0, s25
	s_nop 0
	global_load_lds_dwordx4 v[126:127], off
	v_lshl_add_u64 v[126:127], v[4:5], 0, s[6:7]
	s_mov_b32 m0, s26
	s_nop 0
	global_load_lds_dwordx4 v[126:127], off
	v_lshl_add_u64 v[126:127], v[6:7], 0, s[6:7]
	s_mov_b32 m0, s27
	s_nop 0
	global_load_lds_dwordx4 v[126:127], off
	v_lshl_add_u64 v[126:127], v[8:9], 0, s[6:7]
	s_mov_b32 m0, s35
	s_nop 0
	global_load_lds_dwordx4 v[126:127], off
	v_lshl_add_u64 v[126:127], v[10:11], 0, s[6:7]
	s_mov_b32 m0, s36
	s_nop 0
	global_load_lds_dwordx4 v[126:127], off
	v_lshl_add_u64 v[126:127], v[12:13], 0, s[6:7]
	s_mov_b32 m0, s37
	s_nop 0
	global_load_lds_dwordx4 v[126:127], off
	v_lshl_add_u64 v[126:127], v[14:15], 0, s[6:7]
	s_mov_b32 m0, s40
	s_nop 0
	global_load_lds_dwordx4 v[126:127], off
	ds_read_b128 v[160:163], v24
	ds_read_b128 v[202:205], v23 offset:32768
	ds_read_b128 v[206:209], v23 offset:34816
	ds_read_b128 v[210:213], v23 offset:36864
	ds_read_b128 v[214:217], v23 offset:38912
	s_waitcnt lgkmcnt(0)
	v_mfma_f32_16x16x32_bf16 v[54:57], v[202:205], v[160:163], v[54:57]
	v_mfma_f32_16x16x32_bf16 v[58:61], v[206:209], v[160:163], v[58:61]
	v_mfma_f32_16x16x32_bf16 v[70:73], v[210:213], v[160:163], v[70:73]
	v_mfma_f32_16x16x32_bf16 v[74:77], v[214:217], v[160:163], v[74:77]
	ds_read_b128 v[160:163], v16
	s_waitcnt lgkmcnt(0)
	v_mfma_f32_16x16x32_bf16 v[78:81], v[202:205], v[160:163], v[78:81]
	v_mfma_f32_16x16x32_bf16 v[82:85], v[206:209], v[160:163], v[82:85]
	v_mfma_f32_16x16x32_bf16 v[86:89], v[210:213], v[160:163], v[86:89]
	v_mfma_f32_16x16x32_bf16 v[46:49], v[214:217], v[160:163], v[46:49]
	ds_read_b128 v[160:163], v22
	s_waitcnt lgkmcnt(0)
	v_mfma_f32_16x16x32_bf16 v[98:101], v[202:205], v[160:163], v[98:101]
	v_mfma_f32_16x16x32_bf16 v[102:105], v[206:209], v[160:163], v[102:105]
	v_mfma_f32_16x16x32_bf16 v[106:109], v[210:213], v[160:163], v[106:109]
	v_mfma_f32_16x16x32_bf16 v[90:93], v[214:217], v[160:163], v[90:93]
	ds_read_b128 v[160:163], v19
	s_waitcnt lgkmcnt(0)
	v_mfma_f32_16x16x32_bf16 v[110:113], v[202:205], v[160:163], v[110:113]
	v_mfma_f32_16x16x32_bf16 v[114:117], v[206:209], v[160:163], v[114:117]
	v_mfma_f32_16x16x32_bf16 v[118:121], v[210:213], v[160:163], v[118:121]
	v_mfma_f32_16x16x32_bf16 v[94:97], v[214:217], v[160:163], v[94:97]
	ds_read_b128 v[160:163], v21
	s_waitcnt lgkmcnt(0)
	v_mfma_f32_16x16x32_bf16 v[132:135], v[202:205], v[160:163], v[132:135]
	v_mfma_f32_16x16x32_bf16 v[136:139], v[206:209], v[160:163], v[136:139]
	v_mfma_f32_16x16x32_bf16 v[140:143], v[210:213], v[160:163], v[140:143]
	v_mfma_f32_16x16x32_bf16 v[122:125], v[214:217], v[160:163], v[122:125]
	ds_read_b128 v[160:163], v18
	s_waitcnt lgkmcnt(0)
	v_mfma_f32_16x16x32_bf16 v[144:147], v[202:205], v[160:163], v[144:147]
	v_mfma_f32_16x16x32_bf16 v[148:151], v[206:209], v[160:163], v[148:151]
	v_mfma_f32_16x16x32_bf16 v[152:155], v[210:213], v[160:163], v[152:155]
	v_mfma_f32_16x16x32_bf16 v[160:163], v[214:217], v[160:163], v[168:171]
	s_nop 2
	ds_read_b128 v[168:171], v20
	s_waitcnt lgkmcnt(0)
	v_mfma_f32_16x16x32_bf16 v[172:175], v[202:205], v[168:171], v[172:175]
	v_mfma_f32_16x16x32_bf16 v[176:179], v[206:209], v[168:171], v[176:179]
	v_mfma_f32_16x16x32_bf16 v[194:197], v[210:213], v[168:171], v[194:197]
	v_mfma_f32_16x16x32_bf16 v[156:159], v[214:217], v[168:171], v[156:159]
	ds_read_b128 v[168:171], v17
	s_waitcnt lgkmcnt(0)
	v_mfma_f32_16x16x32_bf16 v[50:53], v[206:209], v[168:171], v[50:53]
	v_mfma_f32_16x16x32_bf16 v[62:65], v[210:213], v[168:171], v[62:65]
	v_mfma_f32_16x16x32_bf16 v[66:69], v[214:217], v[168:171], v[66:69]
	v_mfma_f32_16x16x32_bf16 v[198:201], v[202:205], v[168:171], v[198:201]
	ds_read_b128 v[168:171], v24 offset:1024
	ds_read_b128 v[202:205], v23 offset:33792
	ds_read_b128 v[206:209], v23 offset:35840
	ds_read_b128 v[210:213], v23 offset:37888
	ds_read_b128 v[214:217], v23 offset:39936
	s_waitcnt lgkmcnt(0)
	v_mfma_f32_16x16x32_bf16 v[54:57], v[202:205], v[168:171], v[54:57]
	v_mfma_f32_16x16x32_bf16 v[58:61], v[206:209], v[168:171], v[58:61]
	v_mfma_f32_16x16x32_bf16 v[70:73], v[210:213], v[168:171], v[70:73]
	v_mfma_f32_16x16x32_bf16 v[74:77], v[214:217], v[168:171], v[74:77]
	ds_read_b128 v[168:171], v16 offset:1024
	s_waitcnt lgkmcnt(0)
	v_mfma_f32_16x16x32_bf16 v[78:81], v[202:205], v[168:171], v[78:81]
	v_mfma_f32_16x16x32_bf16 v[82:85], v[206:209], v[168:171], v[82:85]
	v_mfma_f32_16x16x32_bf16 v[86:89], v[210:213], v[168:171], v[86:89]
	v_mfma_f32_16x16x32_bf16 v[46:49], v[214:217], v[168:171], v[46:49]
	ds_read_b128 v[168:171], v22 offset:1024
	s_waitcnt lgkmcnt(0)
	v_mfma_f32_16x16x32_bf16 v[98:101], v[202:205], v[168:171], v[98:101]
	v_mfma_f32_16x16x32_bf16 v[102:105], v[206:209], v[168:171], v[102:105]
	v_mfma_f32_16x16x32_bf16 v[106:109], v[210:213], v[168:171], v[106:109]
	v_mfma_f32_16x16x32_bf16 v[90:93], v[214:217], v[168:171], v[90:93]
	ds_read_b128 v[168:171], v19 offset:1024
	s_waitcnt lgkmcnt(0)
	v_mfma_f32_16x16x32_bf16 v[110:113], v[202:205], v[168:171], v[110:113]
	v_mfma_f32_16x16x32_bf16 v[114:117], v[206:209], v[168:171], v[114:117]
	v_mfma_f32_16x16x32_bf16 v[118:121], v[210:213], v[168:171], v[118:121]
	v_mfma_f32_16x16x32_bf16 v[94:97], v[214:217], v[168:171], v[94:97]
	ds_read_b128 v[168:171], v21 offset:1024
	s_waitcnt lgkmcnt(0)
	v_mfma_f32_16x16x32_bf16 v[132:135], v[202:205], v[168:171], v[132:135]
	v_mfma_f32_16x16x32_bf16 v[136:139], v[206:209], v[168:171], v[136:139]
	v_mfma_f32_16x16x32_bf16 v[140:143], v[210:213], v[168:171], v[140:143]
	v_mfma_f32_16x16x32_bf16 v[122:125], v[214:217], v[168:171], v[122:125]
	ds_read_b128 v[168:171], v18 offset:1024
	s_waitcnt lgkmcnt(0)
	v_mfma_f32_16x16x32_bf16 v[144:147], v[202:205], v[168:171], v[144:147]
	v_mfma_f32_16x16x32_bf16 v[148:151], v[206:209], v[168:171], v[148:151]
	v_mfma_f32_16x16x32_bf16 v[152:155], v[210:213], v[168:171], v[152:155]
	v_mfma_f32_16x16x32_bf16 v[160:163], v[214:217], v[168:171], v[160:163]
	ds_read_b128 v[168:171], v20 offset:1024
	s_waitcnt lgkmcnt(0)
	v_mfma_f32_16x16x32_bf16 v[172:175], v[202:205], v[168:171], v[172:175]
	v_mfma_f32_16x16x32_bf16 v[176:179], v[206:209], v[168:171], v[176:179]
	v_mfma_f32_16x16x32_bf16 v[194:197], v[210:213], v[168:171], v[194:197]
	v_mfma_f32_16x16x32_bf16 v[156:159], v[214:217], v[168:171], v[156:159]
	ds_read_b128 v[168:171], v17 offset:1024
	s_waitcnt lgkmcnt(0)
	v_mfma_f32_16x16x32_bf16 v[50:53], v[206:209], v[168:171], v[50:53]
	v_mfma_f32_16x16x32_bf16 v[62:65], v[210:213], v[168:171], v[62:65]
	v_mfma_f32_16x16x32_bf16 v[66:69], v[214:217], v[168:171], v[66:69]
	v_mfma_f32_16x16x32_bf16 v[198:201], v[202:205], v[168:171], v[198:201]
	s_mov_b64 s[26:27], 0x200
	s_mov_b32 m0, s2
	v_lshl_add_u64 v[126:127], v[0:1], 0, s[26:27]
	s_waitcnt vmcnt(0)
	s_waitcnt vmcnt(0)
	s_barrier
	global_load_lds_dwordx4 v[126:127], off
	v_lshl_add_u64 v[126:127], v[2:3], 0, s[26:27]
	s_mov_b32 m0, s1
	s_nop 0
	global_load_lds_dwordx4 v[126:127], off
	v_lshl_add_u64 v[126:127], v[4:5], 0, s[26:27]
	s_mov_b32 m0, s3
	s_nop 0
	global_load_lds_dwordx4 v[126:127], off
	v_lshl_add_u64 v[126:127], v[6:7], 0, s[26:27]
	s_mov_b32 m0, s9
	s_nop 0
	global_load_lds_dwordx4 v[126:127], off
	v_lshl_add_u64 v[126:127], v[8:9], 0, s[26:27]
	s_mov_b32 m0, s10
	s_nop 0
	global_load_lds_dwordx4 v[126:127], off
	v_lshl_add_u64 v[126:127], v[10:11], 0, s[26:27]
	s_mov_b32 m0, s11
	s_nop 0
	global_load_lds_dwordx4 v[126:127], off
	v_lshl_add_u64 v[126:127], v[12:13], 0, s[26:27]
	s_mov_b32 m0, s16
	s_nop 0
	global_load_lds_dwordx4 v[126:127], off
	v_lshl_add_u64 v[126:127], v[14:15], 0, s[26:27]
	s_mov_b32 m0, s24
	s_nop 0
	global_load_lds_dwordx4 v[126:127], off
	ds_read_b128 v[168:171], v26
	ds_read_b128 v[202:205], v25
	ds_read_b128 v[206:209], v25 offset:2048
	ds_read_b128 v[210:213], v25 offset:4096
	ds_read_b128 v[214:217], v25 offset:6144
	s_waitcnt lgkmcnt(0)
	v_mfma_f32_16x16x32_bf16 v[54:57], v[202:205], v[168:171], v[54:57]
	v_mfma_f32_16x16x32_bf16 v[58:61], v[206:209], v[168:171], v[58:61]
	v_mfma_f32_16x16x32_bf16 v[70:73], v[210:213], v[168:171], v[70:73]
	v_mfma_f32_16x16x32_bf16 v[74:77], v[214:217], v[168:171], v[74:77]
	ds_read_b128 v[168:171], v27
	s_waitcnt lgkmcnt(0)
	v_mfma_f32_16x16x32_bf16 v[78:81], v[202:205], v[168:171], v[78:81]
	v_mfma_f32_16x16x32_bf16 v[82:85], v[206:209], v[168:171], v[82:85]
	v_mfma_f32_16x16x32_bf16 v[86:89], v[210:213], v[168:171], v[86:89]
	v_mfma_f32_16x16x32_bf16 v[46:49], v[214:217], v[168:171], v[46:49]
	ds_read_b128 v[168:171], v28
	s_waitcnt lgkmcnt(0)
	v_mfma_f32_16x16x32_bf16 v[98:101], v[202:205], v[168:171], v[98:101]
	v_mfma_f32_16x16x32_bf16 v[102:105], v[206:209], v[168:171], v[102:105]
	v_mfma_f32_16x16x32_bf16 v[106:109], v[210:213], v[168:171], v[106:109]
	v_mfma_f32_16x16x32_bf16 v[90:93], v[214:217], v[168:171], v[90:93]
	ds_read_b128 v[168:171], v29
	s_waitcnt lgkmcnt(0)
	v_mfma_f32_16x16x32_bf16 v[110:113], v[202:205], v[168:171], v[110:113]
	v_mfma_f32_16x16x32_bf16 v[114:117], v[206:209], v[168:171], v[114:117]
	v_mfma_f32_16x16x32_bf16 v[118:121], v[210:213], v[168:171], v[118:121]
	v_mfma_f32_16x16x32_bf16 v[94:97], v[214:217], v[168:171], v[94:97]
	ds_read_b128 v[168:171], v30
	s_waitcnt lgkmcnt(0)
	v_mfma_f32_16x16x32_bf16 v[132:135], v[202:205], v[168:171], v[132:135]
	v_mfma_f32_16x16x32_bf16 v[136:139], v[206:209], v[168:171], v[136:139]
	v_mfma_f32_16x16x32_bf16 v[140:143], v[210:213], v[168:171], v[140:143]
	v_mfma_f32_16x16x32_bf16 v[122:125], v[214:217], v[168:171], v[122:125]
	ds_read_b128 v[168:171], v31
	s_waitcnt lgkmcnt(0)
	v_mfma_f32_16x16x32_bf16 v[144:147], v[202:205], v[168:171], v[144:147]
	v_mfma_f32_16x16x32_bf16 v[148:151], v[206:209], v[168:171], v[148:151]
	v_mfma_f32_16x16x32_bf16 v[152:155], v[210:213], v[168:171], v[152:155]
	v_mfma_f32_16x16x32_bf16 v[160:163], v[214:217], v[168:171], v[160:163]
	ds_read_b128 v[168:171], v130
	s_waitcnt lgkmcnt(0)
	v_mfma_f32_16x16x32_bf16 v[172:175], v[202:205], v[168:171], v[172:175]
	v_mfma_f32_16x16x32_bf16 v[176:179], v[206:209], v[168:171], v[176:179]
	v_mfma_f32_16x16x32_bf16 v[194:197], v[210:213], v[168:171], v[194:197]
	v_mfma_f32_16x16x32_bf16 v[156:159], v[214:217], v[168:171], v[156:159]
	ds_read_b128 v[168:171], v131
	s_waitcnt lgkmcnt(0)
	v_mfma_f32_16x16x32_bf16 v[50:53], v[206:209], v[168:171], v[50:53]
	v_mfma_f32_16x16x32_bf16 v[62:65], v[210:213], v[168:171], v[62:65]
	v_mfma_f32_16x16x32_bf16 v[66:69], v[214:217], v[168:171], v[66:69]
	v_mfma_f32_16x16x32_bf16 v[198:201], v[202:205], v[168:171], v[198:201]
	ds_read_b128 v[168:171], v26 offset:1024
	ds_read_b128 v[202:205], v25 offset:1024
	ds_read_b128 v[206:209], v25 offset:3072
	ds_read_b128 v[210:213], v25 offset:5120
	ds_read_b128 v[214:217], v25 offset:7168
	s_waitcnt lgkmcnt(0)
	v_mfma_f32_16x16x32_bf16 v[54:57], v[202:205], v[168:171], v[54:57]
	v_mfma_f32_16x16x32_bf16 v[58:61], v[206:209], v[168:171], v[58:61]
	v_mfma_f32_16x16x32_bf16 v[70:73], v[210:213], v[168:171], v[70:73]
	v_mfma_f32_16x16x32_bf16 v[74:77], v[214:217], v[168:171], v[74:77]
	ds_read_b128 v[168:171], v27 offset:1024
	s_waitcnt lgkmcnt(0)
	v_mfma_f32_16x16x32_bf16 v[78:81], v[202:205], v[168:171], v[78:81]
	v_mfma_f32_16x16x32_bf16 v[82:85], v[206:209], v[168:171], v[82:85]
	v_mfma_f32_16x16x32_bf16 v[86:89], v[210:213], v[168:171], v[86:89]
	v_mfma_f32_16x16x32_bf16 v[46:49], v[214:217], v[168:171], v[46:49]
	ds_read_b128 v[168:171], v28 offset:1024
	s_waitcnt lgkmcnt(0)
	v_mfma_f32_16x16x32_bf16 v[98:101], v[202:205], v[168:171], v[98:101]
	v_mfma_f32_16x16x32_bf16 v[102:105], v[206:209], v[168:171], v[102:105]
	v_mfma_f32_16x16x32_bf16 v[106:109], v[210:213], v[168:171], v[106:109]
	v_mfma_f32_16x16x32_bf16 v[90:93], v[214:217], v[168:171], v[90:93]
	ds_read_b128 v[168:171], v29 offset:1024
	s_waitcnt lgkmcnt(0)
	v_mfma_f32_16x16x32_bf16 v[110:113], v[202:205], v[168:171], v[110:113]
	v_mfma_f32_16x16x32_bf16 v[114:117], v[206:209], v[168:171], v[114:117]
	v_mfma_f32_16x16x32_bf16 v[118:121], v[210:213], v[168:171], v[118:121]
	v_mfma_f32_16x16x32_bf16 v[94:97], v[214:217], v[168:171], v[94:97]
	ds_read_b128 v[168:171], v30 offset:1024
	s_waitcnt lgkmcnt(0)
	v_mfma_f32_16x16x32_bf16 v[132:135], v[202:205], v[168:171], v[132:135]
	v_mfma_f32_16x16x32_bf16 v[136:139], v[206:209], v[168:171], v[136:139]
	v_mfma_f32_16x16x32_bf16 v[140:143], v[210:213], v[168:171], v[140:143]
	v_mfma_f32_16x16x32_bf16 v[122:125], v[214:217], v[168:171], v[122:125]
	ds_read_b128 v[168:171], v31 offset:1024
	s_waitcnt lgkmcnt(0)
	v_mfma_f32_16x16x32_bf16 v[144:147], v[202:205], v[168:171], v[144:147]
	v_mfma_f32_16x16x32_bf16 v[148:151], v[206:209], v[168:171], v[148:151]
	v_mfma_f32_16x16x32_bf16 v[152:155], v[210:213], v[168:171], v[152:155]
	v_mfma_f32_16x16x32_bf16 v[160:163], v[214:217], v[168:171], v[160:163]
	ds_read_b128 v[168:171], v130 offset:1024
	s_waitcnt lgkmcnt(0)
	v_mfma_f32_16x16x32_bf16 v[172:175], v[202:205], v[168:171], v[172:175]
	v_mfma_f32_16x16x32_bf16 v[176:179], v[206:209], v[168:171], v[176:179]
	v_mfma_f32_16x16x32_bf16 v[194:197], v[210:213], v[168:171], v[194:197]
	v_mfma_f32_16x16x32_bf16 v[156:159], v[214:217], v[168:171], v[156:159]
	ds_read_b128 v[168:171], v131 offset:1024
	s_waitcnt lgkmcnt(0)
	v_mfma_f32_16x16x32_bf16 v[50:53], v[206:209], v[168:171], v[50:53]
	v_mfma_f32_16x16x32_bf16 v[62:65], v[210:213], v[168:171], v[62:65]
	v_mfma_f32_16x16x32_bf16 v[66:69], v[214:217], v[168:171], v[66:69]
	v_mfma_f32_16x16x32_bf16 v[198:201], v[202:205], v[168:171], v[198:201]
	s_mov_b64 s[26:27], 0x280
	v_readfirstlane_b32 s25, v39
	v_lshl_add_u64 v[126:127], v[0:1], 0, s[26:27]
	s_mov_b32 m0, s25
	v_readfirstlane_b32 s3, v38
	s_waitcnt vmcnt(0)
	s_waitcnt vmcnt(0)
	s_barrier
	global_load_lds_dwordx4 v[126:127], off
	v_lshl_add_u64 v[126:127], v[2:3], 0, s[26:27]
	s_mov_b32 m0, s3
	v_readfirstlane_b32 s9, v40
	global_load_lds_dwordx4 v[126:127], off
	v_lshl_add_u64 v[38:39], v[4:5], 0, s[26:27]
	s_mov_b32 m0, s9
	v_readfirstlane_b32 s10, v41
	global_load_lds_dwordx4 v[38:39], off
	v_lshl_add_u64 v[38:39], v[6:7], 0, s[26:27]
	s_mov_b32 m0, s10
	v_readfirstlane_b32 s11, v42
	global_load_lds_dwordx4 v[38:39], off
	v_lshl_add_u64 v[38:39], v[8:9], 0, s[26:27]
	s_mov_b32 m0, s11
	v_readfirstlane_b32 s16, v43
	global_load_lds_dwordx4 v[38:39], off
	v_lshl_add_u64 v[38:39], v[10:11], 0, s[26:27]
	s_mov_b32 m0, s16
	v_readfirstlane_b32 s24, v44
	global_load_lds_dwordx4 v[38:39], off
	v_lshl_add_u64 v[38:39], v[12:13], 0, s[26:27]
	s_mov_b32 m0, s24
	s_nop 0
	global_load_lds_dwordx4 v[38:39], off
	v_lshl_add_u64 v[38:39], v[14:15], 0, s[26:27]
	v_readfirstlane_b32 s26, v45
	s_mov_b32 m0, s26
	s_nop 0
	global_load_lds_dwordx4 v[38:39], off
	ds_read_b128 v[38:41], v24
	ds_read_b128 v[42:45], v23 offset:32768
	ds_read_b128 v[168:171], v23 offset:34816
	ds_read_b128 v[202:205], v23 offset:36864
	ds_read_b128 v[206:209], v23 offset:38912
	s_waitcnt lgkmcnt(0)
	v_mfma_f32_16x16x32_bf16 v[54:57], v[42:45], v[38:41], v[54:57]
	v_mfma_f32_16x16x32_bf16 v[58:61], v[168:171], v[38:41], v[58:61]
	v_mfma_f32_16x16x32_bf16 v[70:73], v[202:205], v[38:41], v[70:73]
	v_mfma_f32_16x16x32_bf16 v[38:41], v[206:209], v[38:41], v[74:77]
	s_nop 2
	ds_read_b128 v[74:77], v16
	s_waitcnt lgkmcnt(0)
	v_mfma_f32_16x16x32_bf16 v[78:81], v[42:45], v[74:77], v[78:81]
	v_mfma_f32_16x16x32_bf16 v[82:85], v[168:171], v[74:77], v[82:85]
	v_mfma_f32_16x16x32_bf16 v[86:89], v[202:205], v[74:77], v[86:89]
	v_mfma_f32_16x16x32_bf16 v[46:49], v[206:209], v[74:77], v[46:49]
	ds_read_b128 v[74:77], v22
	s_waitcnt lgkmcnt(0)
	v_mfma_f32_16x16x32_bf16 v[98:101], v[42:45], v[74:77], v[98:101]
	v_mfma_f32_16x16x32_bf16 v[102:105], v[168:171], v[74:77], v[102:105]
	v_mfma_f32_16x16x32_bf16 v[106:109], v[202:205], v[74:77], v[106:109]
	v_mfma_f32_16x16x32_bf16 v[74:77], v[206:209], v[74:77], v[90:93]
	s_nop 2
	ds_read_b128 v[90:93], v19
	s_waitcnt lgkmcnt(0)
	v_mfma_f32_16x16x32_bf16 v[110:113], v[42:45], v[90:93], v[110:113]
	v_mfma_f32_16x16x32_bf16 v[114:117], v[168:171], v[90:93], v[114:117]
	v_mfma_f32_16x16x32_bf16 v[118:121], v[202:205], v[90:93], v[118:121]
	v_mfma_f32_16x16x32_bf16 v[90:93], v[206:209], v[90:93], v[94:97]
	s_nop 2
	ds_read_b128 v[94:97], v21
	s_waitcnt lgkmcnt(0)
	v_mfma_f32_16x16x32_bf16 v[132:135], v[42:45], v[94:97], v[132:135]
	v_mfma_f32_16x16x32_bf16 v[136:139], v[168:171], v[94:97], v[136:139]
	v_mfma_f32_16x16x32_bf16 v[140:143], v[202:205], v[94:97], v[140:143]
	v_mfma_f32_16x16x32_bf16 v[94:97], v[206:209], v[94:97], v[122:125]
	s_nop 2
	ds_read_b128 v[122:125], v18
	s_waitcnt lgkmcnt(0)
	v_mfma_f32_16x16x32_bf16 v[144:147], v[42:45], v[122:125], v[144:147]
	v_mfma_f32_16x16x32_bf16 v[148:151], v[168:171], v[122:125], v[148:151]
	v_mfma_f32_16x16x32_bf16 v[152:155], v[202:205], v[122:125], v[152:155]
	v_mfma_f32_16x16x32_bf16 v[122:125], v[206:209], v[122:125], v[160:163]
	s_nop 2
	ds_read_b128 v[160:163], v20
	s_waitcnt lgkmcnt(0)
	v_mfma_f32_16x16x32_bf16 v[172:175], v[42:45], v[160:163], v[172:175]
	v_mfma_f32_16x16x32_bf16 v[176:179], v[168:171], v[160:163], v[176:179]
	v_mfma_f32_16x16x32_bf16 v[194:197], v[202:205], v[160:163], v[194:197]
	v_mfma_f32_16x16x32_bf16 v[156:159], v[206:209], v[160:163], v[156:159]
	ds_read_b128 v[160:163], v17
	s_waitcnt lgkmcnt(0)
	v_mfma_f32_16x16x32_bf16 v[42:45], v[42:45], v[160:163], v[198:201]
	v_mfma_f32_16x16x32_bf16 v[50:53], v[168:171], v[160:163], v[50:53]
	v_mfma_f32_16x16x32_bf16 v[62:65], v[202:205], v[160:163], v[62:65]
	v_mfma_f32_16x16x32_bf16 v[66:69], v[206:209], v[160:163], v[66:69]
	ds_read_b128 v[160:163], v24 offset:1024
	ds_read_b128 v[168:171], v23 offset:33792
	ds_read_b128 v[198:201], v23 offset:35840
	ds_read_b128 v[202:205], v23 offset:37888
	ds_read_b128 v[206:209], v23 offset:39936
	s_waitcnt lgkmcnt(0)
	v_mfma_f32_16x16x32_bf16 v[54:57], v[168:171], v[160:163], v[54:57]
	v_mfma_f32_16x16x32_bf16 v[58:61], v[198:201], v[160:163], v[58:61]
	v_mfma_f32_16x16x32_bf16 v[70:73], v[202:205], v[160:163], v[70:73]
	v_mfma_f32_16x16x32_bf16 v[38:41], v[206:209], v[160:163], v[38:41]
	ds_read_b128 v[160:163], v16 offset:1024
	s_waitcnt lgkmcnt(0)
	v_mfma_f32_16x16x32_bf16 v[78:81], v[168:171], v[160:163], v[78:81]
	v_mfma_f32_16x16x32_bf16 v[82:85], v[198:201], v[160:163], v[82:85]
	v_mfma_f32_16x16x32_bf16 v[86:89], v[202:205], v[160:163], v[86:89]
	v_mfma_f32_16x16x32_bf16 v[46:49], v[206:209], v[160:163], v[46:49]
	ds_read_b128 v[160:163], v22 offset:1024
	s_waitcnt lgkmcnt(0)
	v_mfma_f32_16x16x32_bf16 v[98:101], v[168:171], v[160:163], v[98:101]
	v_mfma_f32_16x16x32_bf16 v[102:105], v[198:201], v[160:163], v[102:105]
	v_mfma_f32_16x16x32_bf16 v[106:109], v[202:205], v[160:163], v[106:109]
	v_mfma_f32_16x16x32_bf16 v[74:77], v[206:209], v[160:163], v[74:77]
	ds_read_b128 v[160:163], v19 offset:1024
	s_waitcnt lgkmcnt(0)
	v_mfma_f32_16x16x32_bf16 v[110:113], v[168:171], v[160:163], v[110:113]
	v_mfma_f32_16x16x32_bf16 v[114:117], v[198:201], v[160:163], v[114:117]
	v_mfma_f32_16x16x32_bf16 v[118:121], v[202:205], v[160:163], v[118:121]
	v_mfma_f32_16x16x32_bf16 v[90:93], v[206:209], v[160:163], v[90:93]
	ds_read_b128 v[160:163], v21 offset:1024
	s_waitcnt lgkmcnt(0)
	v_mfma_f32_16x16x32_bf16 v[132:135], v[168:171], v[160:163], v[132:135]
	v_mfma_f32_16x16x32_bf16 v[136:139], v[198:201], v[160:163], v[136:139]
	v_mfma_f32_16x16x32_bf16 v[140:143], v[202:205], v[160:163], v[140:143]
	v_mfma_f32_16x16x32_bf16 v[94:97], v[206:209], v[160:163], v[94:97]
	ds_read_b128 v[160:163], v18 offset:1024
	s_waitcnt lgkmcnt(0)
	v_mfma_f32_16x16x32_bf16 v[144:147], v[168:171], v[160:163], v[144:147]
	v_mfma_f32_16x16x32_bf16 v[148:151], v[198:201], v[160:163], v[148:151]
	v_mfma_f32_16x16x32_bf16 v[152:155], v[202:205], v[160:163], v[152:155]
	v_mfma_f32_16x16x32_bf16 v[122:125], v[206:209], v[160:163], v[122:125]
	ds_read_b128 v[160:163], v20 offset:1024
	s_waitcnt lgkmcnt(0)
	v_mfma_f32_16x16x32_bf16 v[172:175], v[168:171], v[160:163], v[172:175]
	v_mfma_f32_16x16x32_bf16 v[176:179], v[198:201], v[160:163], v[176:179]
	v_mfma_f32_16x16x32_bf16 v[194:197], v[202:205], v[160:163], v[194:197]
	v_mfma_f32_16x16x32_bf16 v[156:159], v[206:209], v[160:163], v[156:159]
	ds_read_b128 v[160:163], v17 offset:1024
	s_waitcnt lgkmcnt(0)
	v_mfma_f32_16x16x32_bf16 v[42:45], v[168:171], v[160:163], v[42:45]
	v_mfma_f32_16x16x32_bf16 v[50:53], v[198:201], v[160:163], v[50:53]
	v_mfma_f32_16x16x32_bf16 v[62:65], v[202:205], v[160:163], v[62:65]
	v_mfma_f32_16x16x32_bf16 v[66:69], v[206:209], v[160:163], v[66:69]
	s_mov_b64 s[34:35], 0x300
	s_mov_b32 m0, s2
	v_lshl_add_u64 v[126:127], v[0:1], 0, s[34:35]
	s_waitcnt vmcnt(0)
	s_waitcnt vmcnt(0)
	s_barrier
	global_load_lds_dwordx4 v[126:127], off
	v_lshl_add_u64 v[126:127], v[2:3], 0, s[34:35]
	s_mov_b32 m0, s1
	v_readfirstlane_b32 s1, v32
	global_load_lds_dwordx4 v[126:127], off
	v_lshl_add_u64 v[126:127], v[4:5], 0, s[34:35]
	s_mov_b32 m0, s1
	v_readfirstlane_b32 s1, v33
	global_load_lds_dwordx4 v[126:127], off
	v_lshl_add_u64 v[126:127], v[6:7], 0, s[34:35]
	s_mov_b32 m0, s1
	v_readfirstlane_b32 s1, v34
	global_load_lds_dwordx4 v[126:127], off
	v_lshl_add_u64 v[32:33], v[8:9], 0, s[34:35]
	s_mov_b32 m0, s1
	v_readfirstlane_b32 s1, v35
	global_load_lds_dwordx4 v[32:33], off
	v_lshl_add_u64 v[32:33], v[10:11], 0, s[34:35]
	s_mov_b32 m0, s1
	v_readfirstlane_b32 s1, v36
	global_load_lds_dwordx4 v[32:33], off
	v_lshl_add_u64 v[32:33], v[12:13], 0, s[34:35]
	s_mov_b32 m0, s1
	v_readfirstlane_b32 s1, v37
	global_load_lds_dwordx4 v[32:33], off
	v_lshl_add_u64 v[32:33], v[14:15], 0, s[34:35]
	s_mov_b32 m0, s1
	s_nop 0
	global_load_lds_dwordx4 v[32:33], off
	ds_read_b128 v[32:35], v26
	ds_read_b128 v[160:163], v25
	ds_read_b128 v[168:171], v25 offset:2048
	ds_read_b128 v[198:201], v25 offset:4096
	ds_read_b128 v[202:205], v25 offset:6144
	s_waitcnt lgkmcnt(0)
	v_mfma_f32_16x16x32_bf16 v[54:57], v[160:163], v[32:35], v[54:57]
	v_mfma_f32_16x16x32_bf16 v[58:61], v[168:171], v[32:35], v[58:61]
	v_mfma_f32_16x16x32_bf16 v[70:73], v[198:201], v[32:35], v[70:73]
	v_mfma_f32_16x16x32_bf16 v[32:35], v[202:205], v[32:35], v[38:41]
	s_nop 2
	ds_read_b128 v[36:39], v27
	s_waitcnt lgkmcnt(0)
	v_mfma_f32_16x16x32_bf16 v[78:81], v[160:163], v[36:39], v[78:81]
	v_mfma_f32_16x16x32_bf16 v[82:85], v[168:171], v[36:39], v[82:85]
	v_mfma_f32_16x16x32_bf16 v[86:89], v[198:201], v[36:39], v[86:89]
	v_mfma_f32_16x16x32_bf16 v[36:39], v[202:205], v[36:39], v[46:49]
	s_nop 2
	ds_read_b128 v[46:49], v28
	s_waitcnt lgkmcnt(0)
	v_mfma_f32_16x16x32_bf16 v[98:101], v[160:163], v[46:49], v[98:101]
	v_mfma_f32_16x16x32_bf16 v[102:105], v[168:171], v[46:49], v[102:105]
	v_mfma_f32_16x16x32_bf16 v[106:109], v[198:201], v[46:49], v[106:109]
	v_mfma_f32_16x16x32_bf16 v[46:49], v[202:205], v[46:49], v[74:77]
	s_nop 2
	ds_read_b128 v[74:77], v29
	s_waitcnt lgkmcnt(0)
	v_mfma_f32_16x16x32_bf16 v[110:113], v[160:163], v[74:77], v[110:113]
	v_mfma_f32_16x16x32_bf16 v[114:117], v[168:171], v[74:77], v[114:117]
	v_mfma_f32_16x16x32_bf16 v[118:121], v[198:201], v[74:77], v[118:121]
	v_mfma_f32_16x16x32_bf16 v[74:77], v[202:205], v[74:77], v[90:93]
	s_nop 2
	ds_read_b128 v[90:93], v30
	s_waitcnt lgkmcnt(0)
	v_mfma_f32_16x16x32_bf16 v[132:135], v[160:163], v[90:93], v[132:135]
	v_mfma_f32_16x16x32_bf16 v[136:139], v[168:171], v[90:93], v[136:139]
	v_mfma_f32_16x16x32_bf16 v[140:143], v[198:201], v[90:93], v[140:143]
	v_mfma_f32_16x16x32_bf16 v[90:93], v[202:205], v[90:93], v[94:97]
	s_nop 2
	ds_read_b128 v[94:97], v31
	s_waitcnt lgkmcnt(0)
	v_mfma_f32_16x16x32_bf16 v[144:147], v[160:163], v[94:97], v[144:147]
	v_mfma_f32_16x16x32_bf16 v[148:151], v[168:171], v[94:97], v[148:151]
	v_mfma_f32_16x16x32_bf16 v[152:155], v[198:201], v[94:97], v[152:155]
	v_mfma_f32_16x16x32_bf16 v[94:97], v[202:205], v[94:97], v[122:125]
	s_nop 2
	ds_read_b128 v[122:125], v130
	s_waitcnt lgkmcnt(0)
	v_mfma_f32_16x16x32_bf16 v[172:175], v[160:163], v[122:125], v[172:175]
	v_mfma_f32_16x16x32_bf16 v[176:179], v[168:171], v[122:125], v[176:179]
	v_mfma_f32_16x16x32_bf16 v[194:197], v[198:201], v[122:125], v[194:197]
	v_mfma_f32_16x16x32_bf16 v[122:125], v[202:205], v[122:125], v[156:159]
	s_nop 2
	ds_read_b128 v[156:159], v131
	s_waitcnt lgkmcnt(0)
	v_mfma_f32_16x16x32_bf16 v[40:43], v[160:163], v[156:159], v[42:45]
	v_mfma_f32_16x16x32_bf16 v[50:53], v[168:171], v[156:159], v[50:53]
	v_mfma_f32_16x16x32_bf16 v[62:65], v[198:201], v[156:159], v[62:65]
	v_mfma_f32_16x16x32_bf16 v[66:69], v[202:205], v[156:159], v[66:69]
	ds_read_b128 v[156:159], v26 offset:1024
	ds_read_b128 v[160:163], v25 offset:1024
	ds_read_b128 v[168:171], v25 offset:3072
	ds_read_b128 v[198:201], v25 offset:5120
	ds_read_b128 v[202:205], v25 offset:7168
	s_waitcnt lgkmcnt(0)
	v_mfma_f32_16x16x32_bf16 v[54:57], v[160:163], v[156:159], v[54:57]
	v_mfma_f32_16x16x32_bf16 v[58:61], v[168:171], v[156:159], v[58:61]
	v_mfma_f32_16x16x32_bf16 v[70:73], v[198:201], v[156:159], v[70:73]
	v_mfma_f32_16x16x32_bf16 v[32:35], v[202:205], v[156:159], v[32:35]
	ds_read_b128 v[156:159], v27 offset:1024
	s_waitcnt lgkmcnt(0)
	v_mfma_f32_16x16x32_bf16 v[78:81], v[160:163], v[156:159], v[78:81]
	v_mfma_f32_16x16x32_bf16 v[82:85], v[168:171], v[156:159], v[82:85]
	v_mfma_f32_16x16x32_bf16 v[86:89], v[198:201], v[156:159], v[86:89]
	v_mfma_f32_16x16x32_bf16 v[36:39], v[202:205], v[156:159], v[36:39]
	ds_read_b128 v[156:159], v28 offset:1024
	s_waitcnt lgkmcnt(0)
	v_mfma_f32_16x16x32_bf16 v[98:101], v[160:163], v[156:159], v[98:101]
	v_mfma_f32_16x16x32_bf16 v[102:105], v[168:171], v[156:159], v[102:105]
	v_mfma_f32_16x16x32_bf16 v[106:109], v[198:201], v[156:159], v[106:109]
	v_mfma_f32_16x16x32_bf16 v[44:47], v[202:205], v[156:159], v[46:49]
	ds_read_b128 v[156:159], v29 offset:1024
	s_waitcnt lgkmcnt(0)
	v_mfma_f32_16x16x32_bf16 v[110:113], v[160:163], v[156:159], v[110:113]
	v_mfma_f32_16x16x32_bf16 v[114:117], v[168:171], v[156:159], v[114:117]
	v_mfma_f32_16x16x32_bf16 v[118:121], v[198:201], v[156:159], v[118:121]
	v_mfma_f32_16x16x32_bf16 v[74:77], v[202:205], v[156:159], v[74:77]
	ds_read_b128 v[156:159], v30 offset:1024
	s_waitcnt lgkmcnt(0)
	v_mfma_f32_16x16x32_bf16 v[132:135], v[160:163], v[156:159], v[132:135]
	v_mfma_f32_16x16x32_bf16 v[136:139], v[168:171], v[156:159], v[136:139]
	v_mfma_f32_16x16x32_bf16 v[140:143], v[198:201], v[156:159], v[140:143]
	v_mfma_f32_16x16x32_bf16 v[90:93], v[202:205], v[156:159], v[90:93]
	ds_read_b128 v[156:159], v31 offset:1024
	s_waitcnt lgkmcnt(0)
	v_mfma_f32_16x16x32_bf16 v[144:147], v[160:163], v[156:159], v[144:147]
	v_mfma_f32_16x16x32_bf16 v[148:151], v[168:171], v[156:159], v[148:151]
	v_mfma_f32_16x16x32_bf16 v[152:155], v[198:201], v[156:159], v[152:155]
	v_mfma_f32_16x16x32_bf16 v[94:97], v[202:205], v[156:159], v[94:97]
	ds_read_b128 v[156:159], v130 offset:1024
	s_waitcnt lgkmcnt(0)
	v_mfma_f32_16x16x32_bf16 v[172:175], v[160:163], v[156:159], v[172:175]
	v_mfma_f32_16x16x32_bf16 v[176:179], v[168:171], v[156:159], v[176:179]
	v_mfma_f32_16x16x32_bf16 v[194:197], v[198:201], v[156:159], v[194:197]
	v_mfma_f32_16x16x32_bf16 v[122:125], v[202:205], v[156:159], v[122:125]
	ds_read_b128 v[156:159], v131 offset:1024
	s_waitcnt lgkmcnt(0)
	v_mfma_f32_16x16x32_bf16 v[40:43], v[160:163], v[156:159], v[40:43]
	v_mfma_f32_16x16x32_bf16 v[48:51], v[168:171], v[156:159], v[50:53]
	v_mfma_f32_16x16x32_bf16 v[62:65], v[198:201], v[156:159], v[62:65]
	v_mfma_f32_16x16x32_bf16 v[66:69], v[202:205], v[156:159], v[66:69]
	s_mov_b64 s[34:35], 0x380
	s_mov_b32 m0, s25
	v_lshl_add_u64 v[0:1], v[0:1], 0, s[34:35]
	s_waitcnt vmcnt(0)
	s_waitcnt vmcnt(0)
	s_barrier
	global_load_lds_dwordx4 v[0:1], off
	v_lshl_add_u64 v[0:1], v[2:3], 0, s[34:35]
	s_mov_b32 m0, s3
	s_nop 0
	global_load_lds_dwordx4 v[0:1], off
	v_lshl_add_u64 v[0:1], v[4:5], 0, s[34:35]
	s_mov_b32 m0, s9
	s_nop 0
	global_load_lds_dwordx4 v[0:1], off
	v_lshl_add_u64 v[0:1], v[6:7], 0, s[34:35]
	s_mov_b32 m0, s10
	s_nop 0
	global_load_lds_dwordx4 v[0:1], off
	v_lshl_add_u64 v[0:1], v[8:9], 0, s[34:35]
	s_mov_b32 m0, s11
	s_nop 0
	global_load_lds_dwordx4 v[0:1], off
	v_lshl_add_u64 v[0:1], v[10:11], 0, s[34:35]
	s_mov_b32 m0, s16
	s_nop 0
	global_load_lds_dwordx4 v[0:1], off
	v_lshl_add_u64 v[0:1], v[12:13], 0, s[34:35]
	s_mov_b32 m0, s24
	s_nop 0
	global_load_lds_dwordx4 v[0:1], off
	v_lshl_add_u64 v[0:1], v[14:15], 0, s[34:35]
	s_mov_b32 m0, s26
	s_nop 0
	global_load_lds_dwordx4 v[0:1], off
	ds_read_b128 v[0:3], v24
	ds_read_b128 v[4:7], v23 offset:32768
	ds_read_b128 v[12:15], v23 offset:34816
	ds_read_b128 v[156:159], v23 offset:38912
	s_waitcnt lgkmcnt(0)
	v_mfma_f32_16x16x32_bf16 v[8:11], v[4:7], v[0:3], v[54:57]
	v_mfma_f32_16x16x32_bf16 v[52:55], v[12:15], v[0:3], v[58:61]
	s_nop 2
	ds_read_b128 v[56:59], v23 offset:36864
	s_waitcnt lgkmcnt(0)
	v_mfma_f32_16x16x32_bf16 v[70:73], v[56:59], v[0:3], v[70:73]
	v_mfma_f32_16x16x32_bf16 v[0:3], v[156:159], v[0:3], v[32:35]
	s_nop 2
	ds_read_b128 v[32:35], v16
	s_waitcnt lgkmcnt(0)
	v_mfma_f32_16x16x32_bf16 v[78:81], v[4:7], v[32:35], v[78:81]
	v_mfma_f32_16x16x32_bf16 v[82:85], v[12:15], v[32:35], v[82:85]
	v_mfma_f32_16x16x32_bf16 v[86:89], v[56:59], v[32:35], v[86:89]
	v_mfma_f32_16x16x32_bf16 v[32:35], v[156:159], v[32:35], v[36:39]
	s_nop 2
	ds_read_b128 v[36:39], v22
	s_waitcnt lgkmcnt(0)
	v_mfma_f32_16x16x32_bf16 v[98:101], v[4:7], v[36:39], v[98:101]
	v_mfma_f32_16x16x32_bf16 v[102:105], v[12:15], v[36:39], v[102:105]
	v_mfma_f32_16x16x32_bf16 v[106:109], v[56:59], v[36:39], v[106:109]
	v_mfma_f32_16x16x32_bf16 v[36:39], v[156:159], v[36:39], v[44:47]
	s_nop 2
	ds_read_b128 v[44:47], v19
	s_waitcnt lgkmcnt(0)
	v_mfma_f32_16x16x32_bf16 v[110:113], v[4:7], v[44:47], v[110:113]
	v_mfma_f32_16x16x32_bf16 v[114:117], v[12:15], v[44:47], v[114:117]
	v_mfma_f32_16x16x32_bf16 v[118:121], v[56:59], v[44:47], v[118:121]
	v_mfma_f32_16x16x32_bf16 v[44:47], v[156:159], v[44:47], v[74:77]
	s_nop 2
	ds_read_b128 v[74:77], v21
	s_waitcnt lgkmcnt(0)
	v_mfma_f32_16x16x32_bf16 v[132:135], v[4:7], v[74:77], v[132:135]
	v_mfma_f32_16x16x32_bf16 v[136:139], v[12:15], v[74:77], v[136:139]
	v_mfma_f32_16x16x32_bf16 v[140:143], v[56:59], v[74:77], v[140:143]
	v_mfma_f32_16x16x32_bf16 v[74:77], v[156:159], v[74:77], v[90:93]
	s_nop 2
	ds_read_b128 v[90:93], v18
	s_waitcnt lgkmcnt(0)
	v_mfma_f32_16x16x32_bf16 v[144:147], v[4:7], v[90:93], v[144:147]
	v_mfma_f32_16x16x32_bf16 v[148:151], v[12:15], v[90:93], v[148:151]
	v_mfma_f32_16x16x32_bf16 v[152:155], v[56:59], v[90:93], v[152:155]
	v_mfma_f32_16x16x32_bf16 v[90:93], v[156:159], v[90:93], v[94:97]
	s_nop 2
	ds_read_b128 v[94:97], v20
	s_waitcnt lgkmcnt(0)
	v_mfma_f32_16x16x32_bf16 v[160:163], v[4:7], v[94:97], v[172:175]
	v_mfma_f32_16x16x32_bf16 v[168:171], v[12:15], v[94:97], v[176:179]
	v_mfma_f32_16x16x32_bf16 v[172:175], v[56:59], v[94:97], v[194:197]
	v_mfma_f32_16x16x32_bf16 v[94:97], v[156:159], v[94:97], v[122:125]
	s_nop 2
	ds_read_b128 v[122:125], v17
	s_waitcnt lgkmcnt(0)
	v_mfma_f32_16x16x32_bf16 v[4:7], v[4:7], v[122:125], v[40:43]
	v_mfma_f32_16x16x32_bf16 v[12:15], v[12:15], v[122:125], v[48:51]
	v_mfma_f32_16x16x32_bf16 v[40:43], v[56:59], v[122:125], v[62:65]
	v_mfma_f32_16x16x32_bf16 v[48:51], v[156:159], v[122:125], v[66:69]
	ds_read_b128 v[56:59], v24 offset:1024
	s_nop 0
	ds_read_b128 v[60:63], v23 offset:33792
	ds_read_b128 v[64:67], v23 offset:35840
	ds_read_b128 v[122:125], v23 offset:37888
	ds_read_b128 v[156:159], v23 offset:39936
	s_waitcnt lgkmcnt(0)
	v_mfma_f32_16x16x32_bf16 v[8:11], v[60:63], v[56:59], v[8:11]
	v_mfma_f32_16x16x32_bf16 v[52:55], v[64:67], v[56:59], v[52:55]
	v_mfma_f32_16x16x32_bf16 v[68:71], v[122:125], v[56:59], v[70:73]
	v_mfma_f32_16x16x32_bf16 v[0:3], v[156:159], v[56:59], v[0:3]
	ds_read_b128 v[56:59], v16 offset:1024
	s_waitcnt lgkmcnt(0)
	v_mfma_f32_16x16x32_bf16 v[78:81], v[60:63], v[56:59], v[78:81]
	v_mfma_f32_16x16x32_bf16 v[82:85], v[64:67], v[56:59], v[82:85]
	v_mfma_f32_16x16x32_bf16 v[86:89], v[122:125], v[56:59], v[86:89]
	v_mfma_f32_16x16x32_bf16 v[32:35], v[156:159], v[56:59], v[32:35]
	ds_read_b128 v[56:59], v22 offset:1024
	s_waitcnt lgkmcnt(0)
	v_mfma_f32_16x16x32_bf16 v[98:101], v[60:63], v[56:59], v[98:101]
	v_mfma_f32_16x16x32_bf16 v[102:105], v[64:67], v[56:59], v[102:105]
	v_mfma_f32_16x16x32_bf16 v[106:109], v[122:125], v[56:59], v[106:109]
	v_mfma_f32_16x16x32_bf16 v[36:39], v[156:159], v[56:59], v[36:39]
	ds_read_b128 v[56:59], v19 offset:1024
	s_waitcnt lgkmcnt(0)
	v_mfma_f32_16x16x32_bf16 v[110:113], v[60:63], v[56:59], v[110:113]
	v_mfma_f32_16x16x32_bf16 v[114:117], v[64:67], v[56:59], v[114:117]
	v_mfma_f32_16x16x32_bf16 v[118:121], v[122:125], v[56:59], v[118:121]
	v_mfma_f32_16x16x32_bf16 v[44:47], v[156:159], v[56:59], v[44:47]
	ds_read_b128 v[56:59], v21 offset:1024
	s_waitcnt lgkmcnt(0)
	v_mfma_f32_16x16x32_bf16 v[132:135], v[60:63], v[56:59], v[132:135]
	v_mfma_f32_16x16x32_bf16 v[136:139], v[64:67], v[56:59], v[136:139]
	v_mfma_f32_16x16x32_bf16 v[140:143], v[122:125], v[56:59], v[140:143]
	v_mfma_f32_16x16x32_bf16 v[56:59], v[156:159], v[56:59], v[74:77]
	s_nop 2
	ds_read_b128 v[72:75], v18 offset:1024
	ds_read_b128 v[18:21], v20 offset:1024
	s_waitcnt lgkmcnt(0)
	v_mfma_f32_16x16x32_bf16 v[144:147], v[60:63], v[72:75], v[144:147]
	v_mfma_f32_16x16x32_bf16 v[148:151], v[64:67], v[72:75], v[148:151]
	v_mfma_f32_16x16x32_bf16 v[152:155], v[122:125], v[72:75], v[152:155]
	v_mfma_f32_16x16x32_bf16 v[72:75], v[156:159], v[72:75], v[90:93]
	v_mfma_f32_16x16x32_bf16 v[90:93], v[60:63], v[18:21], v[160:163]
	v_mfma_f32_16x16x32_bf16 v[160:163], v[64:67], v[18:21], v[168:171]
	v_mfma_f32_16x16x32_bf16 v[168:171], v[122:125], v[18:21], v[172:175]
	v_mfma_f32_16x16x32_bf16 v[18:21], v[156:159], v[18:21], v[94:97]
	s_nop 2
	ds_read_b128 v[94:97], v17 offset:1024
	s_waitcnt lgkmcnt(0)
	v_mfma_f32_16x16x32_bf16 v[4:7], v[60:63], v[94:97], v[4:7]
	v_mfma_f32_16x16x32_bf16 v[12:15], v[64:67], v[94:97], v[12:15]
	v_mfma_f32_16x16x32_bf16 v[40:43], v[122:125], v[94:97], v[40:43]
	v_mfma_f32_16x16x32_bf16 v[48:51], v[156:159], v[94:97], v[48:51]
	s_waitcnt vmcnt(0)
	s_waitcnt vmcnt(0)
	s_barrier
	ds_read_b128 v[60:63], v26
	ds_read_b128 v[64:67], v25
	ds_read_b128 v[94:97], v25 offset:2048
	ds_read_b128 v[122:125], v25 offset:4096
	ds_read_b128 v[156:159], v25 offset:6144
	s_waitcnt lgkmcnt(3)
	v_mfma_f32_16x16x32_bf16 v[8:11], v[64:67], v[60:63], v[8:11]
	s_waitcnt lgkmcnt(2)
	v_mfma_f32_16x16x32_bf16 v[52:55], v[94:97], v[60:63], v[52:55]
	s_waitcnt lgkmcnt(1)
	v_mfma_f32_16x16x32_bf16 v[68:71], v[122:125], v[60:63], v[68:71]
	s_waitcnt lgkmcnt(0)
	v_mfma_f32_16x16x32_bf16 v[0:3], v[156:159], v[60:63], v[0:3]
	ds_read_b128 v[60:63], v27
	s_waitcnt lgkmcnt(0)
	v_mfma_f32_16x16x32_bf16 v[76:79], v[64:67], v[60:63], v[78:81]
	v_mfma_f32_16x16x32_bf16 v[80:83], v[94:97], v[60:63], v[82:85]
	v_mfma_f32_16x16x32_bf16 v[84:87], v[122:125], v[60:63], v[86:89]
	v_mfma_f32_16x16x32_bf16 v[32:35], v[156:159], v[60:63], v[32:35]
	ds_read_b128 v[60:63], v28
	s_waitcnt lgkmcnt(0)
	v_mfma_f32_16x16x32_bf16 v[172:175], v[64:67], v[60:63], v[98:101]
	v_mfma_f32_16x16x32_bf16 v[176:179], v[94:97], v[60:63], v[102:105]
	v_mfma_f32_16x16x32_bf16 v[194:197], v[122:125], v[60:63], v[106:109]
	v_mfma_f32_16x16x32_bf16 v[36:39], v[156:159], v[60:63], v[36:39]
	ds_read_b128 v[60:63], v29
	s_waitcnt lgkmcnt(0)
	v_mfma_f32_16x16x32_bf16 v[198:201], v[64:67], v[60:63], v[110:113]
	v_mfma_f32_16x16x32_bf16 v[202:205], v[94:97], v[60:63], v[114:117]
	v_mfma_f32_16x16x32_bf16 v[206:209], v[122:125], v[60:63], v[118:121]
	v_mfma_f32_16x16x32_bf16 v[44:47], v[156:159], v[60:63], v[44:47]
	ds_read_b128 v[60:63], v30
	s_waitcnt lgkmcnt(0)
	v_mfma_f32_16x16x32_bf16 v[210:213], v[156:159], v[60:63], v[56:59]
	s_nop 2
	ds_read_b128 v[56:59], v31
	s_waitcnt lgkmcnt(0)
	v_mfma_f32_16x16x32_bf16 v[144:147], v[64:67], v[56:59], v[144:147]
	v_mfma_f32_16x16x32_bf16 v[148:151], v[94:97], v[56:59], v[148:151]
	v_mfma_f32_16x16x32_bf16 v[152:155], v[122:125], v[56:59], v[152:155]
	v_mfma_f32_16x16x32_bf16 v[214:217], v[156:159], v[56:59], v[72:75]
	ds_read_b128 v[56:59], v130
	s_waitcnt lgkmcnt(0)
	v_mfma_f32_16x16x32_bf16 v[20:23], v[156:159], v[56:59], v[18:21]
	s_nop 2
	ds_read_b128 v[16:19], v131
	v_mfma_f32_16x16x32_bf16 v[140:143], v[122:125], v[60:63], v[140:143]
	s_waitcnt lgkmcnt(0)
	v_mfma_f32_16x16x32_bf16 v[4:7], v[64:67], v[16:19], v[4:7]
	v_mfma_f32_16x16x32_bf16 v[132:135], v[64:67], v[60:63], v[132:135]
	v_mfma_f32_16x16x32_bf16 v[136:139], v[94:97], v[60:63], v[136:139]
	v_mfma_f32_16x16x32_bf16 v[218:221], v[64:67], v[56:59], v[90:93]
	v_mfma_f32_16x16x32_bf16 v[160:163], v[94:97], v[56:59], v[160:163]
	v_mfma_f32_16x16x32_bf16 v[168:171], v[122:125], v[56:59], v[168:171]
	v_mfma_f32_16x16x32_bf16 v[222:225], v[94:97], v[16:19], v[12:15]
	v_mfma_f32_16x16x32_bf16 v[226:229], v[122:125], v[16:19], v[40:43]
	v_mfma_f32_16x16x32_bf16 v[156:159], v[156:159], v[16:19], v[48:51]
	s_nop 0
	ds_read_b128 v[12:15], v26 offset:1024
	ds_read_b128 v[230:233], v25 offset:1024
	ds_read_b128 v[238:241], v25 offset:7168
	s_waitcnt lgkmcnt(0)
	v_mfma_f32_16x16x32_bf16 v[120:123], v[238:241], v[12:15], v[0:3]
	s_nop 2
	ds_read_b128 v[0:3], v27 offset:1024
	ds_read_b128 v[234:237], v25 offset:5120
	v_mfma_f32_16x16x32_bf16 v[112:115], v[230:233], v[12:15], v[8:11]
	s_nop 2
	ds_read_b128 v[8:11], v25 offset:3072
	s_waitcnt lgkmcnt(2)
	v_mfma_f32_16x16x32_bf16 v[108:111], v[230:233], v[0:3], v[76:79]
	s_waitcnt lgkmcnt(0)
	v_mfma_f32_16x16x32_bf16 v[96:99], v[8:11], v[0:3], v[80:83]
	v_mfma_f32_16x16x32_bf16 v[104:107], v[234:237], v[0:3], v[84:87]
	v_mfma_f32_16x16x32_bf16 v[100:103], v[238:241], v[0:3], v[32:35]
	ds_read_b128 v[0:3], v28 offset:1024
	s_waitcnt lgkmcnt(0)
	v_mfma_f32_16x16x32_bf16 v[92:95], v[230:233], v[0:3], v[172:175]
	v_mfma_f32_16x16x32_bf16 v[80:83], v[8:11], v[0:3], v[176:179]
	v_mfma_f32_16x16x32_bf16 v[88:91], v[234:237], v[0:3], v[194:197]
	v_mfma_f32_16x16x32_bf16 v[84:87], v[238:241], v[0:3], v[36:39]
	ds_read_b128 v[0:3], v29 offset:1024
	v_mfma_f32_16x16x32_bf16 v[124:127], v[234:237], v[12:15], v[68:71]
	s_waitcnt lgkmcnt(0)
	v_mfma_f32_16x16x32_bf16 v[76:79], v[230:233], v[0:3], v[198:201]
	v_mfma_f32_16x16x32_bf16 v[64:67], v[8:11], v[0:3], v[202:205]
	v_mfma_f32_16x16x32_bf16 v[72:75], v[234:237], v[0:3], v[206:209]
	v_mfma_f32_16x16x32_bf16 v[68:71], v[238:241], v[0:3], v[44:47]
	ds_read_b128 v[0:3], v30 offset:1024
	v_mfma_f32_16x16x32_bf16 v[116:119], v[8:11], v[12:15], v[52:55]
	s_waitcnt lgkmcnt(0)
	v_mfma_f32_16x16x32_bf16 v[60:63], v[230:233], v[0:3], v[132:135]
	v_mfma_f32_16x16x32_bf16 v[48:51], v[8:11], v[0:3], v[136:139]
	v_mfma_f32_16x16x32_bf16 v[56:59], v[234:237], v[0:3], v[140:143]
	v_mfma_f32_16x16x32_bf16 v[52:55], v[238:241], v[0:3], v[210:213]
	ds_read_b128 v[0:3], v31 offset:1024
	s_waitcnt lgkmcnt(0)
	v_mfma_f32_16x16x32_bf16 v[44:47], v[230:233], v[0:3], v[144:147]
	v_mfma_f32_16x16x32_bf16 v[32:35], v[8:11], v[0:3], v[148:151]
	v_mfma_f32_16x16x32_bf16 v[40:43], v[234:237], v[0:3], v[152:155]
	v_mfma_f32_16x16x32_bf16 v[36:39], v[238:241], v[0:3], v[214:217]
	ds_read_b128 v[0:3], v130 offset:1024
	ds_read_b128 v[130:133], v131 offset:1024
	s_waitcnt lgkmcnt(1)
	v_mfma_f32_16x16x32_bf16 v[28:31], v[230:233], v[0:3], v[218:221]
	v_mfma_f32_16x16x32_bf16 v[16:19], v[8:11], v[0:3], v[160:163]
	v_mfma_f32_16x16x32_bf16 v[24:27], v[234:237], v[0:3], v[168:171]
	v_mfma_f32_16x16x32_bf16 v[20:23], v[238:241], v[0:3], v[20:23]
	s_waitcnt lgkmcnt(0)
	v_mfma_f32_16x16x32_bf16 v[12:15], v[230:233], v[130:133], v[4:7]
	v_mfma_f32_16x16x32_bf16 v[0:3], v[8:11], v[130:133], v[222:225]
	v_mfma_f32_16x16x32_bf16 v[8:11], v[234:237], v[130:133], v[226:229]
	v_mfma_f32_16x16x32_bf16 v[4:7], v[238:241], v[130:133], v[156:159]
	s_waitcnt vmcnt(0)
	s_barrier
	s_add_i32 s0, s20, 0xfffffde0
	s_mul_i32 s1, s0, 0xaaab
	s_lshr_b32 s1, s1, 18
	s_mul_i32 s2, s1, 6
	s_sub_i32 s2, s0, s2
	v_readfirstlane_b32 s8, v167
	v_and_b32_e32 v128, 15, v167
	v_bfe_u32 v129, v167, 4, 2
	s_lshr_b32 s8, s8, 6
	s_and_b32 s9, s8, 3
	s_lshr_b32 s8, s8, 2
	s_lshl_b32 s3, s1, 8
	s_lshl_b32 s10, s8, 7
	s_add_u32 s3, s3, s10
	s_lshl_b32 s10, s2, 8
	s_lshl_b32 s11, s9, 6
	s_add_u32 s10, s10, s11
	v_readlane_b32 s24, v255, 28
	v_readlane_b32 s25, v255, 29
	s_mul_i32 s11, s3, 0xc00
	s_lshl_b32 s26, s10, 1
	s_add_u32 s11, s11, s26
	s_add_u32 s24, s24, s11
	s_addc_u32 s25, s25, 0
	v_mul_u32_u24_e32 v131, 0xc00, v128
	v_lshl_add_u32 v131, v129, 3, v131
	s_lshl_b32 s11, s8, 9
	v_lshl_add_u32 v130, v128, 2, s11
	v_add_u32_e32 v130, 0x20000, v130
	ds_read_b32 v134, v130
	ds_read_b32 v135, v130 offset:64
	ds_read_b32 v136, v130 offset:128
	ds_read_b32 v137, v130 offset:192
	ds_read_b32 v138, v130 offset:256
	ds_read_b32 v139, v130 offset:320
	ds_read_b32 v140, v130 offset:384
	ds_read_b32 v141, v130 offset:448
	s_lshl_b32 s11, s2, 2
	s_add_u32 s11, s11, s9
	s_mul_i32 s26, s11, 0xaaab
	s_lshr_b32 s26, s26, 17
	s_mul_i32 s26, s26, 3
	s_sub_u32 s11, s11, s26
	s_cmp_eq_u32 s11, 2
	s_cselect_b32 s11, 1, 0
	s_cmp_lt_u32 s1, 64
	s_cselect_b32 s11, s11, 0
	s_cmp_eq_u32 s11, 0
	s_cbranch_scc1 .Lq_norope
	s_and_b32 s26, s3, 0xfff
	s_lshr_b32 s26, s26, 6
	s_lshl_b32 s26, s26, 7
	v_lshlrev_b32_e32 v132, 5, v129
	v_lshl_add_u32 v133, v128, 7, v132
	v_add_u32_e32 v132, s26, v132
	global_load_dwordx4 v[194:197], v132, s[38:39]
	global_load_dwordx4 v[198:201], v132, s[38:39] offset:16
	global_load_dwordx4 v[210:213], v133, s[38:39]
	global_load_dwordx4 v[214:217], v133, s[38:39] offset:16
	global_load_dwordx4 v[202:205], v132, s[38:39]
	global_load_dwordx4 v[206:209], v132, s[38:39] offset:16
	global_load_dwordx4 v[218:221], v133, s[38:39] offset:2048
	global_load_dwordx4 v[222:225], v133, s[38:39] offset:2064
	s_waitcnt lgkmcnt(0)
	global_load_dwordx4 v[226:229], v132, s[38:39]
	global_load_dwordx4 v[230:233], v132, s[38:39] offset:16
	v_add_u32_e32 v160, 4096, v133
	global_load_dwordx4 v[142:145], v160, s[38:39]
	global_load_dwordx4 v[146:149], v160, s[38:39] offset:16
	global_load_dwordx4 v[234:237], v132, s[38:39]
	global_load_dwordx4 v[238:241], v132, s[38:39] offset:16
	v_add_u32_e32 v160, 6144, v133
	global_load_dwordx4 v[150:153], v160, s[38:39]
	global_load_dwordx4 v[154:157], v160, s[38:39] offset:16
	v_mul_f32_e32 v112, v112, v134
	v_mul_f32_e32 v113, v113, v134
	v_mul_f32_e32 v114, v114, v134
	v_mul_f32_e32 v115, v115, v134
	v_mul_f32_e32 v116, v116, v134
	v_mul_f32_e32 v117, v117, v134
	v_mul_f32_e32 v118, v118, v134
	v_mul_f32_e32 v119, v119, v134
	v_mul_f32_e32 v124, v124, v134
	v_mul_f32_e32 v125, v125, v134
	v_mul_f32_e32 v126, v126, v134
	v_mul_f32_e32 v127, v127, v134
	v_mul_f32_e32 v120, v120, v134
	v_mul_f32_e32 v121, v121, v134
	v_mul_f32_e32 v122, v122, v134
	v_mul_f32_e32 v123, v123, v134
	v_mul_f32_e32 v108, v108, v135
	v_mul_f32_e32 v109, v109, v135
	v_mul_f32_e32 v110, v110, v135
	v_mul_f32_e32 v111, v111, v135
	v_mul_f32_e32 v96, v96, v135
	v_mul_f32_e32 v97, v97, v135
	v_mul_f32_e32 v98, v98, v135
	v_mul_f32_e32 v99, v99, v135
	v_mul_f32_e32 v104, v104, v135
	v_mul_f32_e32 v105, v105, v135
	v_mul_f32_e32 v106, v106, v135
	v_mul_f32_e32 v107, v107, v135
	v_mul_f32_e32 v100, v100, v135
	v_mul_f32_e32 v101, v101, v135
	v_mul_f32_e32 v102, v102, v135
	v_mul_f32_e32 v103, v103, v135
	s_waitcnt vmcnt(8)
	v_mul_f32_e32 v160, v116, v195
	v_mul_f32_e32 v161, v112, v195
	v_fma_f32 v112, v112, v194, -v160
	v_fma_f32 v116, v116, v194, v161
	v_mul_f32_e32 v162, v117, v197
	v_mul_f32_e32 v163, v113, v197
	v_fma_f32 v113, v113, v196, -v162
	v_fma_f32 v117, v117, v196, v163
	v_mul_f32_e32 v160, v118, v199
	v_mul_f32_e32 v161, v114, v199
	v_fma_f32 v114, v114, v198, -v160
	v_fma_f32 v118, v118, v198, v161
	v_mul_f32_e32 v162, v119, v201
	v_mul_f32_e32 v163, v115, v201
	v_fma_f32 v115, v115, v200, -v162
	v_fma_f32 v119, v119, v200, v163
	v_mul_f32_e32 v160, v120, v211
	v_mul_f32_e32 v161, v124, v211
	v_fma_f32 v124, v124, v210, -v160
	v_fma_f32 v120, v120, v210, v161
	v_mul_f32_e32 v162, v121, v213
	v_mul_f32_e32 v163, v125, v213
	v_fma_f32 v125, v125, v212, -v162
	v_fma_f32 v121, v121, v212, v163
	v_mul_f32_e32 v160, v122, v215
	v_mul_f32_e32 v161, v126, v215
	v_fma_f32 v126, v126, v214, -v160
	v_fma_f32 v122, v122, v214, v161
	v_mul_f32_e32 v162, v123, v217
	v_mul_f32_e32 v163, v127, v217
	v_fma_f32 v127, v127, v216, -v162
	v_fma_f32 v123, v123, v216, v163
	v_mul_f32_e32 v160, v96, v203
	v_mul_f32_e32 v161, v108, v203
	v_fma_f32 v108, v108, v202, -v160
	v_fma_f32 v96, v96, v202, v161
	v_mul_f32_e32 v162, v97, v205
	v_mul_f32_e32 v163, v109, v205
	v_fma_f32 v109, v109, v204, -v162
	v_fma_f32 v97, v97, v204, v163
	v_mul_f32_e32 v160, v98, v207
	v_mul_f32_e32 v161, v110, v207
	v_fma_f32 v110, v110, v206, -v160
	v_fma_f32 v98, v98, v206, v161
	v_mul_f32_e32 v162, v99, v209
	v_mul_f32_e32 v163, v111, v209
	v_fma_f32 v111, v111, v208, -v162
	v_fma_f32 v99, v99, v208, v163
	v_mul_f32_e32 v160, v100, v219
	v_mul_f32_e32 v161, v104, v219
	v_fma_f32 v104, v104, v218, -v160
	v_fma_f32 v100, v100, v218, v161
	v_mul_f32_e32 v162, v101, v221
	v_mul_f32_e32 v163, v105, v221
	v_fma_f32 v105, v105, v220, -v162
	v_fma_f32 v101, v101, v220, v163
	v_mul_f32_e32 v160, v102, v223
	v_mul_f32_e32 v161, v106, v223
	v_fma_f32 v106, v106, v222, -v160
	v_fma_f32 v102, v102, v222, v161
	v_mul_f32_e32 v162, v103, v225
	v_mul_f32_e32 v163, v107, v225
	v_fma_f32 v107, v107, v224, -v162
	v_fma_f32 v103, v103, v224, v163
	v_mov_b32_e32 v158, v131
	v_cvt_pk_bf16_f32 v112, v112, v113
	v_cvt_pk_bf16_f32 v113, v114, v115
	v_cvt_pk_bf16_f32 v116, v116, v117
	v_cvt_pk_bf16_f32 v117, v118, v119
	v_cvt_pk_bf16_f32 v124, v124, v125
	v_cvt_pk_bf16_f32 v125, v126, v127
	v_cvt_pk_bf16_f32 v120, v120, v121
	v_cvt_pk_bf16_f32 v121, v122, v123
	global_store_dwordx2 v158, v[112:113], s[24:25]
	global_store_dwordx2 v158, v[116:117], s[24:25] offset:32
	global_store_dwordx2 v158, v[124:125], s[24:25] offset:64
	global_store_dwordx2 v158, v[120:121], s[24:25] offset:96
	v_add_u32_e32 v158, 49152, v131
	v_cvt_pk_bf16_f32 v108, v108, v109
	v_cvt_pk_bf16_f32 v109, v110, v111
	v_cvt_pk_bf16_f32 v96, v96, v97
	v_cvt_pk_bf16_f32 v97, v98, v99
	v_cvt_pk_bf16_f32 v104, v104, v105
	v_cvt_pk_bf16_f32 v105, v106, v107
	v_cvt_pk_bf16_f32 v100, v100, v101
	v_cvt_pk_bf16_f32 v101, v102, v103
	global_store_dwordx2 v158, v[108:109], s[24:25]
	global_store_dwordx2 v158, v[96:97], s[24:25] offset:32
	global_store_dwordx2 v158, v[104:105], s[24:25] offset:64
	global_store_dwordx2 v158, v[100:101], s[24:25] offset:96
	global_load_dwordx4 v[194:197], v132, s[38:39] offset:128
	global_load_dwordx4 v[198:201], v132, s[38:39] offset:144
	global_load_dwordx4 v[210:213], v133, s[38:39]
	global_load_dwordx4 v[214:217], v133, s[38:39] offset:16
	global_load_dwordx4 v[202:205], v132, s[38:39] offset:128
	global_load_dwordx4 v[206:209], v132, s[38:39] offset:144
	global_load_dwordx4 v[218:221], v133, s[38:39] offset:2048
	global_load_dwordx4 v[222:225], v133, s[38:39] offset:2064
	v_mul_f32_e32 v92, v92, v136
	v_mul_f32_e32 v93, v93, v136
	v_mul_f32_e32 v94, v94, v136
	v_mul_f32_e32 v95, v95, v136
	v_mul_f32_e32 v80, v80, v136
	v_mul_f32_e32 v81, v81, v136
	v_mul_f32_e32 v82, v82, v136
	v_mul_f32_e32 v83, v83, v136
	v_mul_f32_e32 v88, v88, v136
	v_mul_f32_e32 v89, v89, v136
	v_mul_f32_e32 v90, v90, v136
	v_mul_f32_e32 v91, v91, v136
	v_mul_f32_e32 v84, v84, v136
	v_mul_f32_e32 v85, v85, v136
	v_mul_f32_e32 v86, v86, v136
	v_mul_f32_e32 v87, v87, v136
	v_mul_f32_e32 v76, v76, v137
	v_mul_f32_e32 v77, v77, v137
	v_mul_f32_e32 v78, v78, v137
	v_mul_f32_e32 v79, v79, v137
	v_mul_f32_e32 v64, v64, v137
	v_mul_f32_e32 v65, v65, v137
	v_mul_f32_e32 v66, v66, v137
	v_mul_f32_e32 v67, v67, v137
	v_mul_f32_e32 v72, v72, v137
	v_mul_f32_e32 v73, v73, v137
	v_mul_f32_e32 v74, v74, v137
	v_mul_f32_e32 v75, v75, v137
	v_mul_f32_e32 v68, v68, v137
	v_mul_f32_e32 v69, v69, v137
	v_mul_f32_e32 v70, v70, v137
	v_mul_f32_e32 v71, v71, v137
	s_waitcnt vmcnt(16)
	v_mul_f32_e32 v160, v80, v227
	v_mul_f32_e32 v161, v92, v227
	v_fma_f32 v92, v92, v226, -v160
	v_fma_f32 v80, v80, v226, v161
	v_mul_f32_e32 v162, v81, v229
	v_mul_f32_e32 v163, v93, v229
	v_fma_f32 v93, v93, v228, -v162
	v_fma_f32 v81, v81, v228, v163
	v_mul_f32_e32 v160, v82, v231
	v_mul_f32_e32 v161, v94, v231
	v_fma_f32 v94, v94, v230, -v160
	v_fma_f32 v82, v82, v230, v161
	v_mul_f32_e32 v162, v83, v233
	v_mul_f32_e32 v163, v95, v233
	v_fma_f32 v95, v95, v232, -v162
	v_fma_f32 v83, v83, v232, v163
	v_mul_f32_e32 v160, v84, v143
	v_mul_f32_e32 v161, v88, v143
	v_fma_f32 v88, v88, v142, -v160
	v_fma_f32 v84, v84, v142, v161
	v_mul_f32_e32 v162, v85, v145
	v_mul_f32_e32 v163, v89, v145
	v_fma_f32 v89, v89, v144, -v162
	v_fma_f32 v85, v85, v144, v163
	v_mul_f32_e32 v160, v86, v147
	v_mul_f32_e32 v161, v90, v147
	v_fma_f32 v90, v90, v146, -v160
	v_fma_f32 v86, v86, v146, v161
	v_mul_f32_e32 v162, v87, v149
	v_mul_f32_e32 v163, v91, v149
	v_fma_f32 v91, v91, v148, -v162
	v_fma_f32 v87, v87, v148, v163
	v_mul_f32_e32 v160, v64, v235
	v_mul_f32_e32 v161, v76, v235
	v_fma_f32 v76, v76, v234, -v160
	v_fma_f32 v64, v64, v234, v161
	v_mul_f32_e32 v162, v65, v237
	v_mul_f32_e32 v163, v77, v237
	v_fma_f32 v77, v77, v236, -v162
	v_fma_f32 v65, v65, v236, v163
	v_mul_f32_e32 v160, v66, v239
	v_mul_f32_e32 v161, v78, v239
	v_fma_f32 v78, v78, v238, -v160
	v_fma_f32 v66, v66, v238, v161
	v_mul_f32_e32 v162, v67, v241
	v_mul_f32_e32 v163, v79, v241
	v_fma_f32 v79, v79, v240, -v162
	v_fma_f32 v67, v67, v240, v163
	v_mul_f32_e32 v160, v68, v151
	v_mul_f32_e32 v161, v72, v151
	v_fma_f32 v72, v72, v150, -v160
	v_fma_f32 v68, v68, v150, v161
	v_mul_f32_e32 v162, v69, v153
	v_mul_f32_e32 v163, v73, v153
	v_fma_f32 v73, v73, v152, -v162
	v_fma_f32 v69, v69, v152, v163
	v_mul_f32_e32 v160, v70, v155
	v_mul_f32_e32 v161, v74, v155
	v_fma_f32 v74, v74, v154, -v160
	v_fma_f32 v70, v70, v154, v161
	v_mul_f32_e32 v162, v71, v157
	v_mul_f32_e32 v163, v75, v157
	v_fma_f32 v75, v75, v156, -v162
	v_fma_f32 v71, v71, v156, v163
	v_add_u32_e32 v158, 98304, v131
	v_cvt_pk_bf16_f32 v92, v92, v93
	v_cvt_pk_bf16_f32 v93, v94, v95
	v_cvt_pk_bf16_f32 v80, v80, v81
	v_cvt_pk_bf16_f32 v81, v82, v83
	v_cvt_pk_bf16_f32 v88, v88, v89
	v_cvt_pk_bf16_f32 v89, v90, v91
	v_cvt_pk_bf16_f32 v84, v84, v85
	v_cvt_pk_bf16_f32 v85, v86, v87
	global_store_dwordx2 v158, v[92:93], s[24:25]
	global_store_dwordx2 v158, v[80:81], s[24:25] offset:32
	global_store_dwordx2 v158, v[88:89], s[24:25] offset:64
	global_store_dwordx2 v158, v[84:85], s[24:25] offset:96
	v_add_u32_e32 v158, 147456, v131
	v_cvt_pk_bf16_f32 v76, v76, v77
	v_cvt_pk_bf16_f32 v77, v78, v79
	v_cvt_pk_bf16_f32 v64, v64, v65
	v_cvt_pk_bf16_f32 v65, v66, v67
	v_cvt_pk_bf16_f32 v72, v72, v73
	v_cvt_pk_bf16_f32 v73, v74, v75
	v_cvt_pk_bf16_f32 v68, v68, v69
	v_cvt_pk_bf16_f32 v69, v70, v71
	global_store_dwordx2 v158, v[76:77], s[24:25]
	global_store_dwordx2 v158, v[64:65], s[24:25] offset:32
	global_store_dwordx2 v158, v[72:73], s[24:25] offset:64
	global_store_dwordx2 v158, v[68:69], s[24:25] offset:96
	global_load_dwordx4 v[226:229], v132, s[38:39] offset:128
	global_load_dwordx4 v[230:233], v132, s[38:39] offset:144
	v_add_u32_e32 v160, 4096, v133
	global_load_dwordx4 v[142:145], v160, s[38:39]
	global_load_dwordx4 v[146:149], v160, s[38:39] offset:16
	global_load_dwordx4 v[234:237], v132, s[38:39] offset:128
	global_load_dwordx4 v[238:241], v132, s[38:39] offset:144
	v_add_u32_e32 v160, 6144, v133
	global_load_dwordx4 v[150:153], v160, s[38:39]
	global_load_dwordx4 v[154:157], v160, s[38:39] offset:16
	v_mul_f32_e32 v60, v60, v138
	v_mul_f32_e32 v61, v61, v138
	v_mul_f32_e32 v62, v62, v138
	v_mul_f32_e32 v63, v63, v138
	v_mul_f32_e32 v48, v48, v138
	v_mul_f32_e32 v49, v49, v138
	v_mul_f32_e32 v50, v50, v138
	v_mul_f32_e32 v51, v51, v138
	v_mul_f32_e32 v56, v56, v138
	v_mul_f32_e32 v57, v57, v138
	v_mul_f32_e32 v58, v58, v138
	v_mul_f32_e32 v59, v59, v138
	v_mul_f32_e32 v52, v52, v138
	v_mul_f32_e32 v53, v53, v138
	v_mul_f32_e32 v54, v54, v138
	v_mul_f32_e32 v55, v55, v138
	v_mul_f32_e32 v44, v44, v139
	v_mul_f32_e32 v45, v45, v139
	v_mul_f32_e32 v46, v46, v139
	v_mul_f32_e32 v47, v47, v139
	v_mul_f32_e32 v32, v32, v139
	v_mul_f32_e32 v33, v33, v139
	v_mul_f32_e32 v34, v34, v139
	v_mul_f32_e32 v35, v35, v139
	v_mul_f32_e32 v40, v40, v139
	v_mul_f32_e32 v41, v41, v139
	v_mul_f32_e32 v42, v42, v139
	v_mul_f32_e32 v43, v43, v139
	v_mul_f32_e32 v36, v36, v139
	v_mul_f32_e32 v37, v37, v139
	v_mul_f32_e32 v38, v38, v139
	v_mul_f32_e32 v39, v39, v139
	s_waitcnt vmcnt(16)
	v_mul_f32_e32 v160, v48, v195
	v_mul_f32_e32 v161, v60, v195
	v_fma_f32 v60, v60, v194, -v160
	v_fma_f32 v48, v48, v194, v161
	v_mul_f32_e32 v162, v49, v197
	v_mul_f32_e32 v163, v61, v197
	v_fma_f32 v61, v61, v196, -v162
	v_fma_f32 v49, v49, v196, v163
	v_mul_f32_e32 v160, v50, v199
	v_mul_f32_e32 v161, v62, v199
	v_fma_f32 v62, v62, v198, -v160
	v_fma_f32 v50, v50, v198, v161
	v_mul_f32_e32 v162, v51, v201
	v_mul_f32_e32 v163, v63, v201
	v_fma_f32 v63, v63, v200, -v162
	v_fma_f32 v51, v51, v200, v163
	v_mul_f32_e32 v160, v52, v211
	v_mul_f32_e32 v161, v56, v211
	v_fma_f32 v56, v56, v210, -v160
	v_fma_f32 v52, v52, v210, v161
	v_mul_f32_e32 v162, v53, v213
	v_mul_f32_e32 v163, v57, v213
	v_fma_f32 v57, v57, v212, -v162
	v_fma_f32 v53, v53, v212, v163
	v_mul_f32_e32 v160, v54, v215
	v_mul_f32_e32 v161, v58, v215
	v_fma_f32 v58, v58, v214, -v160
	v_fma_f32 v54, v54, v214, v161
	v_mul_f32_e32 v162, v55, v217
	v_mul_f32_e32 v163, v59, v217
	v_fma_f32 v59, v59, v216, -v162
	v_fma_f32 v55, v55, v216, v163
	v_mul_f32_e32 v160, v32, v203
	v_mul_f32_e32 v161, v44, v203
	v_fma_f32 v44, v44, v202, -v160
	v_fma_f32 v32, v32, v202, v161
	v_mul_f32_e32 v162, v33, v205
	v_mul_f32_e32 v163, v45, v205
	v_fma_f32 v45, v45, v204, -v162
	v_fma_f32 v33, v33, v204, v163
	v_mul_f32_e32 v160, v34, v207
	v_mul_f32_e32 v161, v46, v207
	v_fma_f32 v46, v46, v206, -v160
	v_fma_f32 v34, v34, v206, v161
	v_mul_f32_e32 v162, v35, v209
	v_mul_f32_e32 v163, v47, v209
	v_fma_f32 v47, v47, v208, -v162
	v_fma_f32 v35, v35, v208, v163
	v_mul_f32_e32 v160, v36, v219
	v_mul_f32_e32 v161, v40, v219
	v_fma_f32 v40, v40, v218, -v160
	v_fma_f32 v36, v36, v218, v161
	v_mul_f32_e32 v162, v37, v221
	v_mul_f32_e32 v163, v41, v221
	v_fma_f32 v41, v41, v220, -v162
	v_fma_f32 v37, v37, v220, v163
	v_mul_f32_e32 v160, v38, v223
	v_mul_f32_e32 v161, v42, v223
	v_fma_f32 v42, v42, v222, -v160
	v_fma_f32 v38, v38, v222, v161
	v_mul_f32_e32 v162, v39, v225
	v_mul_f32_e32 v163, v43, v225
	v_fma_f32 v43, v43, v224, -v162
	v_fma_f32 v39, v39, v224, v163
	v_add_u32_e32 v158, 196608, v131
	v_cvt_pk_bf16_f32 v60, v60, v61
	v_cvt_pk_bf16_f32 v61, v62, v63
	v_cvt_pk_bf16_f32 v48, v48, v49
	v_cvt_pk_bf16_f32 v49, v50, v51
	v_cvt_pk_bf16_f32 v56, v56, v57
	v_cvt_pk_bf16_f32 v57, v58, v59
	v_cvt_pk_bf16_f32 v52, v52, v53
	v_cvt_pk_bf16_f32 v53, v54, v55
	global_store_dwordx2 v158, v[60:61], s[24:25]
	global_store_dwordx2 v158, v[48:49], s[24:25] offset:32
	global_store_dwordx2 v158, v[56:57], s[24:25] offset:64
	global_store_dwordx2 v158, v[52:53], s[24:25] offset:96
	v_add_u32_e32 v158, 245760, v131
	v_cvt_pk_bf16_f32 v44, v44, v45
	v_cvt_pk_bf16_f32 v45, v46, v47
	v_cvt_pk_bf16_f32 v32, v32, v33
	v_cvt_pk_bf16_f32 v33, v34, v35
	v_cvt_pk_bf16_f32 v40, v40, v41
	v_cvt_pk_bf16_f32 v41, v42, v43
	v_cvt_pk_bf16_f32 v36, v36, v37
	v_cvt_pk_bf16_f32 v37, v38, v39
	global_store_dwordx2 v158, v[44:45], s[24:25]
	global_store_dwordx2 v158, v[32:33], s[24:25] offset:32
	global_store_dwordx2 v158, v[40:41], s[24:25] offset:64
	global_store_dwordx2 v158, v[36:37], s[24:25] offset:96
	v_mul_f32_e32 v28, v28, v140
	v_mul_f32_e32 v29, v29, v140
	v_mul_f32_e32 v30, v30, v140
	v_mul_f32_e32 v31, v31, v140
	v_mul_f32_e32 v16, v16, v140
	v_mul_f32_e32 v17, v17, v140
	v_mul_f32_e32 v18, v18, v140
	v_mul_f32_e32 v19, v19, v140
	v_mul_f32_e32 v24, v24, v140
	v_mul_f32_e32 v25, v25, v140
	v_mul_f32_e32 v26, v26, v140
	v_mul_f32_e32 v27, v27, v140
	v_mul_f32_e32 v20, v20, v140
	v_mul_f32_e32 v21, v21, v140
	v_mul_f32_e32 v22, v22, v140
	v_mul_f32_e32 v23, v23, v140
	v_mul_f32_e32 v12, v12, v141
	v_mul_f32_e32 v13, v13, v141
	v_mul_f32_e32 v14, v14, v141
	v_mul_f32_e32 v15, v15, v141
	v_mul_f32_e32 v0, v0, v141
	v_mul_f32_e32 v1, v1, v141
	v_mul_f32_e32 v2, v2, v141
	v_mul_f32_e32 v3, v3, v141
	v_mul_f32_e32 v8, v8, v141
	v_mul_f32_e32 v9, v9, v141
	v_mul_f32_e32 v10, v10, v141
	v_mul_f32_e32 v11, v11, v141
	v_mul_f32_e32 v4, v4, v141
	v_mul_f32_e32 v5, v5, v141
	v_mul_f32_e32 v6, v6, v141
	v_mul_f32_e32 v7, v7, v141
	s_waitcnt vmcnt(8)
	v_mul_f32_e32 v160, v16, v227
	v_mul_f32_e32 v161, v28, v227
	v_fma_f32 v28, v28, v226, -v160
	v_fma_f32 v16, v16, v226, v161
	v_mul_f32_e32 v162, v17, v229
	v_mul_f32_e32 v163, v29, v229
	v_fma_f32 v29, v29, v228, -v162
	v_fma_f32 v17, v17, v228, v163
	v_mul_f32_e32 v160, v18, v231
	v_mul_f32_e32 v161, v30, v231
	v_fma_f32 v30, v30, v230, -v160
	v_fma_f32 v18, v18, v230, v161
	v_mul_f32_e32 v162, v19, v233
	v_mul_f32_e32 v163, v31, v233
	v_fma_f32 v31, v31, v232, -v162
	v_fma_f32 v19, v19, v232, v163
	v_mul_f32_e32 v160, v20, v143
	v_mul_f32_e32 v161, v24, v143
	v_fma_f32 v24, v24, v142, -v160
	v_fma_f32 v20, v20, v142, v161
	v_mul_f32_e32 v162, v21, v145
	v_mul_f32_e32 v163, v25, v145
	v_fma_f32 v25, v25, v144, -v162
	v_fma_f32 v21, v21, v144, v163
	v_mul_f32_e32 v160, v22, v147
	v_mul_f32_e32 v161, v26, v147
	v_fma_f32 v26, v26, v146, -v160
	v_fma_f32 v22, v22, v146, v161
	v_mul_f32_e32 v162, v23, v149
	v_mul_f32_e32 v163, v27, v149
	v_fma_f32 v27, v27, v148, -v162
	v_fma_f32 v23, v23, v148, v163
	v_mul_f32_e32 v160, v0, v235
	v_mul_f32_e32 v161, v12, v235
	v_fma_f32 v12, v12, v234, -v160
	v_fma_f32 v0, v0, v234, v161
	v_mul_f32_e32 v162, v1, v237
	v_mul_f32_e32 v163, v13, v237
	v_fma_f32 v13, v13, v236, -v162
	v_fma_f32 v1, v1, v236, v163
	v_mul_f32_e32 v160, v2, v239
	v_mul_f32_e32 v161, v14, v239
	v_fma_f32 v14, v14, v238, -v160
	v_fma_f32 v2, v2, v238, v161
	v_mul_f32_e32 v162, v3, v241
	v_mul_f32_e32 v163, v15, v241
	v_fma_f32 v15, v15, v240, -v162
	v_fma_f32 v3, v3, v240, v163
	v_mul_f32_e32 v160, v4, v151
	v_mul_f32_e32 v161, v8, v151
	v_fma_f32 v8, v8, v150, -v160
	v_fma_f32 v4, v4, v150, v161
	v_mul_f32_e32 v162, v5, v153
	v_mul_f32_e32 v163, v9, v153
	v_fma_f32 v9, v9, v152, -v162
	v_fma_f32 v5, v5, v152, v163
	v_mul_f32_e32 v160, v6, v155
	v_mul_f32_e32 v161, v10, v155
	v_fma_f32 v10, v10, v154, -v160
	v_fma_f32 v6, v6, v154, v161
	v_mul_f32_e32 v162, v7, v157
	v_mul_f32_e32 v163, v11, v157
	v_fma_f32 v11, v11, v156, -v162
	v_fma_f32 v7, v7, v156, v163
	v_add_u32_e32 v158, 294912, v131
	v_cvt_pk_bf16_f32 v28, v28, v29
	v_cvt_pk_bf16_f32 v29, v30, v31
	v_cvt_pk_bf16_f32 v16, v16, v17
	v_cvt_pk_bf16_f32 v17, v18, v19
	v_cvt_pk_bf16_f32 v24, v24, v25
	v_cvt_pk_bf16_f32 v25, v26, v27
	v_cvt_pk_bf16_f32 v20, v20, v21
	v_cvt_pk_bf16_f32 v21, v22, v23
	global_store_dwordx2 v158, v[28:29], s[24:25]
	global_store_dwordx2 v158, v[16:17], s[24:25] offset:32
	global_store_dwordx2 v158, v[24:25], s[24:25] offset:64
	global_store_dwordx2 v158, v[20:21], s[24:25] offset:96
	v_add_u32_e32 v158, 344064, v131
	v_cvt_pk_bf16_f32 v12, v12, v13
	v_cvt_pk_bf16_f32 v13, v14, v15
	v_cvt_pk_bf16_f32 v0, v0, v1
	v_cvt_pk_bf16_f32 v1, v2, v3
	v_cvt_pk_bf16_f32 v8, v8, v9
	v_cvt_pk_bf16_f32 v9, v10, v11
	v_cvt_pk_bf16_f32 v4, v4, v5
	v_cvt_pk_bf16_f32 v5, v6, v7
	global_store_dwordx2 v158, v[12:13], s[24:25]
	global_store_dwordx2 v158, v[0:1], s[24:25] offset:32
	global_store_dwordx2 v158, v[8:9], s[24:25] offset:64
	global_store_dwordx2 v158, v[4:5], s[24:25] offset:96
	s_branch .Lq_epi_done

.LBB0_906:
	s_and_b64 vcc, exec, s[0:1]
	s_cbranch_vccz .LBB0_803
	v_and_b32_e32 v2, 64, v192
	v_add_u32_e32 v2, 64, v2
	v_xor_b32_e32 v3, 32, v192
	v_cmp_lt_i32_e32 vcc, v3, v2
	v_mov_b32_e32 v128, v167
	s_ashr_i32 s8, s20, 3
	v_cndmask_b32_e32 v3, v192, v3, vcc
	v_lshlrev_b32_e32 v33, 2, v3
	v_xor_b32_e32 v3, 16, v192
	v_cmp_lt_i32_e32 vcc, v3, v2
	s_lshl_b32 s9, s8, 8
	v_and_b32_e32 v0, 63, v128
	v_cndmask_b32_e32 v3, v192, v3, vcc
	v_lshlrev_b32_e32 v34, 2, v3
	v_xor_b32_e32 v3, 8, v192
	v_cmp_lt_i32_e32 vcc, v3, v2
	v_ashrrev_i32_e32 v1, 6, v128
	v_readlane_b32 s1, v254, 47
	v_cndmask_b32_e32 v3, v192, v3, vcc
	v_lshlrev_b32_e32 v35, 2, v3
	v_xor_b32_e32 v3, 4, v192
	v_cmp_lt_i32_e32 vcc, v3, v2
	v_lshlrev_b32_e32 v164, 3, v0
	v_lshl_add_u32 v32, v1, 5, s9
	v_cndmask_b32_e32 v3, v192, v3, vcc
	v_lshlrev_b32_e32 v36, 2, v3
	v_xor_b32_e32 v3, 2, v192
	v_cmp_lt_i32_e32 vcc, v3, v2
	s_mov_b32 s0, 0
	v_cmp_eq_u32_e64 s[10:11], 0, v0
	v_cndmask_b32_e32 v3, v192, v3, vcc
	v_lshlrev_b32_e32 v37, 2, v3
	v_xor_b32_e32 v3, 1, v192
	v_cmp_lt_i32_e32 vcc, v3, v2
	v_lshl_add_u32 v39, v1, 7, s1
	v_lshl_add_u64 v[0:1], s[22:23], 0, v[164:165]
	v_cndmask_b32_e32 v2, v192, v3, vcc
	v_lshlrev_b32_e32 v38, 2, v2
	s_mov_b64 s[2:3], -1
	s_cmp_eq_u32 s99, 1
	s_cbranch_scc1 .Lrskv_skip
	v_readfirstlane_b32 s0, v167
	v_and_b32_e32 v116, 63, v167
	v_and_b32_e32 v118, 15, v167
	s_lshr_b32 s0, s0, 6
	s_lshl_b32 s1, s0, 5
	s_add_u32 s2, s9, s1
	s_mul_i32 s2, s2, 0x1700
	s_add_u32 s2, s2, 0x400
	s_add_u32 s24, s22, s2
	s_addc_u32 s25, s23, 0
	v_lshlrev_b32_e32 v116, 3, v116
	v_and_b32_e32 v117, 48, v167
	s_lshl_b32 s1, s0, 7
	v_add_u32_e32 v117, s1, v117
	v_add_u32_e32 v117, 0x20000, v117
	global_load_dwordx2 v[16:17], v116, s[24:25]
	s_add_u32 s24, s24, 0x1700
	s_addc_u32 s25, s25, 0
	global_load_dwordx2 v[18:19], v116, s[24:25]
	s_add_u32 s24, s24, 0x1700
	s_addc_u32 s25, s25, 0
	global_load_dwordx2 v[20:21], v116, s[24:25]
	s_add_u32 s24, s24, 0x1700
	s_addc_u32 s25, s25, 0
	global_load_dwordx2 v[22:23], v116, s[24:25]
	s_add_u32 s24, s24, 0x1700
	s_addc_u32 s25, s25, 0
	global_load_dwordx2 v[24:25], v116, s[24:25]
	s_add_u32 s24, s24, 0x1700
	s_addc_u32 s25, s25, 0
	global_load_dwordx2 v[26:27], v116, s[24:25]
	s_add_u32 s24, s24, 0x1700
	s_addc_u32 s25, s25, 0
	global_load_dwordx2 v[28:29], v116, s[24:25]
	s_add_u32 s24, s24, 0x1700
	s_addc_u32 s25, s25, 0
	global_load_dwordx2 v[30:31], v116, s[24:25]
	s_add_u32 s24, s24, 0x1700
	s_addc_u32 s25, s25, 0
	global_load_dwordx2 v[32:33], v116, s[24:25]
	s_add_u32 s24, s24, 0x1700
	s_addc_u32 s25, s25, 0
	global_load_dwordx2 v[34:35], v116, s[24:25]
	s_add_u32 s24, s24, 0x1700
	s_addc_u32 s25, s25, 0
	global_load_dwordx2 v[36:37], v116, s[24:25]
	s_add_u32 s24, s24, 0x1700
	s_addc_u32 s25, s25, 0
	global_load_dwordx2 v[38:39], v116, s[24:25]
	s_add_u32 s24, s24, 0x1700
	s_addc_u32 s25, s25, 0
	global_load_dwordx2 v[40:41], v116, s[24:25]
	s_add_u32 s24, s24, 0x1700
	s_addc_u32 s25, s25, 0
	global_load_dwordx2 v[42:43], v116, s[24:25]
	s_add_u32 s24, s24, 0x1700
	s_addc_u32 s25, s25, 0
	global_load_dwordx2 v[44:45], v116, s[24:25]
	s_add_u32 s24, s24, 0x1700
	s_addc_u32 s25, s25, 0
	global_load_dwordx2 v[46:47], v116, s[24:25]
	s_add_u32 s24, s24, 0x1700
	s_addc_u32 s25, s25, 0
	s_waitcnt vmcnt(15)
	v_lshlrev_b32_e32 v112, 16, v16
	v_and_b32_e32 v16, 0xffff0000, v16
	v_mul_f32_e32 v16, v16, v16
	v_lshlrev_b32_e32 v113, 16, v17
	v_fmac_f32_e32 v16, v112, v112
	v_and_b32_e32 v17, 0xffff0000, v17
	v_fmac_f32_e32 v16, v113, v113
	v_fmac_f32_e32 v16, v17, v17
	s_waitcnt vmcnt(14)
	v_lshlrev_b32_e32 v112, 16, v18
	v_and_b32_e32 v18, 0xffff0000, v18
	v_mul_f32_e32 v18, v18, v18
	v_lshlrev_b32_e32 v113, 16, v19
	v_fmac_f32_e32 v18, v112, v112
	v_and_b32_e32 v19, 0xffff0000, v19
	v_fmac_f32_e32 v18, v113, v113
	v_fmac_f32_e32 v18, v19, v19
	s_waitcnt vmcnt(13)
	v_lshlrev_b32_e32 v112, 16, v20
	v_and_b32_e32 v20, 0xffff0000, v20
	v_mul_f32_e32 v20, v20, v20
	v_lshlrev_b32_e32 v113, 16, v21
	v_fmac_f32_e32 v20, v112, v112
	v_and_b32_e32 v21, 0xffff0000, v21
	v_fmac_f32_e32 v20, v113, v113
	v_fmac_f32_e32 v20, v21, v21
	s_waitcnt vmcnt(12)
	v_lshlrev_b32_e32 v112, 16, v22
	v_and_b32_e32 v22, 0xffff0000, v22
	v_mul_f32_e32 v22, v22, v22
	v_lshlrev_b32_e32 v113, 16, v23
	v_fmac_f32_e32 v22, v112, v112
	v_and_b32_e32 v23, 0xffff0000, v23
	v_fmac_f32_e32 v22, v113, v113
	v_fmac_f32_e32 v22, v23, v23
	s_waitcnt vmcnt(11)
	v_lshlrev_b32_e32 v112, 16, v24
	v_and_b32_e32 v24, 0xffff0000, v24
	v_mul_f32_e32 v24, v24, v24
	v_lshlrev_b32_e32 v113, 16, v25
	v_fmac_f32_e32 v24, v112, v112
	v_and_b32_e32 v25, 0xffff0000, v25
	v_fmac_f32_e32 v24, v113, v113
	v_fmac_f32_e32 v24, v25, v25
	s_waitcnt vmcnt(10)
	v_lshlrev_b32_e32 v112, 16, v26
	v_and_b32_e32 v26, 0xffff0000, v26
	v_mul_f32_e32 v26, v26, v26
	v_lshlrev_b32_e32 v113, 16, v27
	v_fmac_f32_e32 v26, v112, v112
	v_and_b32_e32 v27, 0xffff0000, v27
	v_fmac_f32_e32 v26, v113, v113
	v_fmac_f32_e32 v26, v27, v27
	s_waitcnt vmcnt(9)
	v_lshlrev_b32_e32 v112, 16, v28
	v_and_b32_e32 v28, 0xffff0000, v28
	v_mul_f32_e32 v28, v28, v28
	v_lshlrev_b32_e32 v113, 16, v29
	v_fmac_f32_e32 v28, v112, v112
	v_and_b32_e32 v29, 0xffff0000, v29
	v_fmac_f32_e32 v28, v113, v113
	v_fmac_f32_e32 v28, v29, v29
	s_waitcnt vmcnt(8)
	v_lshlrev_b32_e32 v112, 16, v30
	v_and_b32_e32 v30, 0xffff0000, v30
	v_mul_f32_e32 v30, v30, v30
	v_lshlrev_b32_e32 v113, 16, v31
	v_fmac_f32_e32 v30, v112, v112
	v_and_b32_e32 v31, 0xffff0000, v31
	v_fmac_f32_e32 v30, v113, v113
	v_fmac_f32_e32 v30, v31, v31
	s_waitcnt vmcnt(7)
	v_lshlrev_b32_e32 v112, 16, v32
	v_and_b32_e32 v32, 0xffff0000, v32
	v_mul_f32_e32 v32, v32, v32
	v_lshlrev_b32_e32 v113, 16, v33
	v_fmac_f32_e32 v32, v112, v112
	v_and_b32_e32 v33, 0xffff0000, v33
	v_fmac_f32_e32 v32, v113, v113
	v_fmac_f32_e32 v32, v33, v33
	s_waitcnt vmcnt(6)
	v_lshlrev_b32_e32 v112, 16, v34
	v_and_b32_e32 v34, 0xffff0000, v34
	v_mul_f32_e32 v34, v34, v34
	v_lshlrev_b32_e32 v113, 16, v35
	v_fmac_f32_e32 v34, v112, v112
	v_and_b32_e32 v35, 0xffff0000, v35
	v_fmac_f32_e32 v34, v113, v113
	v_fmac_f32_e32 v34, v35, v35
	s_waitcnt vmcnt(5)
	v_lshlrev_b32_e32 v112, 16, v36
	v_and_b32_e32 v36, 0xffff0000, v36
	v_mul_f32_e32 v36, v36, v36
	v_lshlrev_b32_e32 v113, 16, v37
	v_fmac_f32_e32 v36, v112, v112
	v_and_b32_e32 v37, 0xffff0000, v37
	v_fmac_f32_e32 v36, v113, v113
	v_fmac_f32_e32 v36, v37, v37
	s_waitcnt vmcnt(4)
	v_lshlrev_b32_e32 v112, 16, v38
	v_and_b32_e32 v38, 0xffff0000, v38
	v_mul_f32_e32 v38, v38, v38
	v_lshlrev_b32_e32 v113, 16, v39
	v_fmac_f32_e32 v38, v112, v112
	v_and_b32_e32 v39, 0xffff0000, v39
	v_fmac_f32_e32 v38, v113, v113
	v_fmac_f32_e32 v38, v39, v39
	s_waitcnt vmcnt(3)
	v_lshlrev_b32_e32 v112, 16, v40
	v_and_b32_e32 v40, 0xffff0000, v40
	v_mul_f32_e32 v40, v40, v40
	v_lshlrev_b32_e32 v113, 16, v41
	v_fmac_f32_e32 v40, v112, v112
	v_and_b32_e32 v41, 0xffff0000, v41
	v_fmac_f32_e32 v40, v113, v113
	v_fmac_f32_e32 v40, v41, v41
	s_waitcnt vmcnt(2)
	v_lshlrev_b32_e32 v112, 16, v42
	v_and_b32_e32 v42, 0xffff0000, v42
	v_mul_f32_e32 v42, v42, v42
	v_lshlrev_b32_e32 v113, 16, v43
	v_fmac_f32_e32 v42, v112, v112
	v_and_b32_e32 v43, 0xffff0000, v43
	v_fmac_f32_e32 v42, v113, v113
	v_fmac_f32_e32 v42, v43, v43
	s_waitcnt vmcnt(1)
	v_lshlrev_b32_e32 v112, 16, v44
	v_and_b32_e32 v44, 0xffff0000, v44
	v_mul_f32_e32 v44, v44, v44
	v_lshlrev_b32_e32 v113, 16, v45
	v_fmac_f32_e32 v44, v112, v112
	v_and_b32_e32 v45, 0xffff0000, v45
	v_fmac_f32_e32 v44, v113, v113
	v_fmac_f32_e32 v44, v45, v45
	s_waitcnt vmcnt(0)
	v_lshlrev_b32_e32 v112, 16, v46
	v_and_b32_e32 v46, 0xffff0000, v46
	v_mul_f32_e32 v46, v46, v46
	v_lshlrev_b32_e32 v113, 16, v47
	v_fmac_f32_e32 v46, v112, v112
	v_and_b32_e32 v47, 0xffff0000, v47
	v_fmac_f32_e32 v46, v113, v113
	v_fmac_f32_e32 v46, v47, v47
	s_nop 1
	v_permlane32_swap_b32_e32 v16, v32
	v_permlane32_swap_b32_e32 v18, v34
	v_permlane32_swap_b32_e32 v20, v36
	v_permlane32_swap_b32_e32 v22, v38
	v_permlane32_swap_b32_e32 v24, v40
	v_permlane32_swap_b32_e32 v26, v42
	v_permlane32_swap_b32_e32 v28, v44
	v_permlane32_swap_b32_e32 v30, v46
	s_nop 0
	v_add_f32_e32 v16, v16, v32
	v_add_f32_e32 v18, v18, v34
	v_add_f32_e32 v20, v20, v36
	v_add_f32_e32 v22, v22, v38
	v_add_f32_e32 v24, v24, v40
	v_add_f32_e32 v26, v26, v42
	v_add_f32_e32 v28, v28, v44
	v_add_f32_e32 v30, v30, v46
	s_nop 1
	v_permlane16_swap_b32_e32 v16, v24
	v_permlane16_swap_b32_e32 v18, v26
	v_permlane16_swap_b32_e32 v20, v28
	v_permlane16_swap_b32_e32 v22, v30
	s_nop 0
	v_add_f32_e32 v16, v16, v24
	v_add_f32_e32 v18, v18, v26
	v_add_f32_e32 v20, v20, v28
	v_add_f32_e32 v22, v22, v30
	s_nop 1
	v_add_f32_dpp v16, v16, v16 row_ror:8 row_mask:0xf bank_mask:0xf
	v_add_f32_dpp v18, v18, v18 row_ror:8 row_mask:0xf bank_mask:0xf
	v_add_f32_dpp v20, v20, v20 row_ror:8 row_mask:0xf bank_mask:0xf
	v_add_f32_dpp v22, v22, v22 row_ror:8 row_mask:0xf bank_mask:0xf
	s_nop 1
	v_add_f32_dpp v16, v16, v16 row_ror:4 row_mask:0xf bank_mask:0xf
	v_add_f32_dpp v18, v18, v18 row_ror:4 row_mask:0xf bank_mask:0xf
	v_add_f32_dpp v20, v20, v20 row_ror:4 row_mask:0xf bank_mask:0xf
	v_add_f32_dpp v22, v22, v22 row_ror:4 row_mask:0xf bank_mask:0xf
	s_nop 1
	v_add_f32_dpp v16, v16, v16 row_ror:2 row_mask:0xf bank_mask:0xf
	v_add_f32_dpp v18, v18, v18 row_ror:2 row_mask:0xf bank_mask:0xf
	v_add_f32_dpp v20, v20, v20 row_ror:2 row_mask:0xf bank_mask:0xf
	v_add_f32_dpp v22, v22, v22 row_ror:2 row_mask:0xf bank_mask:0xf
	s_nop 1
	v_add_f32_dpp v16, v16, v16 row_ror:1 row_mask:0xf bank_mask:0xf
	v_add_f32_dpp v18, v18, v18 row_ror:1 row_mask:0xf bank_mask:0xf
	v_add_f32_dpp v20, v20, v20 row_ror:1 row_mask:0xf bank_mask:0xf
	v_add_f32_dpp v22, v22, v22 row_ror:1 row_mask:0xf bank_mask:0xf
	v_fmamk_f32 v16, v16, 0x3b800000, v166
	v_fmamk_f32 v18, v18, 0x3b800000, v166
	v_fmamk_f32 v20, v20, 0x3b800000, v166
	v_fmamk_f32 v22, v22, 0x3b800000, v166
	v_mul_f32_e32 v112, 0x4b800000, v16
	v_cmp_gt_f32_e32 vcc, s58, v16
	s_nop 1
	v_cndmask_b32_e32 v16, v16, v112, vcc
	v_rsq_f32_e32 v16, v16
	s_nop 0
	v_mul_f32_e32 v112, 0x45800000, v16
	v_cndmask_b32_e32 v16, v16, v112, vcc
	v_mul_f32_e32 v112, 0x4b800000, v18
	v_cmp_gt_f32_e32 vcc, s58, v18
	s_nop 1
	v_cndmask_b32_e32 v18, v18, v112, vcc
	v_rsq_f32_e32 v18, v18
	s_nop 0
	v_mul_f32_e32 v112, 0x45800000, v18
	v_cndmask_b32_e32 v18, v18, v112, vcc
	v_mul_f32_e32 v112, 0x4b800000, v20
	v_cmp_gt_f32_e32 vcc, s58, v20
	s_nop 1
	v_cndmask_b32_e32 v20, v20, v112, vcc
	v_rsq_f32_e32 v20, v20
	s_nop 0
	v_mul_f32_e32 v112, 0x45800000, v20
	v_cndmask_b32_e32 v20, v20, v112, vcc
	v_mul_f32_e32 v112, 0x4b800000, v22
	v_cmp_gt_f32_e32 vcc, s58, v22
	s_nop 1
	v_cndmask_b32_e32 v22, v22, v112, vcc
	v_rsq_f32_e32 v22, v22
	s_nop 0
	v_mul_f32_e32 v112, 0x45800000, v22
	v_cndmask_b32_e32 v22, v22, v112, vcc
	v_mov_b32_e32 v112, v16
	v_mov_b32_e32 v113, v18
	v_mov_b32_e32 v114, v20
	v_mov_b32_e32 v115, v22
	v_cmp_eq_u32_e32 vcc, 0, v118
	s_and_saveexec_b64 s[0:1], vcc
	ds_write_b128 v117, v[112:115]
	s_or_b64 exec, exec, s[0:1]
	global_load_dwordx2 v[16:17], v116, s[24:25]
	s_add_u32 s24, s24, 0x1700
	s_addc_u32 s25, s25, 0
	global_load_dwordx2 v[18:19], v116, s[24:25]
	s_add_u32 s24, s24, 0x1700
	s_addc_u32 s25, s25, 0
	global_load_dwordx2 v[20:21], v116, s[24:25]
	s_add_u32 s24, s24, 0x1700
	s_addc_u32 s25, s25, 0
	global_load_dwordx2 v[22:23], v116, s[24:25]
	s_add_u32 s24, s24, 0x1700
	s_addc_u32 s25, s25, 0
	global_load_dwordx2 v[24:25], v116, s[24:25]
	s_add_u32 s24, s24, 0x1700
	s_addc_u32 s25, s25, 0
	global_load_dwordx2 v[26:27], v116, s[24:25]
	s_add_u32 s24, s24, 0x1700
	s_addc_u32 s25, s25, 0
	global_load_dwordx2 v[28:29], v116, s[24:25]
	s_add_u32 s24, s24, 0x1700
	s_addc_u32 s25, s25, 0
	global_load_dwordx2 v[30:31], v116, s[24:25]
	s_add_u32 s24, s24, 0x1700
	s_addc_u32 s25, s25, 0
	global_load_dwordx2 v[32:33], v116, s[24:25]
	s_add_u32 s24, s24, 0x1700
	s_addc_u32 s25, s25, 0
	global_load_dwordx2 v[34:35], v116, s[24:25]
	s_add_u32 s24, s24, 0x1700
	s_addc_u32 s25, s25, 0
	global_load_dwordx2 v[36:37], v116, s[24:25]
	s_add_u32 s24, s24, 0x1700
	s_addc_u32 s25, s25, 0
	global_load_dwordx2 v[38:39], v116, s[24:25]
	s_add_u32 s24, s24, 0x1700
	s_addc_u32 s25, s25, 0
	global_load_dwordx2 v[40:41], v116, s[24:25]
	s_add_u32 s24, s24, 0x1700
	s_addc_u32 s25, s25, 0
	global_load_dwordx2 v[42:43], v116, s[24:25]
	s_add_u32 s24, s24, 0x1700
	s_addc_u32 s25, s25, 0
	global_load_dwordx2 v[44:45], v116, s[24:25]
	s_add_u32 s24, s24, 0x1700
	s_addc_u32 s25, s25, 0
	global_load_dwordx2 v[46:47], v116, s[24:25]
	s_add_u32 s24, s24, 0x1700
	s_addc_u32 s25, s25, 0
	s_waitcnt vmcnt(15)
	v_lshlrev_b32_e32 v112, 16, v16
	v_and_b32_e32 v16, 0xffff0000, v16
	v_mul_f32_e32 v16, v16, v16
	v_lshlrev_b32_e32 v113, 16, v17
	v_fmac_f32_e32 v16, v112, v112
	v_and_b32_e32 v17, 0xffff0000, v17
	v_fmac_f32_e32 v16, v113, v113
	v_fmac_f32_e32 v16, v17, v17
	s_waitcnt vmcnt(14)
	v_lshlrev_b32_e32 v112, 16, v18
	v_and_b32_e32 v18, 0xffff0000, v18
	v_mul_f32_e32 v18, v18, v18
	v_lshlrev_b32_e32 v113, 16, v19
	v_fmac_f32_e32 v18, v112, v112
	v_and_b32_e32 v19, 0xffff0000, v19
	v_fmac_f32_e32 v18, v113, v113
	v_fmac_f32_e32 v18, v19, v19
	s_waitcnt vmcnt(13)
	v_lshlrev_b32_e32 v112, 16, v20
	v_and_b32_e32 v20, 0xffff0000, v20
	v_mul_f32_e32 v20, v20, v20
	v_lshlrev_b32_e32 v113, 16, v21
	v_fmac_f32_e32 v20, v112, v112
	v_and_b32_e32 v21, 0xffff0000, v21
	v_fmac_f32_e32 v20, v113, v113
	v_fmac_f32_e32 v20, v21, v21
	s_waitcnt vmcnt(12)
	v_lshlrev_b32_e32 v112, 16, v22
	v_and_b32_e32 v22, 0xffff0000, v22
	v_mul_f32_e32 v22, v22, v22
	v_lshlrev_b32_e32 v113, 16, v23
	v_fmac_f32_e32 v22, v112, v112
	v_and_b32_e32 v23, 0xffff0000, v23
	v_fmac_f32_e32 v22, v113, v113
	v_fmac_f32_e32 v22, v23, v23
	s_waitcnt vmcnt(11)
	v_lshlrev_b32_e32 v112, 16, v24
	v_and_b32_e32 v24, 0xffff0000, v24
	v_mul_f32_e32 v24, v24, v24
	v_lshlrev_b32_e32 v113, 16, v25
	v_fmac_f32_e32 v24, v112, v112
	v_and_b32_e32 v25, 0xffff0000, v25
	v_fmac_f32_e32 v24, v113, v113
	v_fmac_f32_e32 v24, v25, v25
	s_waitcnt vmcnt(10)
	v_lshlrev_b32_e32 v112, 16, v26
	v_and_b32_e32 v26, 0xffff0000, v26
	v_mul_f32_e32 v26, v26, v26
	v_lshlrev_b32_e32 v113, 16, v27
	v_fmac_f32_e32 v26, v112, v112
	v_and_b32_e32 v27, 0xffff0000, v27
	v_fmac_f32_e32 v26, v113, v113
	v_fmac_f32_e32 v26, v27, v27
	s_waitcnt vmcnt(9)
	v_lshlrev_b32_e32 v112, 16, v28
	v_and_b32_e32 v28, 0xffff0000, v28
	v_mul_f32_e32 v28, v28, v28
	v_lshlrev_b32_e32 v113, 16, v29
	v_fmac_f32_e32 v28, v112, v112
	v_and_b32_e32 v29, 0xffff0000, v29
	v_fmac_f32_e32 v28, v113, v113
	v_fmac_f32_e32 v28, v29, v29
	s_waitcnt vmcnt(8)
	v_lshlrev_b32_e32 v112, 16, v30
	v_and_b32_e32 v30, 0xffff0000, v30
	v_mul_f32_e32 v30, v30, v30
	v_lshlrev_b32_e32 v113, 16, v31
	v_fmac_f32_e32 v30, v112, v112
	v_and_b32_e32 v31, 0xffff0000, v31
	v_fmac_f32_e32 v30, v113, v113
	v_fmac_f32_e32 v30, v31, v31
	s_waitcnt vmcnt(7)
	v_lshlrev_b32_e32 v112, 16, v32
	v_and_b32_e32 v32, 0xffff0000, v32
	v_mul_f32_e32 v32, v32, v32
	v_lshlrev_b32_e32 v113, 16, v33
	v_fmac_f32_e32 v32, v112, v112
	v_and_b32_e32 v33, 0xffff0000, v33
	v_fmac_f32_e32 v32, v113, v113
	v_fmac_f32_e32 v32, v33, v33
	s_waitcnt vmcnt(6)
	v_lshlrev_b32_e32 v112, 16, v34
	v_and_b32_e32 v34, 0xffff0000, v34
	v_mul_f32_e32 v34, v34, v34
	v_lshlrev_b32_e32 v113, 16, v35
	v_fmac_f32_e32 v34, v112, v112
	v_and_b32_e32 v35, 0xffff0000, v35
	v_fmac_f32_e32 v34, v113, v113
	v_fmac_f32_e32 v34, v35, v35
	s_waitcnt vmcnt(5)
	v_lshlrev_b32_e32 v112, 16, v36
	v_and_b32_e32 v36, 0xffff0000, v36
	v_mul_f32_e32 v36, v36, v36
	v_lshlrev_b32_e32 v113, 16, v37
	v_fmac_f32_e32 v36, v112, v112
	v_and_b32_e32 v37, 0xffff0000, v37
	v_fmac_f32_e32 v36, v113, v113
	v_fmac_f32_e32 v36, v37, v37
	s_waitcnt vmcnt(4)
	v_lshlrev_b32_e32 v112, 16, v38
	v_and_b32_e32 v38, 0xffff0000, v38
	v_mul_f32_e32 v38, v38, v38
	v_lshlrev_b32_e32 v113, 16, v39
	v_fmac_f32_e32 v38, v112, v112
	v_and_b32_e32 v39, 0xffff0000, v39
	v_fmac_f32_e32 v38, v113, v113
	v_fmac_f32_e32 v38, v39, v39
	s_waitcnt vmcnt(3)
	v_lshlrev_b32_e32 v112, 16, v40
	v_and_b32_e32 v40, 0xffff0000, v40
	v_mul_f32_e32 v40, v40, v40
	v_lshlrev_b32_e32 v113, 16, v41
	v_fmac_f32_e32 v40, v112, v112
	v_and_b32_e32 v41, 0xffff0000, v41
	v_fmac_f32_e32 v40, v113, v113
	v_fmac_f32_e32 v40, v41, v41
	s_waitcnt vmcnt(2)
	v_lshlrev_b32_e32 v112, 16, v42
	v_and_b32_e32 v42, 0xffff0000, v42
	v_mul_f32_e32 v42, v42, v42
	v_lshlrev_b32_e32 v113, 16, v43
	v_fmac_f32_e32 v42, v112, v112
	v_and_b32_e32 v43, 0xffff0000, v43
	v_fmac_f32_e32 v42, v113, v113
	v_fmac_f32_e32 v42, v43, v43
	s_waitcnt vmcnt(1)
	v_lshlrev_b32_e32 v112, 16, v44
	v_and_b32_e32 v44, 0xffff0000, v44
	v_mul_f32_e32 v44, v44, v44
	v_lshlrev_b32_e32 v113, 16, v45
	v_fmac_f32_e32 v44, v112, v112
	v_and_b32_e32 v45, 0xffff0000, v45
	v_fmac_f32_e32 v44, v113, v113
	v_fmac_f32_e32 v44, v45, v45
	s_waitcnt vmcnt(0)
	v_lshlrev_b32_e32 v112, 16, v46
	v_and_b32_e32 v46, 0xffff0000, v46
	v_mul_f32_e32 v46, v46, v46
	v_lshlrev_b32_e32 v113, 16, v47
	v_fmac_f32_e32 v46, v112, v112
	v_and_b32_e32 v47, 0xffff0000, v47
	v_fmac_f32_e32 v46, v113, v113
	v_fmac_f32_e32 v46, v47, v47
	s_nop 1
	v_permlane32_swap_b32_e32 v16, v32
	v_permlane32_swap_b32_e32 v18, v34
	v_permlane32_swap_b32_e32 v20, v36
	v_permlane32_swap_b32_e32 v22, v38
	v_permlane32_swap_b32_e32 v24, v40
	v_permlane32_swap_b32_e32 v26, v42
	v_permlane32_swap_b32_e32 v28, v44
	v_permlane32_swap_b32_e32 v30, v46
	s_nop 0
	v_add_f32_e32 v16, v16, v32
	v_add_f32_e32 v18, v18, v34
	v_add_f32_e32 v20, v20, v36
	v_add_f32_e32 v22, v22, v38
	v_add_f32_e32 v24, v24, v40
	v_add_f32_e32 v26, v26, v42
	v_add_f32_e32 v28, v28, v44
	v_add_f32_e32 v30, v30, v46
	s_nop 1
	v_permlane16_swap_b32_e32 v16, v24
	v_permlane16_swap_b32_e32 v18, v26
	v_permlane16_swap_b32_e32 v20, v28
	v_permlane16_swap_b32_e32 v22, v30
	s_nop 0
	v_add_f32_e32 v16, v16, v24
	v_add_f32_e32 v18, v18, v26
	v_add_f32_e32 v20, v20, v28
	v_add_f32_e32 v22, v22, v30
	s_nop 1
	v_add_f32_dpp v16, v16, v16 row_ror:8 row_mask:0xf bank_mask:0xf
	v_add_f32_dpp v18, v18, v18 row_ror:8 row_mask:0xf bank_mask:0xf
	v_add_f32_dpp v20, v20, v20 row_ror:8 row_mask:0xf bank_mask:0xf
	v_add_f32_dpp v22, v22, v22 row_ror:8 row_mask:0xf bank_mask:0xf
	s_nop 1
	v_add_f32_dpp v16, v16, v16 row_ror:4 row_mask:0xf bank_mask:0xf
	v_add_f32_dpp v18, v18, v18 row_ror:4 row_mask:0xf bank_mask:0xf
	v_add_f32_dpp v20, v20, v20 row_ror:4 row_mask:0xf bank_mask:0xf
	v_add_f32_dpp v22, v22, v22 row_ror:4 row_mask:0xf bank_mask:0xf
	s_nop 1
	v_add_f32_dpp v16, v16, v16 row_ror:2 row_mask:0xf bank_mask:0xf
	v_add_f32_dpp v18, v18, v18 row_ror:2 row_mask:0xf bank_mask:0xf
	v_add_f32_dpp v20, v20, v20 row_ror:2 row_mask:0xf bank_mask:0xf
	v_add_f32_dpp v22, v22, v22 row_ror:2 row_mask:0xf bank_mask:0xf
	s_nop 1
	v_add_f32_dpp v16, v16, v16 row_ror:1 row_mask:0xf bank_mask:0xf
	v_add_f32_dpp v18, v18, v18 row_ror:1 row_mask:0xf bank_mask:0xf
	v_add_f32_dpp v20, v20, v20 row_ror:1 row_mask:0xf bank_mask:0xf
	v_add_f32_dpp v22, v22, v22 row_ror:1 row_mask:0xf bank_mask:0xf
	v_fmamk_f32 v16, v16, 0x3b800000, v166
	v_fmamk_f32 v18, v18, 0x3b800000, v166
	v_fmamk_f32 v20, v20, 0x3b800000, v166
	v_fmamk_f32 v22, v22, 0x3b800000, v166
	v_mul_f32_e32 v112, 0x4b800000, v16
	v_cmp_gt_f32_e32 vcc, s58, v16
	s_nop 1
	v_cndmask_b32_e32 v16, v16, v112, vcc
	v_rsq_f32_e32 v16, v16
	s_nop 0
	v_mul_f32_e32 v112, 0x45800000, v16
	v_cndmask_b32_e32 v16, v16, v112, vcc
	v_mul_f32_e32 v112, 0x4b800000, v18
	v_cmp_gt_f32_e32 vcc, s58, v18
	s_nop 1
	v_cndmask_b32_e32 v18, v18, v112, vcc
	v_rsq_f32_e32 v18, v18
	s_nop 0
	v_mul_f32_e32 v112, 0x45800000, v18
	v_cndmask_b32_e32 v18, v18, v112, vcc
	v_mul_f32_e32 v112, 0x4b800000, v20
	v_cmp_gt_f32_e32 vcc, s58, v20
	s_nop 1
	v_cndmask_b32_e32 v20, v20, v112, vcc
	v_rsq_f32_e32 v20, v20
	s_nop 0
	v_mul_f32_e32 v112, 0x45800000, v20
	v_cndmask_b32_e32 v20, v20, v112, vcc
	v_mul_f32_e32 v112, 0x4b800000, v22
	v_cmp_gt_f32_e32 vcc, s58, v22
	s_nop 1
	v_cndmask_b32_e32 v22, v22, v112, vcc
	v_rsq_f32_e32 v22, v22
	s_nop 0
	v_mul_f32_e32 v112, 0x45800000, v22
	v_cndmask_b32_e32 v22, v22, v112, vcc
	v_mov_b32_e32 v112, v16
	v_mov_b32_e32 v113, v18
	v_mov_b32_e32 v114, v20
	v_mov_b32_e32 v115, v22
	v_cmp_eq_u32_e32 vcc, 0, v118
	s_and_saveexec_b64 s[0:1], vcc
	ds_write_b128 v117, v[112:115] offset:64
	s_or_b64 exec, exec, s[0:1]
.Lrskv_skip:
.LBB0_941:
	v_mov_b32_e32 v22, v167
	s_waitcnt lgkmcnt(0)
	s_barrier
	s_movk_i32 s11, 0xb80
	v_lshlrev_b32_e32 v1, 4, v22
	v_and_b32_e32 v0, 32, v22
	v_bitop3_b32 v0, v1, v0, 48 bitop3:0x6c
	v_lshrrev_b32_e32 v2, 1, v22
	v_lshrrev_b32_e32 v0, 1, v0
	v_lshrrev_b32_e32 v3, 2, v22
	v_and_or_b32 v5, v2, 32, v0
	v_ashrrev_i32_e32 v0, 3, v22
	v_and_b32_e32 v18, 0xfffffc00, v1
	v_bfi_b32 v2, 15, v3, v0
	v_add_u32_e32 v4, 0x2000, v1
	v_add_u32_e32 v7, 0x4000, v1
	v_add_u32_e32 v1, 0x6000, v1
	s_and_b32 s10, s20, 7
	s_mul_i32 s0, s9, 0x1700
	v_mul_lo_u32 v0, v2, s11
	v_ashrrev_i32_e32 v4, 7, v4
	v_ashrrev_i32_e32 v7, 7, v7
	v_ashrrev_i32_e32 v1, 7, v1
	s_mul_hi_i32 s1, s9, 0x1700
	s_add_u32 s0, s22, s0
	v_or_b32_e32 v0, v0, v5
	v_bfi_b32 v6, -16, v4, v3
	v_bfi_b32 v7, -16, v7, v3
	v_bfi_b32 v1, -16, v1, v3
	s_addc_u32 s1, s23, s1
	s_lshl_b32 s2, s10, 17
	v_mul_lo_u32 v4, v6, s11
	v_mul_lo_u32 v8, v7, s11
	v_mul_lo_u32 v3, v1, s11
	v_lshl_or_b32 v14, v1, 8, v5
	v_add_u32_e32 v19, 0, v18
	v_ashrrev_i32_e32 v1, 31, v0
	s_add_u32 s2, s14, s2
	v_lshl_or_b32 v2, v2, 8, v5
	v_or_b32_e32 v4, v4, v5
	v_lshl_or_b32 v6, v6, 8, v5
	v_or_b32_e32 v8, v8, v5
	v_lshl_or_b32 v10, v7, 8, v5
	v_or_b32_e32 v12, v3, v5
	v_add_u32_e32 v5, 0x8000, v19
	v_lshl_add_u64 v[0:1], v[0:1], 1, s[0:1]
	s_mov_b64 s[40:41], 0x400
	v_readfirstlane_b32 s26, v19
	s_addc_u32 s3, s15, 0
	v_lshl_add_u64 v[16:17], v[0:1], 0, s[40:41]
	s_mov_b32 m0, s26
	v_ashrrev_i32_e32 v3, 31, v2
	v_readfirstlane_b32 s25, v5
	v_ashrrev_i32_e32 v5, 31, v4
	v_add_u32_e32 v7, 0x2000, v19
	global_load_lds_dwordx4 v[16:17], off
	v_lshl_add_u64 v[2:3], v[2:3], 1, s[2:3]
	s_mov_b32 m0, s25
	v_lshl_add_u64 v[4:5], v[4:5], 1, s[0:1]
	v_readfirstlane_b32 s27, v7
	v_add_u32_e32 v9, 0xa000, v19
	global_load_lds_dwordx4 v[2:3], off
	v_lshl_add_u64 v[16:17], v[4:5], 0, s[40:41]
	s_mov_b32 m0, s27
	v_ashrrev_i32_e32 v7, 31, v6
	v_readfirstlane_b32 s34, v9
	v_ashrrev_i32_e32 v9, 31, v8
	v_add_u32_e32 v11, 0x4000, v19
	global_load_lds_dwordx4 v[16:17], off
	v_lshl_add_u64 v[6:7], v[6:7], 1, s[2:3]
	s_mov_b32 m0, s34
	v_lshl_add_u64 v[8:9], v[8:9], 1, s[0:1]
	v_readfirstlane_b32 s35, v11
	v_add_u32_e32 v13, 0xc000, v19
	global_load_lds_dwordx4 v[6:7], off
	v_lshl_add_u64 v[16:17], v[8:9], 0, s[40:41]
	s_mov_b32 m0, s35
	v_ashrrev_i32_e32 v11, 31, v10
	v_readfirstlane_b32 s36, v13
	v_ashrrev_i32_e32 v13, 31, v12
	v_add_u32_e32 v15, 0x6000, v19
	global_load_lds_dwordx4 v[16:17], off
	v_lshl_add_u64 v[10:11], v[10:11], 1, s[2:3]
	s_mov_b32 m0, s36
	v_lshl_add_u64 v[12:13], v[12:13], 1, s[0:1]
	v_readfirstlane_b32 s37, v15
	global_load_lds_dwordx4 v[10:11], off
	v_lshl_add_u64 v[16:17], v[12:13], 0, s[40:41]
	s_mov_b32 m0, s37
	v_ashrrev_i32_e32 v15, 31, v14
	global_load_lds_dwordx4 v[16:17], off
	v_add_u32_e32 v16, 0xe000, v19
	v_lshlrev_b32_e32 v19, 2, v22
	v_readfirstlane_b32 s40, v16
	v_and_b32_e32 v16, 15, v22
	v_and_b32_e32 v17, 48, v22
	v_lshlrev_b32_e32 v16, 6, v16
	v_and_b32_e32 v19, 32, v19
	v_bitop3_b32 v25, v16, v19, v17 bitop3:0x36
	v_lshlrev_b32_e32 v16, 6, v22
	v_and_b32_e32 v126, 0xffffc000, v16
	v_and_b32_e32 v16, 0x3c0, v16
	v_bitop3_b32 v129, v16, v19, v17 bitop3:0x36
	v_add_u32_e32 v19, s90, v18
	v_readlane_b32 s41, v254, 11
	v_lshl_add_u64 v[14:15], v[14:15], 1, s[2:3]
	s_mov_b32 m0, s40
	v_add_u32_e32 v18, s41, v18
	s_mov_b64 s[42:43], 0x480
	v_readfirstlane_b32 s3, v19
	global_load_lds_dwordx4 v[14:15], off
	v_lshl_add_u64 v[16:17], v[0:1], 0, s[42:43]
	s_mov_b32 m0, s3
	v_readfirstlane_b32 s0, v18
	v_add_u32_e32 v20, 0x2000, v19
	s_waitcnt vmcnt(0)
	s_waitcnt vmcnt(0) lgkmcnt(0)
	s_barrier
	global_load_lds_dwordx4 v[16:17], off
	v_lshl_add_u64 v[16:17], v[2:3], 0, s[96:97]
	s_mov_b32 m0, s0
	v_readfirstlane_b32 s1, v20
	v_add_u32_e32 v20, 0x2000, v18
	global_load_lds_dwordx4 v[16:17], off
	v_lshl_add_u64 v[16:17], v[4:5], 0, s[42:43]
	s_mov_b32 m0, s1
	v_readfirstlane_b32 s2, v20
	v_add_u32_e32 v20, 0x4000, v19
	global_load_lds_dwordx4 v[16:17], off
	v_lshl_add_u64 v[16:17], v[6:7], 0, s[96:97]
	s_mov_b32 m0, s2
	v_readfirstlane_b32 s11, v20
	v_add_u32_e32 v20, 0x4000, v18
	global_load_lds_dwordx4 v[16:17], off
	v_lshl_add_u64 v[16:17], v[8:9], 0, s[42:43]
	s_mov_b32 m0, s11
	v_readfirstlane_b32 s16, v20
	v_add_u32_e32 v19, 0x6000, v19
	global_load_lds_dwordx4 v[16:17], off
	v_lshl_add_u64 v[16:17], v[10:11], 0, s[96:97]
	s_mov_b32 m0, s16
	v_readfirstlane_b32 s21, v19
	v_add_u32_e32 v18, 0x6000, v18
	global_load_lds_dwordx4 v[16:17], off
	v_lshl_add_u64 v[16:17], v[12:13], 0, s[42:43]
	s_mov_b32 m0, s21
	v_readfirstlane_b32 s24, v18
	global_load_lds_dwordx4 v[16:17], off
	v_lshl_add_u64 v[16:17], v[14:15], 0, s[96:97]
	s_mov_b32 m0, s24
	v_or_b32_e32 v127, 0x800, v126
	global_load_lds_dwordx4 v[16:17], off
	v_add_u32_e32 v16, 0, v25
	v_add_u32_e32 v24, v16, v126
	ds_read_b128 v[18:21], v24
	v_lshlrev_b32_e32 v17, 7, v22
	v_and_b32_e32 v162, 0x6000, v17
	v_add_u32_e32 v17, 0, v129
	v_add_u32_e32 v23, v16, v162
	v_add_u32_e32 v16, v17, v127
	ds_read_b128 v[26:29], v23 offset:32768
	ds_read_b128 v[30:33], v16
	ds_read_b128 v[34:37], v23 offset:34816
	ds_read_b128 v[46:49], v23 offset:36864
	ds_read_b128 v[50:53], v23 offset:38912
	v_or_b32_e32 v163, 0x1000, v126
	v_or_b32_e32 v164, 0x1800, v126
	v_or_b32_e32 v180, 0x2000, v126
	v_or_b32_e32 v182, 0x2800, v126
	v_or_b32_e32 v183, 0x3000, v126
	v_or_b32_e32 v193, 0x3800, v126
	s_waitcnt lgkmcnt(0)
	v_mfma_f32_16x16x32_bf16 v[38:41], v[18:21], v[26:29], 0
	v_add_u32_e32 v22, v17, v163
	ds_read_b128 v[74:77], v22
	v_mfma_f32_16x16x32_bf16 v[42:45], v[18:21], v[34:37], 0
	v_mfma_f32_16x16x32_bf16 v[54:57], v[18:21], v[46:49], 0
	v_mfma_f32_16x16x32_bf16 v[58:61], v[18:21], v[50:53], 0
	v_add_u32_e32 v19, v17, v164
	v_add_u32_e32 v21, v17, v180
	v_add_u32_e32 v18, v17, v182
	v_add_u32_e32 v20, v17, v183
	v_add_u32_e32 v17, v17, v193
	ds_read_b128 v[78:81], v19
	ds_read_b128 v[142:145], v20
	ds_read_b128 v[106:109], v21
	ds_read_b128 v[110:113], v18
	ds_read_b128 v[146:149], v17
	v_mfma_f32_16x16x32_bf16 v[62:65], v[30:33], v[26:29], 0
	v_mfma_f32_16x16x32_bf16 v[66:69], v[30:33], v[34:37], 0
	v_mfma_f32_16x16x32_bf16 v[70:73], v[30:33], v[46:49], 0
	v_mfma_f32_16x16x32_bf16 v[30:33], v[30:33], v[50:53], 0
	s_waitcnt lgkmcnt(0)
	v_mfma_f32_16x16x32_bf16 v[82:85], v[74:77], v[26:29], 0
	v_mfma_f32_16x16x32_bf16 v[86:89], v[74:77], v[34:37], 0
	v_mfma_f32_16x16x32_bf16 v[90:93], v[74:77], v[46:49], 0
	v_mfma_f32_16x16x32_bf16 v[74:77], v[74:77], v[50:53], 0
	v_mfma_f32_16x16x32_bf16 v[94:97], v[78:81], v[26:29], 0
	v_mfma_f32_16x16x32_bf16 v[98:101], v[78:81], v[34:37], 0
	v_mfma_f32_16x16x32_bf16 v[102:105], v[78:81], v[46:49], 0
	v_mfma_f32_16x16x32_bf16 v[78:81], v[78:81], v[50:53], 0
	v_mfma_f32_16x16x32_bf16 v[114:117], v[106:109], v[26:29], 0
	v_mfma_f32_16x16x32_bf16 v[118:121], v[106:109], v[34:37], 0
	v_mfma_f32_16x16x32_bf16 v[122:125], v[106:109], v[46:49], 0
	v_mfma_f32_16x16x32_bf16 v[106:109], v[106:109], v[50:53], 0
	v_mfma_f32_16x16x32_bf16 v[130:133], v[110:113], v[26:29], 0
	v_mfma_f32_16x16x32_bf16 v[134:137], v[110:113], v[34:37], 0
	v_mfma_f32_16x16x32_bf16 v[138:141], v[110:113], v[46:49], 0
	v_mfma_f32_16x16x32_bf16 v[110:113], v[110:113], v[50:53], 0
	v_mfma_f32_16x16x32_bf16 v[150:153], v[142:145], v[26:29], 0
	v_mfma_f32_16x16x32_bf16 v[154:157], v[142:145], v[34:37], 0
	v_mfma_f32_16x16x32_bf16 v[158:161], v[142:145], v[46:49], 0
	v_mfma_f32_16x16x32_bf16 v[142:145], v[142:145], v[50:53], 0
	v_mfma_f32_16x16x32_bf16 v[26:29], v[146:149], v[26:29], 0
	v_mfma_f32_16x16x32_bf16 v[34:37], v[146:149], v[34:37], 0
	v_mfma_f32_16x16x32_bf16 v[46:49], v[146:149], v[46:49], 0
	v_mfma_f32_16x16x32_bf16 v[50:53], v[146:149], v[50:53], 0
	ds_read_b128 v[146:149], v24 offset:1024
	ds_read_b128 v[168:171], v23 offset:33792
	ds_read_b128 v[172:175], v23 offset:35840
	ds_read_b128 v[176:179], v23 offset:37888
	ds_read_b128 v[194:197], v23 offset:39936
	s_waitcnt lgkmcnt(0)
	v_mfma_f32_16x16x32_bf16 v[38:41], v[146:149], v[168:171], v[38:41]
	v_mfma_f32_16x16x32_bf16 v[42:45], v[146:149], v[172:175], v[42:45]
	v_mfma_f32_16x16x32_bf16 v[54:57], v[146:149], v[176:179], v[54:57]
	v_mfma_f32_16x16x32_bf16 v[58:61], v[146:149], v[194:197], v[58:61]
	ds_read_b128 v[146:149], v16 offset:1024
	s_waitcnt lgkmcnt(0)
	v_mfma_f32_16x16x32_bf16 v[62:65], v[146:149], v[168:171], v[62:65]
	v_mfma_f32_16x16x32_bf16 v[66:69], v[146:149], v[172:175], v[66:69]
	v_mfma_f32_16x16x32_bf16 v[70:73], v[146:149], v[176:179], v[70:73]
	v_mfma_f32_16x16x32_bf16 v[30:33], v[146:149], v[194:197], v[30:33]
	ds_read_b128 v[146:149], v22 offset:1024
	s_waitcnt lgkmcnt(0)
	v_mfma_f32_16x16x32_bf16 v[82:85], v[146:149], v[168:171], v[82:85]
	v_mfma_f32_16x16x32_bf16 v[86:89], v[146:149], v[172:175], v[86:89]
	v_mfma_f32_16x16x32_bf16 v[90:93], v[146:149], v[176:179], v[90:93]
	v_mfma_f32_16x16x32_bf16 v[74:77], v[146:149], v[194:197], v[74:77]
	ds_read_b128 v[146:149], v19 offset:1024
	s_waitcnt lgkmcnt(0)
	v_mfma_f32_16x16x32_bf16 v[94:97], v[146:149], v[168:171], v[94:97]
	v_mfma_f32_16x16x32_bf16 v[98:101], v[146:149], v[172:175], v[98:101]
	v_mfma_f32_16x16x32_bf16 v[102:105], v[146:149], v[176:179], v[102:105]
	v_mfma_f32_16x16x32_bf16 v[78:81], v[146:149], v[194:197], v[78:81]
	ds_read_b128 v[146:149], v21 offset:1024
	s_waitcnt lgkmcnt(0)
	v_mfma_f32_16x16x32_bf16 v[114:117], v[146:149], v[168:171], v[114:117]
	v_mfma_f32_16x16x32_bf16 v[118:121], v[146:149], v[172:175], v[118:121]
	v_mfma_f32_16x16x32_bf16 v[122:125], v[146:149], v[176:179], v[122:125]
	v_mfma_f32_16x16x32_bf16 v[106:109], v[146:149], v[194:197], v[106:109]
	ds_read_b128 v[146:149], v18 offset:1024
	s_waitcnt lgkmcnt(0)
	v_mfma_f32_16x16x32_bf16 v[130:133], v[146:149], v[168:171], v[130:133]
	v_mfma_f32_16x16x32_bf16 v[134:137], v[146:149], v[172:175], v[134:137]
	v_mfma_f32_16x16x32_bf16 v[138:141], v[146:149], v[176:179], v[138:141]
	v_mfma_f32_16x16x32_bf16 v[110:113], v[146:149], v[194:197], v[110:113]
	ds_read_b128 v[146:149], v20 offset:1024
	s_waitcnt lgkmcnt(0)
	v_mfma_f32_16x16x32_bf16 v[150:153], v[146:149], v[168:171], v[150:153]
	v_mfma_f32_16x16x32_bf16 v[154:157], v[146:149], v[172:175], v[154:157]
	v_mfma_f32_16x16x32_bf16 v[158:161], v[146:149], v[176:179], v[158:161]
	v_mfma_f32_16x16x32_bf16 v[142:145], v[146:149], v[194:197], v[142:145]
	ds_read_b128 v[146:149], v17 offset:1024
	s_waitcnt lgkmcnt(0)
	v_mfma_f32_16x16x32_bf16 v[34:37], v[146:149], v[172:175], v[34:37]
	v_mfma_f32_16x16x32_bf16 v[46:49], v[146:149], v[176:179], v[46:49]
	v_mfma_f32_16x16x32_bf16 v[50:53], v[146:149], v[194:197], v[50:53]
	v_mfma_f32_16x16x32_bf16 v[168:171], v[146:149], v[168:171], v[26:29]
	s_mov_b64 s[42:43], 0x500
	s_mov_b32 m0, s26
	s_nop 0
	v_lshl_add_u64 v[26:27], v[0:1], 0, s[42:43]
	s_waitcnt vmcnt(0)
	s_waitcnt vmcnt(0)
	s_barrier
	global_load_lds_dwordx4 v[26:27], off
	v_lshl_add_u64 v[26:27], v[2:3], 0, s[62:63]
	s_mov_b32 m0, s25
	s_nop 0
	global_load_lds_dwordx4 v[26:27], off
	v_lshl_add_u64 v[26:27], v[4:5], 0, s[42:43]
	s_mov_b32 m0, s27
	s_nop 0
	global_load_lds_dwordx4 v[26:27], off
	v_lshl_add_u64 v[26:27], v[6:7], 0, s[62:63]
	s_mov_b32 m0, s34
	s_nop 0
	global_load_lds_dwordx4 v[26:27], off
	v_lshl_add_u64 v[26:27], v[8:9], 0, s[42:43]
	s_mov_b32 m0, s35
	s_nop 0
	global_load_lds_dwordx4 v[26:27], off
	v_lshl_add_u64 v[26:27], v[10:11], 0, s[62:63]
	s_mov_b32 m0, s36
	s_nop 0
	global_load_lds_dwordx4 v[26:27], off
	v_lshl_add_u64 v[26:27], v[12:13], 0, s[42:43]
	s_mov_b32 m0, s37
	s_nop 0
	global_load_lds_dwordx4 v[26:27], off
	v_lshl_add_u64 v[26:27], v[14:15], 0, s[62:63]
	s_mov_b32 m0, s40
	s_nop 0
	global_load_lds_dwordx4 v[26:27], off
	v_add3_u32 v26, s90, v25, v126
	ds_read_b128 v[146:149], v26
	v_add3_u32 v25, s41, v25, v162
	ds_read_b128 v[172:175], v25
	ds_read_b128 v[176:179], v25 offset:2048
	ds_read_b128 v[194:197], v25 offset:4096
	ds_read_b128 v[198:201], v25 offset:6144
	v_add_u32_e32 v126, s90, v129
	v_add_u32_e32 v27, v126, v127
	v_add_u32_e32 v29, v126, v164
	ds_read_b128 v[202:205], v29
	s_waitcnt lgkmcnt(0)
	v_mfma_f32_16x16x32_bf16 v[38:41], v[146:149], v[172:175], v[38:41]
	v_add_u32_e32 v28, v126, v163
	v_add_u32_e32 v129, v126, v183
	v_mfma_f32_16x16x32_bf16 v[42:45], v[146:149], v[176:179], v[42:45]
	v_mfma_f32_16x16x32_bf16 v[54:57], v[146:149], v[194:197], v[54:57]
	v_mfma_f32_16x16x32_bf16 v[58:61], v[146:149], v[198:201], v[58:61]
	ds_read_b128 v[146:149], v27
	s_waitcnt lgkmcnt(0)
	v_mfma_f32_16x16x32_bf16 v[62:65], v[146:149], v[172:175], v[62:65]
	v_mfma_f32_16x16x32_bf16 v[66:69], v[146:149], v[176:179], v[66:69]
	v_mfma_f32_16x16x32_bf16 v[70:73], v[146:149], v[194:197], v[70:73]
	v_mfma_f32_16x16x32_bf16 v[146:149], v[146:149], v[198:201], v[30:33]
	s_nop 2
	ds_read_b128 v[30:33], v28
	s_waitcnt lgkmcnt(0)
	v_mfma_f32_16x16x32_bf16 v[82:85], v[30:33], v[172:175], v[82:85]
	v_mfma_f32_16x16x32_bf16 v[86:89], v[30:33], v[176:179], v[86:89]
	v_mfma_f32_16x16x32_bf16 v[90:93], v[30:33], v[194:197], v[90:93]
	v_mfma_f32_16x16x32_bf16 v[74:77], v[30:33], v[198:201], v[74:77]
	v_add_u32_e32 v30, v126, v180
	v_add_u32_e32 v31, v126, v182
	v_mfma_f32_16x16x32_bf16 v[94:97], v[202:205], v[172:175], v[94:97]
	v_mfma_f32_16x16x32_bf16 v[98:101], v[202:205], v[176:179], v[98:101]
	v_mfma_f32_16x16x32_bf16 v[102:105], v[202:205], v[194:197], v[102:105]
	v_mfma_f32_16x16x32_bf16 v[78:81], v[202:205], v[198:201], v[78:81]
	ds_read_b128 v[202:205], v30
	s_waitcnt lgkmcnt(0)
	v_mfma_f32_16x16x32_bf16 v[114:117], v[202:205], v[172:175], v[114:117]
	v_mfma_f32_16x16x32_bf16 v[118:121], v[202:205], v[176:179], v[118:121]
	v_mfma_f32_16x16x32_bf16 v[122:125], v[202:205], v[194:197], v[122:125]
	v_mfma_f32_16x16x32_bf16 v[106:109], v[202:205], v[198:201], v[106:109]
	ds_read_b128 v[202:205], v31
	s_waitcnt lgkmcnt(0)
	v_mfma_f32_16x16x32_bf16 v[206:209], v[202:205], v[172:175], v[130:133]
	s_nop 2
	v_add_u32_e32 v130, v126, v193
	v_mfma_f32_16x16x32_bf16 v[132:135], v[202:205], v[176:179], v[134:137]
	v_mfma_f32_16x16x32_bf16 v[136:139], v[202:205], v[194:197], v[138:141]
	v_mfma_f32_16x16x32_bf16 v[110:113], v[202:205], v[198:201], v[110:113]
	ds_read_b128 v[202:205], v129
	s_waitcnt lgkmcnt(0)
	v_mfma_f32_16x16x32_bf16 v[150:153], v[202:205], v[172:175], v[150:153]
	v_mfma_f32_16x16x32_bf16 v[154:157], v[202:205], v[176:179], v[154:157]
	v_mfma_f32_16x16x32_bf16 v[158:161], v[202:205], v[194:197], v[158:161]
	v_mfma_f32_16x16x32_bf16 v[140:143], v[202:205], v[198:201], v[142:145]
	ds_read_b128 v[202:205], v130
	s_waitcnt lgkmcnt(0)
	v_mfma_f32_16x16x32_bf16 v[32:35], v[202:205], v[176:179], v[34:37]
	v_mfma_f32_16x16x32_bf16 v[46:49], v[202:205], v[194:197], v[46:49]
	v_mfma_f32_16x16x32_bf16 v[50:53], v[202:205], v[198:201], v[50:53]
	v_mfma_f32_16x16x32_bf16 v[168:171], v[202:205], v[172:175], v[168:171]
	ds_read_b128 v[172:175], v26 offset:1024
	ds_read_b128 v[176:179], v25 offset:1024
	ds_read_b128 v[194:197], v25 offset:3072
	ds_read_b128 v[198:201], v25 offset:5120
	ds_read_b128 v[202:205], v25 offset:7168
	s_waitcnt lgkmcnt(0)
	v_mfma_f32_16x16x32_bf16 v[36:39], v[172:175], v[176:179], v[38:41]
	v_mfma_f32_16x16x32_bf16 v[40:43], v[172:175], v[194:197], v[42:45]
	v_mfma_f32_16x16x32_bf16 v[54:57], v[172:175], v[198:201], v[54:57]
	v_mfma_f32_16x16x32_bf16 v[58:61], v[172:175], v[202:205], v[58:61]
	ds_read_b128 v[172:175], v27 offset:1024
	s_waitcnt lgkmcnt(0)
	v_mfma_f32_16x16x32_bf16 v[62:65], v[172:175], v[176:179], v[62:65]
	v_mfma_f32_16x16x32_bf16 v[66:69], v[172:175], v[194:197], v[66:69]
	v_mfma_f32_16x16x32_bf16 v[70:73], v[172:175], v[198:201], v[70:73]
	v_mfma_f32_16x16x32_bf16 v[144:147], v[172:175], v[202:205], v[146:149]
	ds_read_b128 v[172:175], v28 offset:1024
	s_waitcnt lgkmcnt(0)
	v_mfma_f32_16x16x32_bf16 v[82:85], v[172:175], v[176:179], v[82:85]
	v_mfma_f32_16x16x32_bf16 v[86:89], v[172:175], v[194:197], v[86:89]
	v_mfma_f32_16x16x32_bf16 v[90:93], v[172:175], v[198:201], v[90:93]
	v_mfma_f32_16x16x32_bf16 v[74:77], v[172:175], v[202:205], v[74:77]
	ds_read_b128 v[172:175], v29 offset:1024
	s_waitcnt lgkmcnt(0)
	v_mfma_f32_16x16x32_bf16 v[94:97], v[172:175], v[176:179], v[94:97]
	v_mfma_f32_16x16x32_bf16 v[98:101], v[172:175], v[194:197], v[98:101]
	v_mfma_f32_16x16x32_bf16 v[102:105], v[172:175], v[198:201], v[102:105]
	v_mfma_f32_16x16x32_bf16 v[78:81], v[172:175], v[202:205], v[78:81]
	ds_read_b128 v[172:175], v30 offset:1024
	s_waitcnt lgkmcnt(0)
	v_mfma_f32_16x16x32_bf16 v[114:117], v[172:175], v[176:179], v[114:117]
	v_mfma_f32_16x16x32_bf16 v[118:121], v[172:175], v[194:197], v[118:121]
	v_mfma_f32_16x16x32_bf16 v[122:125], v[172:175], v[198:201], v[122:125]
	v_mfma_f32_16x16x32_bf16 v[106:109], v[172:175], v[202:205], v[106:109]
	ds_read_b128 v[172:175], v31 offset:1024
	s_waitcnt lgkmcnt(0)
	v_mfma_f32_16x16x32_bf16 v[206:209], v[172:175], v[176:179], v[206:209]
	v_mfma_f32_16x16x32_bf16 v[132:135], v[172:175], v[194:197], v[132:135]
	v_mfma_f32_16x16x32_bf16 v[136:139], v[172:175], v[198:201], v[136:139]
	v_mfma_f32_16x16x32_bf16 v[110:113], v[172:175], v[202:205], v[110:113]
	ds_read_b128 v[172:175], v129 offset:1024
	s_waitcnt lgkmcnt(0)
	v_mfma_f32_16x16x32_bf16 v[148:151], v[172:175], v[176:179], v[150:153]
	v_mfma_f32_16x16x32_bf16 v[152:155], v[172:175], v[194:197], v[154:157]
	v_mfma_f32_16x16x32_bf16 v[156:159], v[172:175], v[198:201], v[158:161]
	s_nop 2
	ds_read_b128 v[160:163], v130 offset:1024
	s_waitcnt lgkmcnt(0)
	v_mfma_f32_16x16x32_bf16 v[32:35], v[160:163], v[194:197], v[32:35]
	v_mfma_f32_16x16x32_bf16 v[44:47], v[160:163], v[198:201], v[46:49]
	v_mfma_f32_16x16x32_bf16 v[48:51], v[160:163], v[202:205], v[50:53]
	v_mfma_f32_16x16x32_bf16 v[140:143], v[172:175], v[202:205], v[140:143]
	v_mfma_f32_16x16x32_bf16 v[168:171], v[160:163], v[176:179], v[168:171]
	s_mov_b64 s[26:27], 0x580
	s_mov_b32 m0, s3
	v_lshl_add_u64 v[0:1], v[0:1], 0, s[26:27]
	s_waitcnt vmcnt(0)
	s_waitcnt vmcnt(0)
	s_barrier
	global_load_lds_dwordx4 v[0:1], off
	v_lshl_add_u64 v[0:1], v[2:3], 0, s[6:7]
	s_mov_b32 m0, s0
	s_nop 0
	global_load_lds_dwordx4 v[0:1], off
	v_lshl_add_u64 v[0:1], v[4:5], 0, s[26:27]
	s_mov_b32 m0, s1
	s_nop 0
	global_load_lds_dwordx4 v[0:1], off
	v_lshl_add_u64 v[0:1], v[6:7], 0, s[6:7]
	s_mov_b32 m0, s2
	s_nop 0
	global_load_lds_dwordx4 v[0:1], off
	v_lshl_add_u64 v[0:1], v[8:9], 0, s[26:27]
	s_mov_b32 m0, s11
	s_nop 0
	global_load_lds_dwordx4 v[0:1], off
	v_lshl_add_u64 v[0:1], v[10:11], 0, s[6:7]
	s_mov_b32 m0, s16
	s_nop 0
	global_load_lds_dwordx4 v[0:1], off
	v_lshl_add_u64 v[0:1], v[12:13], 0, s[26:27]
	s_mov_b32 m0, s21
	s_nop 0
	global_load_lds_dwordx4 v[0:1], off
	v_lshl_add_u64 v[0:1], v[14:15], 0, s[6:7]
	s_mov_b32 m0, s24
	s_nop 0
	global_load_lds_dwordx4 v[0:1], off
	ds_read_b128 v[0:3], v24
	ds_read_b128 v[4:7], v23 offset:32768
	ds_read_b128 v[12:15], v23 offset:34816
	ds_read_b128 v[160:163], v23 offset:38912
	s_waitcnt lgkmcnt(0)
	v_mfma_f32_16x16x32_bf16 v[8:11], v[0:3], v[4:7], v[36:39]
	v_mfma_f32_16x16x32_bf16 v[36:39], v[0:3], v[12:15], v[40:43]
	s_nop 2
	ds_read_b128 v[40:43], v23 offset:36864
	s_waitcnt lgkmcnt(0)
	v_mfma_f32_16x16x32_bf16 v[52:55], v[0:3], v[40:43], v[54:57]
	v_mfma_f32_16x16x32_bf16 v[0:3], v[0:3], v[160:163], v[58:61]
	s_nop 2
	ds_read_b128 v[56:59], v16
	s_waitcnt lgkmcnt(0)
	v_mfma_f32_16x16x32_bf16 v[60:63], v[56:59], v[4:7], v[62:65]
	v_mfma_f32_16x16x32_bf16 v[64:67], v[56:59], v[12:15], v[66:69]
	v_mfma_f32_16x16x32_bf16 v[68:71], v[56:59], v[40:43], v[70:73]
	v_mfma_f32_16x16x32_bf16 v[56:59], v[56:59], v[160:163], v[144:147]
	s_nop 2
	ds_read_b128 v[144:147], v22
	s_waitcnt lgkmcnt(0)
	v_mfma_f32_16x16x32_bf16 v[82:85], v[144:147], v[4:7], v[82:85]
	v_mfma_f32_16x16x32_bf16 v[86:89], v[144:147], v[12:15], v[86:89]
	v_mfma_f32_16x16x32_bf16 v[90:93], v[144:147], v[40:43], v[90:93]
	v_mfma_f32_16x16x32_bf16 v[72:75], v[144:147], v[160:163], v[74:77]
	ds_read_b128 v[144:147], v19
	s_waitcnt lgkmcnt(0)
	v_mfma_f32_16x16x32_bf16 v[94:97], v[144:147], v[4:7], v[94:97]
	v_mfma_f32_16x16x32_bf16 v[98:101], v[144:147], v[12:15], v[98:101]
	v_mfma_f32_16x16x32_bf16 v[102:105], v[144:147], v[40:43], v[102:105]
	v_mfma_f32_16x16x32_bf16 v[76:79], v[144:147], v[160:163], v[78:81]
	ds_read_b128 v[144:147], v21
	s_waitcnt lgkmcnt(0)
	v_mfma_f32_16x16x32_bf16 v[114:117], v[144:147], v[4:7], v[114:117]
	v_mfma_f32_16x16x32_bf16 v[118:121], v[144:147], v[12:15], v[118:121]
	v_mfma_f32_16x16x32_bf16 v[122:125], v[144:147], v[40:43], v[122:125]
	v_mfma_f32_16x16x32_bf16 v[106:109], v[144:147], v[160:163], v[106:109]
	ds_read_b128 v[144:147], v18
	s_waitcnt lgkmcnt(0)
	v_mfma_f32_16x16x32_bf16 v[172:175], v[144:147], v[4:7], v[206:209]
	v_mfma_f32_16x16x32_bf16 v[132:135], v[144:147], v[12:15], v[132:135]
	v_mfma_f32_16x16x32_bf16 v[136:139], v[144:147], v[40:43], v[136:139]
	v_mfma_f32_16x16x32_bf16 v[110:113], v[144:147], v[160:163], v[110:113]
	ds_read_b128 v[144:147], v20
	s_waitcnt lgkmcnt(0)
	v_mfma_f32_16x16x32_bf16 v[148:151], v[144:147], v[4:7], v[148:151]
	v_mfma_f32_16x16x32_bf16 v[152:155], v[144:147], v[12:15], v[152:155]
	v_mfma_f32_16x16x32_bf16 v[156:159], v[144:147], v[40:43], v[156:159]
	v_mfma_f32_16x16x32_bf16 v[140:143], v[144:147], v[160:163], v[140:143]
	ds_read_b128 v[144:147], v17
	s_waitcnt lgkmcnt(0)
	v_mfma_f32_16x16x32_bf16 v[4:7], v[144:147], v[4:7], v[168:171]
	v_mfma_f32_16x16x32_bf16 v[12:15], v[144:147], v[12:15], v[32:35]
	v_mfma_f32_16x16x32_bf16 v[32:35], v[144:147], v[40:43], v[44:47]
	v_mfma_f32_16x16x32_bf16 v[40:43], v[144:147], v[160:163], v[48:51]
	s_nop 1
	ds_read_b128 v[44:47], v24 offset:1024
	ds_read_b128 v[48:51], v23 offset:33792
	ds_read_b128 v[144:147], v23 offset:35840
	ds_read_b128 v[160:163], v23 offset:37888
	ds_read_b128 v[168:171], v23 offset:39936
	s_waitcnt lgkmcnt(0)
	v_mfma_f32_16x16x32_bf16 v[8:11], v[44:47], v[48:51], v[8:11]
	v_mfma_f32_16x16x32_bf16 v[36:39], v[44:47], v[144:147], v[36:39]
	v_mfma_f32_16x16x32_bf16 v[52:55], v[44:47], v[160:163], v[52:55]
	v_mfma_f32_16x16x32_bf16 v[0:3], v[44:47], v[168:171], v[0:3]
	ds_read_b128 v[44:47], v16 offset:1024
	s_waitcnt lgkmcnt(0)
	v_mfma_f32_16x16x32_bf16 v[60:63], v[44:47], v[48:51], v[60:63]
	v_mfma_f32_16x16x32_bf16 v[64:67], v[44:47], v[144:147], v[64:67]
	v_mfma_f32_16x16x32_bf16 v[68:71], v[44:47], v[160:163], v[68:71]
	v_mfma_f32_16x16x32_bf16 v[44:47], v[44:47], v[168:171], v[56:59]
	s_nop 2
	ds_read_b128 v[56:59], v22 offset:1024
	s_waitcnt lgkmcnt(0)
	v_mfma_f32_16x16x32_bf16 v[80:83], v[56:59], v[48:51], v[82:85]
	v_mfma_f32_16x16x32_bf16 v[84:87], v[56:59], v[144:147], v[86:89]
	v_mfma_f32_16x16x32_bf16 v[88:91], v[56:59], v[160:163], v[90:93]
	v_mfma_f32_16x16x32_bf16 v[56:59], v[56:59], v[168:171], v[72:75]
	s_nop 2
	ds_read_b128 v[72:75], v19 offset:1024
	s_waitcnt lgkmcnt(0)
	v_mfma_f32_16x16x32_bf16 v[92:95], v[72:75], v[48:51], v[94:97]
	v_mfma_f32_16x16x32_bf16 v[96:99], v[72:75], v[144:147], v[98:101]
	v_mfma_f32_16x16x32_bf16 v[100:103], v[72:75], v[160:163], v[102:105]
	v_mfma_f32_16x16x32_bf16 v[72:75], v[72:75], v[168:171], v[76:79]
	s_nop 2
	ds_read_b128 v[76:79], v21 offset:1024
	s_waitcnt lgkmcnt(0)
	v_mfma_f32_16x16x32_bf16 v[114:117], v[76:79], v[48:51], v[114:117]
	v_mfma_f32_16x16x32_bf16 v[118:121], v[76:79], v[144:147], v[118:121]
	v_mfma_f32_16x16x32_bf16 v[122:125], v[76:79], v[160:163], v[122:125]
	v_mfma_f32_16x16x32_bf16 v[76:79], v[76:79], v[168:171], v[106:109]
	s_nop 2
	ds_read_b128 v[104:107], v18 offset:1024
	ds_read_b128 v[18:21], v20 offset:1024
	s_waitcnt lgkmcnt(0)
	v_mfma_f32_16x16x32_bf16 v[172:175], v[104:107], v[48:51], v[172:175]
	v_mfma_f32_16x16x32_bf16 v[132:135], v[104:107], v[144:147], v[132:135]
	v_mfma_f32_16x16x32_bf16 v[136:139], v[104:107], v[160:163], v[136:139]
	v_mfma_f32_16x16x32_bf16 v[104:107], v[104:107], v[168:171], v[110:113]
	v_mfma_f32_16x16x32_bf16 v[108:111], v[18:21], v[48:51], v[148:151]
	v_mfma_f32_16x16x32_bf16 v[148:151], v[18:21], v[144:147], v[152:155]
	v_mfma_f32_16x16x32_bf16 v[152:155], v[18:21], v[160:163], v[156:159]
	v_mfma_f32_16x16x32_bf16 v[18:21], v[18:21], v[168:171], v[140:143]
	s_nop 2
	ds_read_b128 v[140:143], v17 offset:1024
	s_waitcnt lgkmcnt(0)
	v_mfma_f32_16x16x32_bf16 v[4:7], v[140:143], v[48:51], v[4:7]
	v_mfma_f32_16x16x32_bf16 v[12:15], v[140:143], v[144:147], v[12:15]
	v_mfma_f32_16x16x32_bf16 v[32:35], v[140:143], v[160:163], v[32:35]
	v_mfma_f32_16x16x32_bf16 v[40:43], v[140:143], v[168:171], v[40:43]
	s_waitcnt vmcnt(0)
	s_waitcnt vmcnt(0)
	s_barrier
	ds_read_b128 v[48:51], v26
	ds_read_b128 v[140:143], v25
	ds_read_b128 v[144:147], v25 offset:2048
	ds_read_b128 v[156:159], v25 offset:4096
	ds_read_b128 v[160:163], v25 offset:6144
	s_waitcnt lgkmcnt(3)
	v_mfma_f32_16x16x32_bf16 v[8:11], v[48:51], v[140:143], v[8:11]
	s_waitcnt lgkmcnt(2)
	v_mfma_f32_16x16x32_bf16 v[36:39], v[48:51], v[144:147], v[36:39]
	s_waitcnt lgkmcnt(1)
	v_mfma_f32_16x16x32_bf16 v[52:55], v[48:51], v[156:159], v[52:55]
	s_waitcnt lgkmcnt(0)
	v_mfma_f32_16x16x32_bf16 v[0:3], v[48:51], v[160:163], v[0:3]
	ds_read_b128 v[48:51], v27
	s_waitcnt lgkmcnt(0)
	v_mfma_f32_16x16x32_bf16 v[60:63], v[48:51], v[140:143], v[60:63]
	v_mfma_f32_16x16x32_bf16 v[64:67], v[48:51], v[144:147], v[64:67]
	v_mfma_f32_16x16x32_bf16 v[68:71], v[48:51], v[156:159], v[68:71]
	v_mfma_f32_16x16x32_bf16 v[44:47], v[48:51], v[160:163], v[44:47]
	ds_read_b128 v[48:51], v28
	s_waitcnt lgkmcnt(0)
	v_mfma_f32_16x16x32_bf16 v[80:83], v[48:51], v[140:143], v[80:83]
	v_mfma_f32_16x16x32_bf16 v[84:87], v[48:51], v[144:147], v[84:87]
	v_mfma_f32_16x16x32_bf16 v[168:171], v[48:51], v[156:159], v[88:91]
	v_mfma_f32_16x16x32_bf16 v[48:51], v[48:51], v[160:163], v[56:59]
	s_nop 2
	ds_read_b128 v[56:59], v29
	s_waitcnt lgkmcnt(0)
	v_mfma_f32_16x16x32_bf16 v[176:179], v[56:59], v[140:143], v[92:95]
	v_mfma_f32_16x16x32_bf16 v[194:197], v[56:59], v[144:147], v[96:99]
	v_mfma_f32_16x16x32_bf16 v[198:201], v[56:59], v[156:159], v[100:103]
	v_mfma_f32_16x16x32_bf16 v[56:59], v[56:59], v[160:163], v[72:75]
	s_nop 2
	ds_read_b128 v[72:75], v30
	s_waitcnt lgkmcnt(0)
	v_mfma_f32_16x16x32_bf16 v[202:205], v[72:75], v[140:143], v[114:117]
	v_mfma_f32_16x16x32_bf16 v[206:209], v[72:75], v[144:147], v[118:121]
	v_mfma_f32_16x16x32_bf16 v[210:213], v[72:75], v[156:159], v[122:125]
	v_mfma_f32_16x16x32_bf16 v[214:217], v[72:75], v[160:163], v[76:79]
	ds_read_b128 v[72:75], v31
	s_waitcnt lgkmcnt(0)
	v_mfma_f32_16x16x32_bf16 v[172:175], v[72:75], v[140:143], v[172:175]
	v_mfma_f32_16x16x32_bf16 v[132:135], v[72:75], v[144:147], v[132:135]
	v_mfma_f32_16x16x32_bf16 v[136:139], v[72:75], v[156:159], v[136:139]
	v_mfma_f32_16x16x32_bf16 v[218:221], v[72:75], v[160:163], v[104:107]
	ds_read_b128 v[72:75], v129
	s_waitcnt lgkmcnt(0)
	v_mfma_f32_16x16x32_bf16 v[16:19], v[72:75], v[160:163], v[18:21]
	s_nop 2
	ds_read_b128 v[20:23], v130
	s_waitcnt lgkmcnt(0)
	v_mfma_f32_16x16x32_bf16 v[4:7], v[20:23], v[140:143], v[4:7]
	v_mfma_f32_16x16x32_bf16 v[222:225], v[72:75], v[140:143], v[108:111]
	v_mfma_f32_16x16x32_bf16 v[148:151], v[72:75], v[144:147], v[148:151]
	v_mfma_f32_16x16x32_bf16 v[152:155], v[72:75], v[156:159], v[152:155]
	v_mfma_f32_16x16x32_bf16 v[140:143], v[20:23], v[144:147], v[12:15]
	v_mfma_f32_16x16x32_bf16 v[144:147], v[20:23], v[156:159], v[32:35]
	v_mfma_f32_16x16x32_bf16 v[156:159], v[20:23], v[160:163], v[40:43]
	s_nop 0
	ds_read_b128 v[12:15], v26 offset:1024
	ds_read_b128 v[160:163], v25 offset:1024
	ds_read_b128 v[230:233], v25 offset:7168
	s_waitcnt lgkmcnt(0)
	v_mfma_f32_16x16x32_bf16 v[112:115], v[12:15], v[230:233], v[0:3]
	s_nop 2
	ds_read_b128 v[0:3], v27 offset:1024
	ds_read_b128 v[226:229], v25 offset:5120
	v_mfma_f32_16x16x32_bf16 v[124:127], v[12:15], v[160:163], v[8:11]
	s_nop 2
	ds_read_b128 v[8:11], v25 offset:3072
	s_waitcnt lgkmcnt(2)
	v_mfma_f32_16x16x32_bf16 v[108:111], v[0:3], v[160:163], v[60:63]
	s_waitcnt lgkmcnt(0)
	v_mfma_f32_16x16x32_bf16 v[104:107], v[0:3], v[8:11], v[64:67]
	v_mfma_f32_16x16x32_bf16 v[100:103], v[0:3], v[226:229], v[68:71]
	v_mfma_f32_16x16x32_bf16 v[96:99], v[0:3], v[230:233], v[44:47]
	ds_read_b128 v[0:3], v28 offset:1024
	s_waitcnt lgkmcnt(0)
	v_mfma_f32_16x16x32_bf16 v[92:95], v[0:3], v[160:163], v[80:83]
	v_mfma_f32_16x16x32_bf16 v[88:91], v[0:3], v[8:11], v[84:87]
	v_mfma_f32_16x16x32_bf16 v[84:87], v[0:3], v[226:229], v[168:171]
	v_mfma_f32_16x16x32_bf16 v[80:83], v[0:3], v[230:233], v[48:51]
	ds_read_b128 v[0:3], v29 offset:1024
	s_waitcnt lgkmcnt(0)
	v_mfma_f32_16x16x32_bf16 v[76:79], v[0:3], v[160:163], v[176:179]
	v_mfma_f32_16x16x32_bf16 v[72:75], v[0:3], v[8:11], v[194:197]
	v_mfma_f32_16x16x32_bf16 v[68:71], v[0:3], v[226:229], v[198:201]
	v_mfma_f32_16x16x32_bf16 v[64:67], v[0:3], v[230:233], v[56:59]
	ds_read_b128 v[0:3], v30 offset:1024
	v_mfma_f32_16x16x32_bf16 v[116:119], v[12:15], v[226:229], v[52:55]
	s_waitcnt lgkmcnt(0)
	v_mfma_f32_16x16x32_bf16 v[60:63], v[0:3], v[160:163], v[202:205]
	v_mfma_f32_16x16x32_bf16 v[56:59], v[0:3], v[8:11], v[206:209]
	v_mfma_f32_16x16x32_bf16 v[52:55], v[0:3], v[226:229], v[210:213]
	v_mfma_f32_16x16x32_bf16 v[48:51], v[0:3], v[230:233], v[214:217]
	ds_read_b128 v[0:3], v31 offset:1024
	v_mfma_f32_16x16x32_bf16 v[120:123], v[12:15], v[8:11], v[36:39]
	s_waitcnt lgkmcnt(0)
	v_mfma_f32_16x16x32_bf16 v[44:47], v[0:3], v[160:163], v[172:175]
	v_mfma_f32_16x16x32_bf16 v[40:43], v[0:3], v[8:11], v[132:135]
	v_mfma_f32_16x16x32_bf16 v[36:39], v[0:3], v[226:229], v[136:139]
	v_mfma_f32_16x16x32_bf16 v[32:35], v[0:3], v[230:233], v[218:221]
	ds_read_b128 v[0:3], v129 offset:1024
	s_waitcnt lgkmcnt(0)
	v_mfma_f32_16x16x32_bf16 v[28:31], v[0:3], v[160:163], v[222:225]
	v_mfma_f32_16x16x32_bf16 v[24:27], v[0:3], v[8:11], v[148:151]
	v_mfma_f32_16x16x32_bf16 v[20:23], v[0:3], v[226:229], v[152:155]
	v_mfma_f32_16x16x32_bf16 v[16:19], v[0:3], v[230:233], v[16:19]
	ds_read_b128 v[0:3], v130 offset:1024
	s_waitcnt lgkmcnt(0)
	v_mfma_f32_16x16x32_bf16 v[12:15], v[0:3], v[160:163], v[4:7]
	v_mfma_f32_16x16x32_bf16 v[8:11], v[0:3], v[8:11], v[140:143]
	v_mfma_f32_16x16x32_bf16 v[4:7], v[0:3], v[226:229], v[144:147]
	v_mfma_f32_16x16x32_bf16 v[0:3], v[0:3], v[230:233], v[156:159]
	s_waitcnt vmcnt(0)
	v_ashrrev_i32_e32 v132, 1, v128
	v_and_b32_e32 v131, 0xffffff80, v132
	v_add_u32_e32 v129, s9, v131
	s_cmp_gt_i32 s8, 63
	s_mov_b64 s[0:1], -1
	s_barrier
	s_cbranch_scc0 .LBB0_943
	v_add_u32_e32 v130, 0xffffc000, v129
	v_ashrrev_i32_e32 v130, 8, v130
	v_and_b32_e32 v164, 0x80, v132
	s_mov_b64 s[0:1], 0
